# GEMM1 first-K-iteration peeled with relaxed vmcnt after epilogue; gla_pre gate weights hoisted; GLA state combine loads batched; bf16 bit-trick packs replaced by v_cvt_pk_bf16_f32
# speedup vs baseline: 1.0031x; 1.0031x over previous
; #define LAS __attribute__((address_space(3)))
; __device__ __forceinline__ void tr_item_regs(const float (&tv)[32], int k0, bf16_t* dst, int ldd, int dst_row0, int dst_col0, LAS float* scr, int lane) {
; #pragma unroll
;     for (int i = 0; i < 32; ++i) scr[(2 * i + (lane >> 5)) * 33 + (lane & 31)] = tv[i];
; __device__ __forceinline__ void phase_prologue(const Params& P, LAS unsigned char* lds) {
;     ...
;     for (int it = gw; it < I_IN; it += 2 * NGW) {
;         const int it1 = it + NGW < I_IN ? it + NGW : it; float t0[32], t1[32];
;         const int kb0 = it >> 8, d0 = it & 255, c0 = win_src_col(d0 >> 3, d0 & 7), kb1 = it1 >> 8, d1 = it1 & 255, c1 = win_src_col(d1 >> 3, d1 & 7);
; #pragma unroll
;         for (int i = 0; i < 32; ++i) t0[i] = P.w_in[(size_t)(64 * kb0 + 2 * i + (lane >> 5)) * NIN + c0 + (lane & 31)];
; #pragma unroll
;         for (int i = 0; i < 32; ++i) t1[i] = P.w_in[(size_t)(64 * kb1 + 2 * i + (lane >> 5)) * NIN + c1 + (lane & 31)];
;         tr_item_regs(t0, 64 * kb0, WinT, 1024, 32 * d0, 0, scr, lane);
;         if (it1 != it) tr_item_regs(t1, 64 * kb1, WinT, 1024, 32 * d1, 0, scr, lane);
.LBB0_92:
	s_or_b64 exec, exec, s[10:11]
	v_ashrrev_i32_e32 v6, 2, v29
	v_and_b32_e32 v8, 0xffffffc0, v6
	v_or_b32_e32 v6, v8, v13
	s_waitcnt vmcnt(32)
	v_lshl_add_u64 v[30:31], v[0:1], 2, v[4:5]
	v_or_b32_e32 v0, 2, v6
	s_waitcnt vmcnt(28)
	v_mad_i64_i32 v[34:35], s[4:5], v0, s34, v[30:31]
	v_or_b32_e32 v0, 4, v6
	v_mad_i64_i32 v[36:37], s[4:5], v0, s34, v[30:31]
	v_or_b32_e32 v0, 6, v6
	s_waitcnt vmcnt(27)
	v_mad_i64_i32 v[38:39], s[4:5], v0, s34, v[30:31]
	v_or_b32_e32 v0, 8, v6
	s_waitcnt vmcnt(25)
	v_mad_i64_i32 v[40:41], s[4:5], v0, s34, v[30:31]
	v_or_b32_e32 v0, 10, v6
	s_waitcnt vmcnt(23)
	v_mad_i64_i32 v[42:43], s[4:5], v0, s34, v[30:31]
	v_or_b32_e32 v0, 12, v6
	v_mad_i64_i32 v[32:33], s[4:5], v6, s34, v[30:31]
	s_waitcnt vmcnt(21)
	v_mad_i64_i32 v[44:45], s[4:5], v0, s34, v[30:31]
	v_or_b32_e32 v0, 14, v6
	v_or_b32_e32 v11, 16, v6
	s_waitcnt vmcnt(20)
	v_mad_i64_i32 v[46:47], s[4:5], v0, s34, v[30:31]
	global_load_dword v0, v[32:33], off
	global_load_dword v9, v[34:35], off
	global_load_dword v48, v[36:37], off
	global_load_dword v49, v[38:39], off
	global_load_dword v50, v[40:41], off
	global_load_dword v51, v[42:43], off
	global_load_dword v52, v[44:45], off
	global_load_dword v53, v[46:47], off
	v_mad_i64_i32 v[32:33], s[4:5], v11, s34, v[30:31]
	v_or_b32_e32 v11, 18, v6
	v_mad_i64_i32 v[34:35], s[4:5], v11, s34, v[30:31]
	v_or_b32_e32 v11, 20, v6
	v_mad_i64_i32 v[36:37], s[4:5], v11, s34, v[30:31]
	v_or_b32_e32 v11, 22, v6
	v_mad_i64_i32 v[38:39], s[4:5], v11, s34, v[30:31]
	v_or_b32_e32 v11, 24, v6
	v_mad_i64_i32 v[40:41], s[4:5], v11, s34, v[30:31]
	v_or_b32_e32 v11, 26, v6
	v_mad_i64_i32 v[42:43], s[4:5], v11, s34, v[30:31]
	v_or_b32_e32 v11, 28, v6
	v_mad_i64_i32 v[44:45], s[4:5], v11, s34, v[30:31]
	v_or_b32_e32 v11, 30, v6
	v_mad_i64_i32 v[46:47], s[4:5], v11, s34, v[30:31]
	v_or_b32_e32 v11, 32, v6
	global_load_dword v54, v[32:33], off
	global_load_dword v55, v[34:35], off
	global_load_dword v56, v[36:37], off
	global_load_dword v57, v[38:39], off
	global_load_dword v58, v[40:41], off
	global_load_dword v59, v[42:43], off
	global_load_dword v62, v[44:45], off
	global_load_dword v63, v[46:47], off
	v_mad_i64_i32 v[32:33], s[4:5], v11, s34, v[30:31]
	v_or_b32_e32 v11, 34, v6
	v_mad_i64_i32 v[34:35], s[4:5], v11, s34, v[30:31]
	v_or_b32_e32 v11, 36, v6
	v_mad_i64_i32 v[36:37], s[4:5], v11, s34, v[30:31]
	v_or_b32_e32 v11, 38, v6
	v_mad_i64_i32 v[38:39], s[4:5], v11, s34, v[30:31]
	v_or_b32_e32 v11, 40, v6
	v_mad_i64_i32 v[40:41], s[4:5], v11, s34, v[30:31]
	v_or_b32_e32 v11, 42, v6
	v_mad_i64_i32 v[42:43], s[4:5], v11, s34, v[30:31]
	v_or_b32_e32 v11, 44, v6
	v_mad_i64_i32 v[44:45], s[4:5], v11, s34, v[30:31]
	v_or_b32_e32 v11, 46, v6
	v_mad_i64_i32 v[46:47], s[4:5], v11, s34, v[30:31]
	v_or_b32_e32 v11, 48, v6
	global_load_dword v65, v[32:33], off
	global_load_dword v67, v[34:35], off
	global_load_dword v68, v[36:37], off
	global_load_dword v69, v[38:39], off
	global_load_dword v70, v[40:41], off
	global_load_dword v71, v[42:43], off
	global_load_dword v72, v[44:45], off
	global_load_dword v73, v[46:47], off
	v_mad_i64_i32 v[32:33], s[4:5], v11, s34, v[30:31]
	v_or_b32_e32 v11, 50, v6
	v_mad_i64_i32 v[34:35], s[4:5], v11, s34, v[30:31]
	v_or_b32_e32 v11, 52, v6
	v_mad_i64_i32 v[36:37], s[4:5], v11, s34, v[30:31]
	v_or_b32_e32 v11, 54, v6
	v_mad_i64_i32 v[38:39], s[4:5], v11, s34, v[30:31]
	v_or_b32_e32 v11, 56, v6
	v_mad_i64_i32 v[40:41], s[4:5], v11, s34, v[30:31]
	v_or_b32_e32 v11, 58, v6
	v_mad_i64_i32 v[42:43], s[4:5], v11, s34, v[30:31]
	v_or_b32_e32 v11, 60, v6
	v_or_b32_e32 v6, 62, v6
	v_mad_i64_i32 v[44:45], s[4:5], v11, s34, v[30:31]
	v_mad_i64_i32 v[30:31], s[4:5], v6, s34, v[30:31]
	global_load_dword v74, v[32:33], off
	global_load_dword v75, v[34:35], off
	global_load_dword v76, v[36:37], off
	global_load_dword v77, v[38:39], off
	global_load_dword v78, v[40:41], off
	global_load_dword v79, v[42:43], off
	global_load_dword v80, v[44:45], off
	global_load_dword v81, v[30:31], off
	v_ashrrev_i32_e32 v6, 2, v7
	v_and_b32_e32 v6, 0xffffffc0, v6
	v_or_b32_e32 v82, v6, v13
	v_mov_b32_e32 v11, v1
	s_waitcnt vmcnt(41)
	v_lshl_add_u64 v[60:61], v[10:11], 2, v[4:5]
	s_waitcnt vmcnt(30)
	ds_write2_b32 v28, v0, v9 offset1:66
	v_or_b32_e32 v0, 10, v82
	v_mad_i64_i32 v[38:39], s[4:5], v0, s34, v[60:61]
	v_or_b32_e32 v0, 12, v82
	v_or_b32_e32 v30, 2, v82
	v_or_b32_e32 v32, 4, v82
	v_or_b32_e32 v34, 6, v82
	v_mad_i64_i32 v[40:41], s[4:5], v0, s34, v[60:61]
	v_or_b32_e32 v0, 14, v82
	v_mad_i64_i32 v[10:11], s[4:5], v82, s34, v[60:61]
	v_mad_i64_i32 v[30:31], s[4:5], v30, s34, v[60:61]
	v_mad_i64_i32 v[32:33], s[4:5], v32, s34, v[60:61]
	v_mad_i64_i32 v[34:35], s[4:5], v34, s34, v[60:61]
	v_or_b32_e32 v36, 8, v82
	s_waitcnt vmcnt(28)
	ds_write2_b32 v28, v48, v49 offset0:132 offset1:198
	v_mad_i64_i32 v[42:43], s[4:5], v0, s34, v[60:61]
	v_or_b32_e32 v0, 16, v82
	v_mad_i64_i32 v[36:37], s[4:5], v36, s34, v[60:61]
	global_load_dword v10, v[10:11], off
	s_nop 0
	global_load_dword v11, v[30:31], off
	s_nop 0
	global_load_dword v30, v[32:33], off
	global_load_dword v31, v[34:35], off
	s_nop 0
	global_load_dword v32, v[36:37], off
	global_load_dword v33, v[38:39], off
	global_load_dword v34, v[40:41], off
	global_load_dword v35, v[42:43], off
	v_mad_i64_i32 v[40:41], s[4:5], v0, s34, v[60:61]
	v_or_b32_e32 v0, 18, v82
	v_mad_i64_i32 v[42:43], s[4:5], v0, s34, v[60:61]
	v_or_b32_e32 v0, 20, v82
	v_mad_i64_i32 v[44:45], s[4:5], v0, s34, v[60:61]
	v_or_b32_e32 v0, 22, v82
	v_mad_i64_i32 v[46:47], s[4:5], v0, s34, v[60:61]
	v_or_b32_e32 v0, 24, v82
	v_add_u32_e32 v36, 0x400, v28
	v_mad_i64_i32 v[48:49], s[4:5], v0, s34, v[60:61]
	v_or_b32_e32 v0, 26, v82
	s_waitcnt vmcnt(34)
; #define LAS __attribute__((address_space(3)))
; __device__ __forceinline__ unsigned pk2(float lo, float hi) { return f2bf(lo) | (f2bf(hi) << 16); }
; __device__ __forceinline__ void tr_item_regs(const float (&tv)[32], int k0, bf16_t* dst, int ldd, int dst_row0, int dst_col0, LAS float* scr, int lane) {
; #pragma unroll
;     for (int i = 0; i < 32; ++i) scr[(2 * i + (lane >> 5)) * 33 + (lane & 31)] = tv[i];
;     asm volatile("s_waitcnt lgkmcnt(0)" ::: "memory");
;     const int c = lane & 7;
; #pragma unroll
;     for (int j = 0; j < 4; ++j) { const int n = (lane >> 3) + 8 * j; const LAS float* s = scr + (8 * c) * 33 + n;
;         u32x4 o; o.x = pk2(s[0 * 33], s[1 * 33]); o.y = pk2(s[2 * 33], s[3 * 33]); o.z = pk2(s[4 * 33], s[5 * 33]); o.w = pk2(s[6 * 33], s[7 * 33]);
;         *(u32x4*)(dst + (size_t)(dst_row0 + n) * ldd + dst_col0 + k0 + 8 * c) = o; }
;     asm volatile("s_waitcnt lgkmcnt(0)" ::: "memory");
; __device__ __forceinline__ void phase_prologue(const Params& P, LAS unsigned char* lds) {
;     ...
;         for (int i = 0; i < 32; ++i) t1[i] = P.w_in[(size_t)(64 * kb1 + 2 * i + (lane >> 5)) * NIN + c1 + (lane & 31)];
	ds_write2_b32 v36, v50, v51 offset0:8 offset1:74
	v_mad_i64_i32 v[50:51], s[4:5], v0, s34, v[60:61]
	v_or_b32_e32 v0, 28, v82
	s_waitcnt vmcnt(32)
	ds_write2_b32 v36, v52, v53 offset0:140 offset1:206
	v_add_u32_e32 v37, 0x800, v28
	v_add_u32_e32 v38, 0xc00, v28
	v_mad_i64_i32 v[52:53], s[4:5], v0, s34, v[60:61]
	v_or_b32_e32 v0, 30, v82
	s_waitcnt vmcnt(30)
	ds_write2_b32 v37, v54, v55 offset0:16 offset1:82
	s_waitcnt vmcnt(28)
	ds_write2_b32 v37, v56, v57 offset0:148 offset1:214
	s_waitcnt vmcnt(26)
	ds_write2_b32 v38, v58, v59 offset0:24 offset1:90
	v_mad_i64_i32 v[54:55], s[4:5], v0, s34, v[60:61]
	v_or_b32_e32 v0, 32, v82
	global_load_dword v39, v[40:41], off
	s_nop 0
	global_load_dword v40, v[42:43], off
	global_load_dword v41, v[44:45], off
	s_nop 0
	global_load_dword v42, v[46:47], off
	global_load_dword v43, v[48:49], off
	global_load_dword v44, v[50:51], off
	global_load_dword v45, v[52:53], off
	s_nop 0
	global_load_dword v46, v[54:55], off
	v_mad_i64_i32 v[50:51], s[4:5], v0, s34, v[60:61]
	v_or_b32_e32 v0, 34, v82
	v_mad_i64_i32 v[52:53], s[4:5], v0, s34, v[60:61]
	v_or_b32_e32 v0, 36, v82
	v_mad_i64_i32 v[54:55], s[4:5], v0, s34, v[60:61]
	v_or_b32_e32 v0, 38, v82
	v_mad_i64_i32 v[56:57], s[4:5], v0, s34, v[60:61]
	v_or_b32_e32 v0, 40, v82
	v_mad_i64_i32 v[58:59], s[4:5], v0, s34, v[60:61]
	v_or_b32_e32 v0, 42, v82
	s_waitcnt vmcnt(32)
	ds_write2_b32 v38, v62, v63 offset0:156 offset1:222
	v_add_u32_e32 v47, 0x1000, v28
	v_add_u32_e32 v48, 0x1400, v28
	v_mad_i64_i32 v[62:63], s[4:5], v0, s34, v[60:61]
	v_or_b32_e32 v0, 44, v82
	v_add_u32_e32 v49, 0x1800, v28
	s_waitcnt vmcnt(30)
	ds_write2_b32 v47, v65, v67 offset0:32 offset1:98
	s_waitcnt vmcnt(28)
	ds_write2_b32 v47, v68, v69 offset0:164 offset1:230
	s_waitcnt vmcnt(26)
	ds_write2_b32 v48, v70, v71 offset0:40 offset1:106
	s_waitcnt vmcnt(24)
	ds_write2_b32 v48, v72, v73 offset0:172 offset1:238
	v_mad_i64_i32 v[68:69], s[4:5], v0, s34, v[60:61]
	s_waitcnt vmcnt(22)
	ds_write2_b32 v49, v74, v75 offset0:48 offset1:114
	v_or_b32_e32 v0, 46, v82
	v_mad_i64_i32 v[70:71], s[4:5], v0, s34, v[60:61]
	global_load_dword v50, v[50:51], off
	s_nop 0
	global_load_dword v51, v[52:53], off
	s_nop 0
	global_load_dword v52, v[54:55], off
	global_load_dword v53, v[56:57], off
	s_nop 0
	global_load_dword v54, v[58:59], off
	global_load_dword v55, v[62:63], off
	global_load_dword v56, v[68:69], off
	global_load_dword v57, v[70:71], off
	v_or_b32_e32 v0, 48, v82
	v_or_b32_e32 v9, 50, v82
	v_add_u32_e32 v58, 0x1c00, v28
	s_waitcnt vmcnt(28)
	ds_write2_b32 v49, v76, v77 offset0:180 offset1:246
	s_waitcnt vmcnt(26)
	ds_write2_b32 v58, v78, v79 offset0:56 offset1:122
	v_or_b32_e32 v59, 52, v82
	v_or_b32_e32 v65, 54, v82
	s_waitcnt vmcnt(24)
	ds_write2_b32 v58, v80, v81 offset0:188 offset1:254
	v_or_b32_e32 v67, 56, v82
	v_or_b32_e32 v76, 58, v82
	v_or_b32_e32 v78, 60, v82
	v_or_b32_e32 v80, 62, v82
	v_mad_i64_i32 v[62:63], s[4:5], v0, s34, v[60:61]
	v_mad_i64_i32 v[68:69], s[4:5], v9, s34, v[60:61]
	v_mad_i64_i32 v[70:71], s[4:5], v59, s34, v[60:61]
	v_mad_i64_i32 v[72:73], s[4:5], v65, s34, v[60:61]
	v_mad_i64_i32 v[74:75], s[4:5], v67, s34, v[60:61]
	v_mad_i64_i32 v[76:77], s[4:5], v76, s34, v[60:61]
	v_mad_i64_i32 v[78:79], s[4:5], v78, s34, v[60:61]
	v_mad_i64_i32 v[80:81], s[4:5], v80, s34, v[60:61]
	global_load_dword v59, v[62:63], off
	global_load_dword v60, v[68:69], off
	global_load_dword v61, v[70:71], off
	s_nop 0
	global_load_dword v62, v[72:73], off
	global_load_dword v63, v[74:75], off
	global_load_dword v65, v[76:77], off
	global_load_dword v67, v[78:79], off
	global_load_dword v68, v[80:81], off
	s_waitcnt lgkmcnt(0)
	ds_read2_b32 v[74:75], v15 offset1:8
	ds_read2_b32 v[76:77], v15 offset0:33 offset1:41
	ds_read2_b32 v[80:81], v15 offset0:99 offset1:107
	ds_read2_b32 v[82:83], v15 offset0:132 offset1:140
	ds_read2_b32 v[84:85], v15 offset0:165 offset1:173
	s_waitcnt lgkmcnt(4)
	ds_read2_b32 v[78:79], v15 offset0:66 offset1:74
	s_waitcnt lgkmcnt(4)
	ds_read2_b32 v[86:87], v15 offset0:198 offset1:206
	s_waitcnt lgkmcnt(4)
	ds_read2_b32 v[88:89], v15 offset0:231 offset1:239
	v_cvt_pk_bf16_f32 v70, v74, v76
	s_waitcnt lgkmcnt(4)
	s_waitcnt lgkmcnt(3)
	s_waitcnt lgkmcnt(2)
	v_cvt_pk_bf16_f32 v72, v82, v84
	s_waitcnt lgkmcnt(1)
	s_waitcnt lgkmcnt(0)
	v_cvt_pk_bf16_f32 v71, v78, v80
	v_lshlrev_b32_sdwa v69, v27, v29 dst_sel:DWORD dst_unused:UNUSED_PAD src0_sel:DWORD src1_sel:BYTE_0
	v_cvt_pk_bf16_f32 v73, v86, v88
	v_or_b32_e32 v0, v69, v14
	v_ashrrev_i32_e32 v9, 31, v8
	v_lshlrev_b32_e32 v0, 11, v0
	v_lshl_add_u64 v[8:9], v[8:9], 1, v[2:3]
	v_lshl_add_u64 v[90:91], v[8:9], 0, v[0:1]
	global_store_dwordx4 v[90:91], v[70:73], off
	s_nop 1
	v_cvt_pk_bf16_f32 v70, v75, v77
	s_nop 0
	v_cvt_pk_bf16_f32 v71, v79, v81
	v_cvt_pk_bf16_f32 v72, v83, v85
	v_cvt_pk_bf16_f32 v73, v87, v89
	v_or_b32_e32 v0, v69, v18
	v_lshlrev_b32_e32 v0, 11, v0
	ds_read2_b32 v[74:75], v15 offset0:16 offset1:24
	v_lshl_add_u64 v[76:77], v[8:9], 0, v[0:1]
	global_store_dwordx4 v[76:77], v[70:73], off
	ds_read2_b32 v[76:77], v15 offset0:49 offset1:57
	ds_read2_b32 v[78:79], v15 offset0:82 offset1:90
	ds_read2_b32 v[80:81], v15 offset0:115 offset1:123
	ds_read2_b32 v[82:83], v15 offset0:148 offset1:156
	ds_read2_b32 v[84:85], v15 offset0:181 offset1:189
	s_waitcnt lgkmcnt(5)
	s_waitcnt lgkmcnt(4)
	s_waitcnt lgkmcnt(3)
	ds_read2_b32 v[86:87], v15 offset0:214 offset1:222
	s_waitcnt lgkmcnt(3)
	ds_read2_b32 v[88:89], v15 offset0:247 offset1:255
	v_cvt_pk_bf16_f32 v70, v74, v76
	s_waitcnt lgkmcnt(3)
	v_cvt_pk_bf16_f32 v71, v78, v80
	s_waitcnt lgkmcnt(2)
	v_cvt_pk_bf16_f32 v72, v82, v84
	s_waitcnt lgkmcnt(1)
	s_waitcnt lgkmcnt(0)
	v_cvt_pk_bf16_f32 v73, v86, v88
	v_or_b32_e32 v0, v69, v19
	v_lshlrev_b32_e32 v0, 11, v0
	v_lshl_add_u64 v[90:91], v[8:9], 0, v[0:1]
	global_store_dwordx4 v[90:91], v[70:73], off
	s_nop 1
	v_cvt_pk_bf16_f32 v70, v75, v77
	s_nop 0
	v_cvt_pk_bf16_f32 v71, v79, v81
	v_cvt_pk_bf16_f32 v72, v83, v85
	v_cvt_pk_bf16_f32 v73, v87, v89
	v_or_b32_e32 v0, v69, v20
	v_lshlrev_b32_e32 v0, 11, v0
	v_lshl_add_u64 v[8:9], v[8:9], 0, v[0:1]
	global_store_dwordx4 v[8:9], v[70:73], off
	s_waitcnt lgkmcnt(0)
	v_cmp_ne_u32_e64 s[4:5], v29, v7
	s_and_saveexec_b64 s[10:11], s[4:5]
	s_cbranch_execz .LBB0_27
; #define LAS __attribute__((address_space(3)))
; __device__ __forceinline__ unsigned pk2(float lo, float hi) { return f2bf(lo) | (f2bf(hi) << 16); }
; __device__ __forceinline__ void tr_item_regs(const float (&tv)[32], int k0, bf16_t* dst, int ldd, int dst_row0, int dst_col0, LAS float* scr, int lane) {
; #pragma unroll
;     for (int i = 0; i < 32; ++i) scr[(2 * i + (lane >> 5)) * 33 + (lane & 31)] = tv[i];
;     asm volatile("s_waitcnt lgkmcnt(0)" ::: "memory");
;     const int c = lane & 7;
; #pragma unroll
;     for (int j = 0; j < 4; ++j) { const int n = (lane >> 3) + 8 * j; const LAS float* s = scr + (8 * c) * 33 + n;
;         u32x4 o; o.x = pk2(s[0 * 33], s[1 * 33]); o.y = pk2(s[2 * 33], s[3 * 33]); o.z = pk2(s[4 * 33], s[5 * 33]); o.w = pk2(s[6 * 33], s[7 * 33]);
;         *(u32x4*)(dst + (size_t)(dst_row0 + n) * ldd + dst_col0 + k0 + 8 * c) = o; }
;     asm volatile("s_waitcnt lgkmcnt(0)" ::: "memory");
	s_waitcnt vmcnt(34)
	ds_write2_b32 v28, v10, v11 offset1:66
	s_waitcnt vmcnt(32)
	ds_write2_b32 v28, v30, v31 offset0:132 offset1:198
	s_waitcnt vmcnt(30)
	ds_write2_b32 v36, v32, v33 offset0:8 offset1:74
	s_waitcnt vmcnt(28)
	ds_write2_b32 v36, v34, v35 offset0:140 offset1:206
	s_waitcnt vmcnt(26)
	ds_write2_b32 v37, v39, v40 offset0:16 offset1:82
	s_waitcnt vmcnt(24)
	ds_write2_b32 v37, v41, v42 offset0:148 offset1:214
	s_waitcnt vmcnt(22)
	ds_write2_b32 v38, v43, v44 offset0:24 offset1:90
	s_waitcnt vmcnt(20)
	ds_write2_b32 v38, v45, v46 offset0:156 offset1:222
	s_waitcnt vmcnt(18)
	ds_write2_b32 v47, v50, v51 offset0:32 offset1:98
	s_waitcnt vmcnt(16)
	ds_write2_b32 v47, v52, v53 offset0:164 offset1:230
	s_waitcnt vmcnt(14)
	ds_write2_b32 v48, v54, v55 offset0:40 offset1:106
	s_waitcnt vmcnt(12)
	ds_write2_b32 v48, v56, v57 offset0:172 offset1:238
	s_waitcnt vmcnt(10)
	ds_write2_b32 v49, v59, v60 offset0:48 offset1:114
	s_waitcnt vmcnt(8)
	ds_write2_b32 v49, v61, v62 offset0:180 offset1:246
	s_waitcnt vmcnt(6)
	ds_write2_b32 v58, v63, v65 offset0:56 offset1:122
	s_waitcnt vmcnt(4)
	ds_write2_b32 v58, v67, v68 offset0:188 offset1:254
	s_waitcnt lgkmcnt(0)
	ds_read2_b32 v[10:11], v15 offset1:8
	ds_read2_b32 v[32:33], v15 offset0:33 offset1:41
	ds_read2_b32 v[34:35], v15 offset0:66 offset1:74
	ds_read2_b32 v[36:37], v15 offset0:99 offset1:107
	v_lshlrev_b32_sdwa v48, v27, v7 dst_sel:DWORD dst_unused:UNUSED_PAD src0_sel:DWORD src1_sel:BYTE_0
	v_ashrrev_i32_e32 v7, 31, v6
	s_waitcnt lgkmcnt(3)
	v_lshl_add_u64 v[30:31], v[6:7], 1, v[2:3]
	s_waitcnt lgkmcnt(2)
	ds_read2_b32 v[38:39], v15 offset0:132 offset1:140
	ds_read2_b32 v[40:41], v15 offset0:165 offset1:173
	v_cvt_pk_bf16_f32 v6, v10, v32
	s_waitcnt lgkmcnt(3)
	s_waitcnt lgkmcnt(2)
	ds_read2_b32 v[42:43], v15 offset0:198 offset1:206
	ds_read2_b32 v[44:45], v15 offset0:231 offset1:239
	v_cvt_pk_bf16_f32 v7, v34, v36
	s_waitcnt lgkmcnt(3)
	s_waitcnt lgkmcnt(2)
	v_cvt_pk_bf16_f32 v8, v38, v40
	s_waitcnt lgkmcnt(1)
	s_waitcnt lgkmcnt(0)
	v_cvt_pk_bf16_f32 v9, v42, v44
	v_or_b32_e32 v0, v48, v14
	v_lshlrev_b32_e32 v0, 11, v0
	v_lshl_add_u64 v[46:47], v[30:31], 0, v[0:1]
	global_store_dwordx4 v[46:47], v[6:9], off
	s_nop 1
	v_cvt_pk_bf16_f32 v6, v11, v33
	s_nop 0
	v_cvt_pk_bf16_f32 v7, v35, v37
	v_cvt_pk_bf16_f32 v8, v39, v41
	v_cvt_pk_bf16_f32 v9, v43, v45
	v_or_b32_e32 v0, v48, v18
	v_lshlrev_b32_e32 v0, 11, v0
	ds_read2_b32 v[10:11], v15 offset0:16 offset1:24
	v_lshl_add_u64 v[32:33], v[30:31], 0, v[0:1]
	global_store_dwordx4 v[32:33], v[6:9], off
	ds_read2_b32 v[32:33], v15 offset0:49 offset1:57
	ds_read2_b32 v[34:35], v15 offset0:82 offset1:90
	ds_read2_b32 v[36:37], v15 offset0:115 offset1:123
	s_waitcnt lgkmcnt(3)
	s_waitcnt lgkmcnt(2)
	ds_read2_b32 v[38:39], v15 offset0:148 offset1:156
	ds_read2_b32 v[40:41], v15 offset0:181 offset1:189
	v_cvt_pk_bf16_f32 v6, v10, v32
	s_waitcnt lgkmcnt(3)
	s_waitcnt lgkmcnt(2)
	ds_read2_b32 v[42:43], v15 offset0:214 offset1:222
	ds_read2_b32 v[44:45], v15 offset0:247 offset1:255
	v_cvt_pk_bf16_f32 v7, v34, v36
	s_waitcnt lgkmcnt(3)
	s_waitcnt lgkmcnt(2)
	v_cvt_pk_bf16_f32 v8, v38, v40
	s_waitcnt lgkmcnt(1)
	s_waitcnt lgkmcnt(0)
	v_cvt_pk_bf16_f32 v9, v42, v44
	v_or_b32_e32 v0, v48, v19
	v_lshlrev_b32_e32 v0, 11, v0
	v_lshl_add_u64 v[46:47], v[30:31], 0, v[0:1]
	global_store_dwordx4 v[46:47], v[6:9], off
	s_nop 1
	v_cvt_pk_bf16_f32 v6, v11, v33
	s_nop 0
	v_cvt_pk_bf16_f32 v7, v35, v37
	v_cvt_pk_bf16_f32 v8, v39, v41
	v_cvt_pk_bf16_f32 v9, v43, v45
	v_or_b32_e32 v0, v48, v20
	v_lshlrev_b32_e32 v0, 11, v0
	v_lshl_add_u64 v[10:11], v[30:31], 0, v[0:1]
	global_store_dwordx4 v[10:11], v[6:9], off
	s_waitcnt lgkmcnt(0)
	s_branch .LBB0_27

; __device__ __forceinline__ unsigned pk2(float lo, float hi) { return f2bf(lo) | (f2bf(hi) << 16); }
; __device__ __forceinline__ void phase_prologue(const Params& P, LAS unsigned char* lds) {
;     ...
;     for (int m0 = gw; m0 < NTOK; m0 += RP * NGW) {
;         f32x4 v[RP][4];
; #pragma unroll
;         for (int q = 0; q < RP; ++q) {
;             const f32x4* xr = (const f32x4*)(P.x + (size_t)(m0 + q * NGW) * DM) + lane;
; #pragma unroll
;             for (int j = 0; j < 4; ++j) v[q][j] = __builtin_nontemporal_load(xr + 64 * j);
;         }
; #pragma unroll
;         for (int q = 0; q < RP; ++q) {
;             float ss = 0.f;
; #pragma unroll
;             for (int j = 0; j < 4; ++j) ss += (v[q][j][0] * v[q][j][0] + v[q][j][1] * v[q][j][1]) + (v[q][j][2] * v[q][j][2] + v[q][j][3] * v[q][j][3]);
;             const float rstd = 1.0f / sqrtf(wave_sum(ss) * (1.0f / DM) + RMS_EPS);
;             unsigned long long* o8 = (unsigned long long*)(HB + (size_t)(m0 + q * NGW) * DM) + lane;
; #pragma unroll
;             for (int j = 0; j < 4; ++j) { v[q][j] = v[q][j] * rstd * ng[j]; o8[64 * j] = (unsigned long long)pk2(v[q][j][0], v[q][j][1]) | ((unsigned long long)pk2(v[q][j][2], v[q][j][3]) << 32); }
.LBB0_100:
	v_lshl_add_u64 v[28:29], v[78:79], 0, v[68:69]
	global_load_dwordx4 v[24:27], v[28:29], off nt
	global_load_dwordx4 v[20:23], v[28:29], off offset:1024 nt
	s_waitcnt lgkmcnt(0)
	global_load_dwordx4 v[16:19], v[28:29], off offset:3072 nt
	s_nop 0
	global_load_dwordx4 v[28:31], v[28:29], off offset:2048 nt
	v_lshl_add_u64 v[36:37], v[84:85], 0, v[68:69]
	global_load_dwordx4 v[44:47], v[36:37], off nt
	global_load_dwordx4 v[40:43], v[36:37], off offset:1024 nt
	global_load_dwordx4 v[32:35], v[36:37], off offset:3072 nt
	s_nop 0
	global_load_dwordx4 v[36:39], v[36:37], off offset:2048 nt
	v_add_u32_e32 v92, s1, v64
	v_ashrrev_i32_e32 v93, 31, v92
	v_lshl_add_u64 v[110:111], v[82:83], 0, v[66:67]
	s_waitcnt vmcnt(7)
	v_pk_mul_f32 v[48:49], v[26:27], v[26:27]
	v_pk_mul_f32 v[50:51], v[24:25], v[24:25]
	s_waitcnt vmcnt(6)
	v_pk_mul_f32 v[52:53], v[22:23], v[22:23]
	v_pk_mul_f32 v[54:55], v[20:21], v[20:21]
	v_pk_mov_b32 v[60:61], v[50:51], v[48:49] op_sel:[1,0]
	v_mov_b32_e32 v51, v49
	v_pk_mov_b32 v[48:49], v[54:55], v[52:53] op_sel:[1,0]
	v_mov_b32_e32 v55, v53
	s_waitcnt vmcnt(5)
	v_mul_f32_e32 v59, v16, v16
	s_waitcnt vmcnt(4)
	v_mul_f32_e32 v56, v29, v29
	v_mul_f32_e32 v58, v31, v31
	v_pk_add_f32 v[50:51], v[60:61], v[50:51]
	v_pk_add_f32 v[48:49], v[48:49], v[54:55]
	v_mul_f32_e32 v62, v17, v17
	v_mul_f32_e32 v63, v18, v18
	v_mul_f32_e32 v90, v19, v19
	v_pk_fma_f32 v[52:53], v[28:29], v[28:29], v[56:57] op_sel_hi:[1,1,0]
	v_pk_fma_f32 v[56:57], v[30:31], v[30:31], v[58:59] op_sel_hi:[1,1,0]
	v_pk_add_f32 v[50:51], v[50:51], v[50:51] op_sel:[0,1] op_sel_hi:[1,0]
	v_pk_add_f32 v[48:49], v[48:49], v[48:49] op_sel:[0,1] op_sel_hi:[1,0]
	v_mov_b32_e32 v53, v63
	v_mov_b32_e32 v57, v90
	v_mov_b32_e32 v51, v59
	v_mov_b32_e32 v49, v62
	v_pk_add_f32 v[52:53], v[52:53], v[56:57]
	v_pk_add_f32 v[48:49], v[50:51], v[48:49]
	s_waitcnt vmcnt(3)
	v_pk_mul_f32 v[50:51], v[46:47], v[46:47]
	v_pk_add_f32 v[48:49], v[48:49], v[52:53]
	v_pk_mul_f32 v[52:53], v[44:45], v[44:45]
	v_add_f32_e32 v48, v48, v49
	ds_bpermute_b32 v49, v112, v48
	s_waitcnt vmcnt(2)
	v_pk_mul_f32 v[54:55], v[42:43], v[42:43]
	s_waitcnt vmcnt(1)
	v_mul_f32_e32 v61, v32, v32
	s_waitcnt vmcnt(0)
	v_mul_f32_e32 v58, v37, v37
	v_pk_mov_b32 v[62:63], v[52:53], v[50:51] op_sel:[1,0]
	s_waitcnt lgkmcnt(0)
	v_add_f32_e32 v56, v48, v49
	ds_bpermute_b32 v57, v113, v56
	v_mov_b32_e32 v53, v51
	v_pk_add_f32 v[52:53], v[62:63], v[52:53]
	v_mul_f32_e32 v94, v33, v33
	v_pk_add_f32 v[52:53], v[52:53], v[52:53] op_sel:[0,1] op_sel_hi:[1,0]
	s_waitcnt lgkmcnt(0)
	v_add_f32_e32 v59, v56, v57
	ds_bpermute_b32 v60, v114, v59
	v_pk_mul_f32 v[56:57], v[40:41], v[40:41]
	v_mul_f32_e32 v96, v34, v34
	v_pk_mov_b32 v[50:51], v[56:57], v[54:55] op_sel:[1,0]
	v_mov_b32_e32 v57, v55
	s_waitcnt lgkmcnt(0)
	v_add_f32_e32 v59, v59, v60
	ds_bpermute_b32 v95, v115, v59
	v_mul_f32_e32 v60, v39, v39
	v_pk_fma_f32 v[54:55], v[36:37], v[36:37], v[58:59] op_sel_hi:[1,1,0]
	v_pk_add_f32 v[50:51], v[50:51], v[56:57]
	v_mov_b32_e32 v55, v96
	s_waitcnt lgkmcnt(0)
	v_add_f32_e32 v95, v59, v95
	ds_bpermute_b32 v97, v116, v95
	v_pk_fma_f32 v[58:59], v[38:39], v[38:39], v[60:61] op_sel_hi:[1,1,0]
	v_pk_add_f32 v[50:51], v[50:51], v[50:51] op_sel:[0,1] op_sel_hi:[1,0]
	v_lshlrev_b64 v[48:49], 12, v[92:93]
	v_mov_b32_e32 v51, v94
	s_waitcnt lgkmcnt(0)
	v_add_f32_e32 v59, v95, v97
	ds_bpermute_b32 v60, v117, v59
	v_add_u32_e32 v90, s3, v64
	v_ashrrev_i32_e32 v91, 31, v90
	s_waitcnt lgkmcnt(0)
	v_add_f32_e32 v53, v59, v60
	v_fmamk_f32 v53, v53, 0x3a800000, v65
	v_mul_f32_e32 v56, 0x4f800000, v53
	v_cmp_gt_f32_e32 vcc, s16, v53
	s_nop 1
	v_cndmask_b32_e32 v56, v53, v56, vcc
	v_sqrt_f32_e32 v57, v56
	v_mov_b32_e32 v53, v61
	v_pk_add_f32 v[50:51], v[52:53], v[50:51]
	v_add_u32_e32 v59, -1, v57
	v_add_u32_e32 v60, 1, v57
	v_fma_f32 v61, -v59, v57, v56
	v_fma_f32 v62, -v60, v57, v56
	v_cmp_ge_f32_e64 s[14:15], 0, v61
	s_nop 1
	v_cndmask_b32_e64 v57, v57, v59, s[14:15]
	v_cmp_lt_f32_e64 s[14:15], 0, v62
	s_nop 1
	v_cndmask_b32_e64 v57, v57, v60, s[14:15]
	v_mul_f32_e32 v59, 0x37800000, v57
	v_cndmask_b32_e32 v57, v57, v59, vcc
	v_cmp_class_f32_e32 vcc, v56, v119
	s_nop 1
	v_cndmask_b32_e32 v56, v57, v56, vcc
	v_div_scale_f32 v57, s[14:15], v56, v56, 1.0
	v_rcp_f32_e32 v59, v57
	v_div_scale_f32 v52, vcc, 1.0, v56, 1.0
	v_fma_f32 v53, -v57, v59, 1.0
	v_fmac_f32_e32 v59, v53, v59
	v_mul_f32_e32 v53, v52, v59
	v_fma_f32 v60, -v57, v53, v52
	v_fmac_f32_e32 v53, v60, v59
	v_fma_f32 v52, -v57, v53, v52
	v_div_fmas_f32 v52, v52, v59, v53
	v_div_fixup_f32 v52, v52, v56, 1.0
	v_pk_mul_f32 v[24:25], v[24:25], v[52:53] op_sel_hi:[1,0]
	v_pk_mul_f32 v[20:21], v[20:21], v[52:53] op_sel_hi:[1,0]
	v_pk_mul_f32 v[108:109], v[0:1], v[24:25]
	v_pk_mul_f32 v[100:101], v[16:17], v[52:53] op_sel_hi:[1,0]
	v_pk_mul_f32 v[104:105], v[4:5], v[20:21]
	v_mul_f32_e32 v59, v35, v35
	v_cvt_pk_bf16_f32 v120, v108, v109
	v_pk_add_f32 v[16:17], v[54:55], v[58:59]
	v_pk_mul_f32 v[26:27], v[26:27], v[52:53] op_sel_hi:[1,0]
	v_pk_add_f32 v[16:17], v[50:51], v[16:17]
	v_pk_mul_f32 v[106:107], v[2:3], v[26:27]
	v_cvt_pk_bf16_f32 v122, v104, v105
	v_add_f32_e32 v20, v16, v17
	v_pk_mul_f32 v[98:99], v[18:19], v[52:53] op_sel_hi:[1,0]
	ds_bpermute_b32 v21, v112, v20
	v_cvt_pk_bf16_f32 v121, v106, v107
	v_lshl_add_u64 v[18:19], v[74:75], 0, v[48:49]
	v_pk_mul_f32 v[22:23], v[22:23], v[52:53] op_sel_hi:[1,0]
	v_pk_mul_f32 v[28:29], v[28:29], v[52:53] op_sel_hi:[1,0]
	v_pk_mul_f32 v[30:31], v[30:31], v[52:53] op_sel_hi:[1,0]
	global_load_dwordx4 v[60:63], v[18:19], off nt
	global_load_dwordx4 v[56:59], v[18:19], off offset:1024 nt
	global_load_dwordx4 v[52:55], v[18:19], off offset:2048 nt
	global_load_dwordx4 v[48:51], v[18:19], off offset:3072 nt
	s_waitcnt lgkmcnt(0)
; __device__ __forceinline__ unsigned pk2(float lo, float hi) { return f2bf(lo) | (f2bf(hi) << 16); }
; __device__ __forceinline__ void phase_prologue(const Params& P, LAS unsigned char* lds) {
;     ...
;         for (int q = 0; q < RP; ++q) {
;             float ss = 0.f;
; #pragma unroll
;             for (int j = 0; j < 4; ++j) ss += (v[q][j][0] * v[q][j][0] + v[q][j][1] * v[q][j][1]) + (v[q][j][2] * v[q][j][2] + v[q][j][3] * v[q][j][3]);
;             const float rstd = 1.0f / sqrtf(wave_sum(ss) * (1.0f / DM) + RMS_EPS);
;             unsigned long long* o8 = (unsigned long long*)(HB + (size_t)(m0 + q * NGW) * DM) + lane;
; #pragma unroll
;             for (int j = 0; j < 4; ++j) { v[q][j] = v[q][j] * rstd * ng[j]; o8[64 * j] = (unsigned long long)pk2(v[q][j][0], v[q][j][1]) | ((unsigned long long)pk2(v[q][j][2], v[q][j][3]) << 32); }
;         }
	v_add_f32_e32 v20, v20, v21
	ds_bpermute_b32 v21, v113, v20
	v_pk_mul_f32 v[102:103], v[6:7], v[22:23]
	v_pk_mul_f32 v[94:95], v[10:11], v[30:31]
	v_pk_mul_f32 v[96:97], v[8:9], v[28:29]
	s_waitcnt lgkmcnt(0)
	v_add_f32_e32 v126, v20, v21
	ds_bpermute_b32 v127, v114, v126
	s_waitcnt lgkmcnt(0)
	v_add_f32_e32 v126, v126, v127
	ds_bpermute_b32 v127, v115, v126
	v_lshlrev_b64 v[16:17], 12, v[90:91]
	v_lshl_add_u64 v[16:17], v[74:75], 0, v[16:17]
	v_cvt_pk_bf16_f32 v123, v102, v103
	v_cvt_pk_bf16_f32 v124, v96, v97
	v_cvt_pk_bf16_f32 v125, v94, v95
	global_load_dwordx4 v[28:31], v[16:17], off nt
	global_load_dwordx4 v[24:27], v[16:17], off offset:1024 nt
	global_load_dwordx4 v[20:23], v[16:17], off offset:2048 nt
	s_nop 0
	global_load_dwordx4 v[16:19], v[16:17], off offset:3072 nt
	s_nop 0
	global_store_dwordx2 v[110:111], v[120:121], off
	global_store_dwordx2 v[110:111], v[122:123], off offset:512
	global_store_dwordx2 v[110:111], v[124:125], off offset:1024
	s_waitcnt lgkmcnt(0)
	v_add_f32_e32 v120, v126, v127
	ds_bpermute_b32 v121, v116, v120
	v_pk_mul_f32 v[100:101], v[12:13], v[100:101]
	v_pk_mul_f32 v[98:99], v[14:15], v[98:99]
	s_waitcnt lgkmcnt(0)
	v_add_f32_e32 v121, v120, v121
	ds_bpermute_b32 v124, v117, v121
	v_cvt_pk_bf16_f32 v120, v100, v101
	s_waitcnt lgkmcnt(0)
	v_add_f32_e32 v121, v121, v124
	v_fmamk_f32 v121, v121, 0x3a800000, v65
	v_mul_f32_e32 v123, 0x4f800000, v121
	v_cmp_gt_f32_e32 vcc, s16, v121
	s_nop 1
	v_cndmask_b32_e32 v121, v121, v123, vcc
	v_sqrt_f32_e32 v123, v121
	s_nop 0
	v_add_u32_e32 v125, -1, v123
	v_fma_f32 v126, -v125, v123, v121
	v_cmp_ge_f32_e64 s[14:15], 0, v126
	v_add_u32_e32 v126, 1, v123
	s_nop 0
	v_cndmask_b32_e64 v125, v123, v125, s[14:15]
	v_fma_f32 v123, -v126, v123, v121
	v_cmp_lt_f32_e64 s[14:15], 0, v123
	s_nop 1
	v_cndmask_b32_e64 v123, v125, v126, s[14:15]
	v_mul_f32_e32 v125, 0x37800000, v123
	v_cndmask_b32_e32 v123, v123, v125, vcc
	v_cmp_class_f32_e32 vcc, v121, v119
	s_nop 1
	v_cndmask_b32_e32 v123, v123, v121, vcc
	v_div_scale_f32 v125, s[14:15], v123, v123, 1.0
	v_rcp_f32_e32 v126, v125
	v_cvt_pk_bf16_f32 v121, v98, v99
	global_store_dwordx2 v[110:111], v[120:121], off offset:1536
	v_fma_f32 v110, -v125, v126, 1.0
	v_fmac_f32_e32 v126, v110, v126
	v_div_scale_f32 v110, vcc, 1.0, v123, 1.0
	v_mul_f32_e32 v111, v110, v126
	v_fma_f32 v120, -v125, v111, v110
	v_fmac_f32_e32 v111, v120, v126
	v_fma_f32 v110, -v125, v111, v110
	v_div_fmas_f32 v110, v110, v126, v111
	v_div_fixup_f32 v110, v110, v123, 1.0
	v_pk_mul_f32 v[44:45], v[44:45], v[110:111] op_sel_hi:[1,0]
	v_pk_mul_f32 v[122:123], v[38:39], v[110:111] op_sel_hi:[1,0]
	v_pk_mul_f32 v[38:39], v[0:1], v[44:45]
	v_pk_mul_f32 v[124:125], v[32:33], v[110:111] op_sel_hi:[1,0]
	v_pk_mul_f32 v[46:47], v[46:47], v[110:111] op_sel_hi:[1,0]
	v_pk_mul_f32 v[120:121], v[36:37], v[110:111] op_sel_hi:[1,0]
	v_pk_mul_f32 v[36:37], v[2:3], v[46:47]
	v_cvt_pk_bf16_f32 v32, v38, v39
	v_pk_mul_f32 v[40:41], v[40:41], v[110:111] op_sel_hi:[1,0]
	v_pk_mul_f32 v[42:43], v[42:43], v[110:111] op_sel_hi:[1,0]
	v_pk_mul_f32 v[110:111], v[34:35], v[110:111] op_sel_hi:[1,0]
	v_cvt_pk_bf16_f32 v33, v36, v37
	v_pk_mul_f32 v[34:35], v[4:5], v[40:41]
	v_lshl_add_u64 v[126:127], v[80:81], 0, v[66:67]
	global_store_dwordx2 v[126:127], v[32:33], off
	v_pk_mul_f32 v[32:33], v[6:7], v[42:43]
	v_cvt_pk_bf16_f32 v40, v34, v35
	v_cvt_pk_bf16_f32 v41, v32, v33
	global_store_dwordx2 v[126:127], v[40:41], off offset:512
	s_waitcnt vmcnt(13)
	v_pk_mul_f32 v[40:41], v[62:63], v[62:63]
	v_pk_mul_f32 v[42:43], v[60:61], v[60:61]
	s_nop 0
	v_pk_mov_b32 v[44:45], v[42:43], v[40:41] op_sel:[1,0]
	v_mov_b32_e32 v43, v41
	v_pk_add_f32 v[40:41], v[44:45], v[42:43]
	s_waitcnt vmcnt(12)
	v_pk_mul_f32 v[42:43], v[58:59], v[58:59]
	v_pk_mul_f32 v[44:45], v[56:57], v[56:57]
	v_pk_add_f32 v[40:41], v[40:41], v[40:41] op_sel:[0,1] op_sel_hi:[1,0]
	v_pk_mov_b32 v[46:47], v[44:45], v[42:43] op_sel:[1,0]
	v_mov_b32_e32 v45, v43
	v_pk_add_f32 v[42:43], v[46:47], v[44:45]
	s_waitcnt vmcnt(10)
	v_mul_f32_e32 v41, v48, v48
	v_pk_add_f32 v[42:43], v[42:43], v[42:43] op_sel:[0,1] op_sel_hi:[1,0]
	v_mul_f32_e32 v44, v55, v55
	v_mul_f32_e32 v43, v49, v49
	v_pk_add_f32 v[40:41], v[40:41], v[42:43]
	v_mul_f32_e32 v42, v53, v53
	v_pk_fma_f32 v[42:43], v[52:53], v[52:53], v[42:43] op_sel_hi:[1,1,0]
	v_pk_fma_f32 v[44:45], v[54:55], v[54:55], v[44:45] op_sel_hi:[1,1,0]
	v_mul_f32_e32 v43, v50, v50
	v_mul_f32_e32 v45, v51, v51
	v_pk_add_f32 v[42:43], v[42:43], v[44:45]
	v_pk_mul_f32 v[44:45], v[8:9], v[120:121]
	v_pk_add_f32 v[40:41], v[40:41], v[42:43]
	v_add_f32_e32 v40, v40, v41
	ds_bpermute_b32 v41, v112, v40
	v_pk_mul_f32 v[42:43], v[10:11], v[122:123]
	s_waitcnt lgkmcnt(0)
	v_add_f32_e32 v41, v40, v41
	ds_bpermute_b32 v47, v113, v41
	v_cvt_pk_bf16_f32 v40, v44, v45
	s_waitcnt lgkmcnt(0)
	v_add_f32_e32 v41, v41, v47
	ds_bpermute_b32 v46, v114, v41
	s_waitcnt lgkmcnt(0)
	v_add_f32_e32 v46, v41, v46
	ds_bpermute_b32 v121, v115, v46
	v_cvt_pk_bf16_f32 v41, v42, v43
	global_store_dwordx2 v[126:127], v[40:41], off offset:1024
	v_pk_mul_f32 v[40:41], v[14:15], v[110:111]
	s_waitcnt lgkmcnt(0)
	v_add_f32_e32 v110, v46, v121
	ds_bpermute_b32 v111, v116, v110
	v_pk_mul_f32 v[46:47], v[12:13], v[124:125]
	s_waitcnt lgkmcnt(0)
	v_add_f32_e32 v111, v110, v111
	ds_bpermute_b32 v121, v117, v111
	v_cvt_pk_bf16_f32 v110, v46, v47
	s_waitcnt lgkmcnt(0)
; #define LAS __attribute__((address_space(3)))
; __device__ __forceinline__ unsigned pk2(float lo, float hi) { return f2bf(lo) | (f2bf(hi) << 16); }
; __device__ __forceinline__ void phase_prologue(const Params& P, LAS unsigned char* lds) {
;     ...
;         for (int q = 0; q < RP; ++q) {
;             float ss = 0.f;
; #pragma unroll
;             for (int j = 0; j < 4; ++j) ss += (v[q][j][0] * v[q][j][0] + v[q][j][1] * v[q][j][1]) + (v[q][j][2] * v[q][j][2] + v[q][j][3] * v[q][j][3]);
;             const float rstd = 1.0f / sqrtf(wave_sum(ss) * (1.0f / DM) + RMS_EPS);
;             unsigned long long* o8 = (unsigned long long*)(HB + (size_t)(m0 + q * NGW) * DM) + lane;
; #pragma unroll
;             for (int j = 0; j < 4; ++j) { v[q][j] = v[q][j] * rstd * ng[j]; o8[64 * j] = (unsigned long long)pk2(v[q][j][0], v[q][j][1]) | ((unsigned long long)pk2(v[q][j][2], v[q][j][3]) << 32); }
;         }
;     ...
;         for (int r = 0; r < 16; ++r) {
;             float sacc[RP];
; #pragma unroll
;             for (int q = 0; q < RP; ++q) sacc[q] = 0.f;
; #pragma unroll
;             for (int j = 0; j < 4; ++j) { const f32x4 wv = *(const LAS f32x4*)(Wl + r * 1024 + 4 * lane + 256 * j);
; #pragma unroll
;                 for (int q = 0; q < RP; ++q) sacc[q] += (v[q][j][0] * wv[0] + v[q][j][1] * wv[1]) + (v[q][j][2] * wv[2] + v[q][j][3] * wv[3]); }
	v_add_f32_e32 v111, v111, v121
	v_fmamk_f32 v111, v111, 0x3a800000, v65
	v_mul_f32_e32 v121, 0x4f800000, v111
	v_cmp_gt_f32_e32 vcc, s16, v111
	s_nop 1
	v_cndmask_b32_e32 v111, v111, v121, vcc
	v_sqrt_f32_e32 v121, v111
	s_nop 0
	v_add_u32_e32 v123, -1, v121
	v_fma_f32 v124, -v123, v121, v111
	v_cmp_ge_f32_e64 s[14:15], 0, v124
	v_add_u32_e32 v124, 1, v121
	s_nop 0
	v_cndmask_b32_e64 v123, v121, v123, s[14:15]
	v_fma_f32 v121, -v124, v121, v111
	v_cmp_lt_f32_e64 s[14:15], 0, v121
	s_nop 1
	v_cndmask_b32_e64 v121, v123, v124, s[14:15]
	v_mul_f32_e32 v123, 0x37800000, v121
	v_cndmask_b32_e32 v121, v121, v123, vcc
	v_cmp_class_f32_e32 vcc, v111, v119
	s_nop 1
	v_cndmask_b32_e32 v121, v121, v111, vcc
	v_div_scale_f32 v123, s[14:15], v121, v121, 1.0
	v_rcp_f32_e32 v124, v123
	v_cvt_pk_bf16_f32 v111, v40, v41
	global_store_dwordx2 v[126:127], v[110:111], off offset:1536
	v_fma_f32 v110, -v123, v124, 1.0
	v_fmac_f32_e32 v124, v110, v124
	v_div_scale_f32 v110, vcc, 1.0, v121, 1.0
	v_mul_f32_e32 v111, v110, v124
	v_fma_f32 v120, -v123, v111, v110
	v_fmac_f32_e32 v111, v120, v124
	v_fma_f32 v110, -v123, v111, v110
	v_div_fmas_f32 v110, v110, v124, v111
	v_div_fixup_f32 v110, v110, v121, 1.0
	v_pk_mul_f32 v[60:61], v[60:61], v[110:111] op_sel_hi:[1,0]
	v_pk_mul_f32 v[122:123], v[54:55], v[110:111] op_sel_hi:[1,0]
	v_pk_mul_f32 v[54:55], v[0:1], v[60:61]
	v_pk_mul_f32 v[124:125], v[48:49], v[110:111] op_sel_hi:[1,0]
	v_pk_mul_f32 v[62:63], v[62:63], v[110:111] op_sel_hi:[1,0]
	v_pk_mul_f32 v[120:121], v[52:53], v[110:111] op_sel_hi:[1,0]
	v_pk_mul_f32 v[52:53], v[2:3], v[62:63]
	v_cvt_pk_bf16_f32 v48, v54, v55
	v_pk_mul_f32 v[56:57], v[56:57], v[110:111] op_sel_hi:[1,0]
	v_pk_mul_f32 v[58:59], v[58:59], v[110:111] op_sel_hi:[1,0]
	v_pk_mul_f32 v[110:111], v[50:51], v[110:111] op_sel_hi:[1,0]
	v_cvt_pk_bf16_f32 v49, v52, v53
	v_lshlrev_b64 v[50:51], 11, v[92:93]
	v_lshl_add_u64 v[126:127], v[70:71], 0, v[50:51]
	v_pk_mul_f32 v[50:51], v[4:5], v[56:57]
	global_store_dwordx2 v[126:127], v[48:49], off
	v_pk_mul_f32 v[48:49], v[6:7], v[58:59]
	v_cvt_pk_bf16_f32 v56, v50, v51
	v_cvt_pk_bf16_f32 v57, v48, v49
	global_store_dwordx2 v[126:127], v[56:57], off offset:512
	s_waitcnt vmcnt(13)
	v_pk_mul_f32 v[56:57], v[30:31], v[30:31]
	v_pk_mul_f32 v[58:59], v[28:29], v[28:29]
	s_nop 0
	v_pk_mov_b32 v[60:61], v[58:59], v[56:57] op_sel:[1,0]
	v_mov_b32_e32 v59, v57
	v_pk_add_f32 v[56:57], v[60:61], v[58:59]
	s_waitcnt vmcnt(12)
	v_pk_mul_f32 v[58:59], v[26:27], v[26:27]
	v_pk_mul_f32 v[60:61], v[24:25], v[24:25]
	v_pk_add_f32 v[56:57], v[56:57], v[56:57] op_sel:[0,1] op_sel_hi:[1,0]
	v_pk_mov_b32 v[62:63], v[60:61], v[58:59] op_sel:[1,0]
	v_mov_b32_e32 v61, v59
	v_pk_add_f32 v[58:59], v[62:63], v[60:61]
	s_waitcnt vmcnt(10)
	v_mul_f32_e32 v57, v16, v16
	v_pk_add_f32 v[58:59], v[58:59], v[58:59] op_sel:[0,1] op_sel_hi:[1,0]
	v_mul_f32_e32 v60, v23, v23
	v_mul_f32_e32 v59, v17, v17
	v_pk_add_f32 v[56:57], v[56:57], v[58:59]
	v_mul_f32_e32 v58, v21, v21
	v_pk_fma_f32 v[58:59], v[20:21], v[20:21], v[58:59] op_sel_hi:[1,1,0]
	v_pk_fma_f32 v[60:61], v[22:23], v[22:23], v[60:61] op_sel_hi:[1,1,0]
	v_mul_f32_e32 v59, v18, v18
	v_mul_f32_e32 v61, v19, v19
	v_pk_add_f32 v[58:59], v[58:59], v[60:61]
	v_pk_mul_f32 v[62:63], v[8:9], v[120:121]
	v_pk_add_f32 v[56:57], v[56:57], v[58:59]
	v_add_f32_e32 v56, v56, v57
	ds_bpermute_b32 v57, v112, v56
	v_pk_mul_f32 v[58:59], v[10:11], v[122:123]
	s_waitcnt lgkmcnt(0)
	v_add_f32_e32 v57, v56, v57
	ds_bpermute_b32 v61, v113, v57
	v_cvt_pk_bf16_f32 v56, v62, v63
	s_waitcnt lgkmcnt(0)
	v_add_f32_e32 v57, v57, v61
	ds_bpermute_b32 v60, v114, v57
	s_waitcnt lgkmcnt(0)
	v_add_f32_e32 v60, v57, v60
	ds_bpermute_b32 v121, v115, v60
	v_cvt_pk_bf16_f32 v57, v58, v59
	global_store_dwordx2 v[126:127], v[56:57], off offset:1024
	v_pk_mul_f32 v[56:57], v[14:15], v[110:111]
	s_waitcnt lgkmcnt(0)
	v_add_f32_e32 v110, v60, v121
	ds_bpermute_b32 v111, v116, v110
	v_pk_mul_f32 v[60:61], v[12:13], v[124:125]
	s_waitcnt lgkmcnt(0)
	v_add_f32_e32 v111, v110, v111
	ds_bpermute_b32 v121, v117, v111
	v_cvt_pk_bf16_f32 v110, v60, v61
	s_waitcnt lgkmcnt(0)
	v_add_f32_e32 v111, v111, v121
	v_fmamk_f32 v111, v111, 0x3a800000, v65
	v_mul_f32_e32 v121, 0x4f800000, v111
	v_cmp_gt_f32_e32 vcc, s16, v111
	s_nop 1
	v_cndmask_b32_e32 v111, v111, v121, vcc
	v_sqrt_f32_e32 v121, v111
	s_nop 0
	v_add_u32_e32 v123, -1, v121
	v_fma_f32 v124, -v123, v121, v111
	v_cmp_ge_f32_e64 s[14:15], 0, v124
	v_add_u32_e32 v124, 1, v121
	s_nop 0
	v_cndmask_b32_e64 v123, v121, v123, s[14:15]
	v_fma_f32 v121, -v124, v121, v111
	v_cmp_lt_f32_e64 s[14:15], 0, v121
	s_nop 1
	v_cndmask_b32_e64 v121, v123, v124, s[14:15]
	v_mul_f32_e32 v123, 0x37800000, v121
	v_cndmask_b32_e32 v121, v121, v123, vcc
	v_cmp_class_f32_e32 vcc, v111, v119
	s_nop 1
	v_cndmask_b32_e32 v121, v121, v111, vcc
	v_div_scale_f32 v123, s[14:15], v121, v121, 1.0
	v_rcp_f32_e32 v124, v123
	v_cvt_pk_bf16_f32 v111, v56, v57
	global_store_dwordx2 v[126:127], v[110:111], off offset:1536
	v_fma_f32 v110, -v123, v124, 1.0
	v_fmac_f32_e32 v124, v110, v124
	v_div_scale_f32 v110, vcc, 1.0, v121, 1.0
	v_mul_f32_e32 v111, v110, v124
	v_fma_f32 v120, -v123, v111, v110
	v_fmac_f32_e32 v111, v120, v124
	v_fma_f32 v110, -v123, v111, v110
	v_div_fmas_f32 v110, v110, v124, v111
	v_div_fixup_f32 v110, v110, v121, 1.0
	v_pk_mul_f32 v[120:121], v[28:29], v[110:111] op_sel_hi:[1,0]
	v_pk_mul_f32 v[28:29], v[30:31], v[110:111] op_sel_hi:[1,0]
	v_pk_mul_f32 v[30:31], v[0:1], v[120:121]
	v_pk_mul_f32 v[126:127], v[16:17], v[110:111] op_sel_hi:[1,0]
	v_pk_mul_f32 v[16:17], v[18:19], v[110:111] op_sel_hi:[1,0]
	v_pk_mul_f32 v[28:29], v[2:3], v[28:29]
	v_cvt_pk_bf16_f32 v18, v30, v31
	v_pk_mul_f32 v[124:125], v[20:21], v[110:111] op_sel_hi:[1,0]
	v_pk_mul_f32 v[20:21], v[22:23], v[110:111] op_sel_hi:[1,0]
	v_pk_mul_f32 v[122:123], v[24:25], v[110:111] op_sel_hi:[1,0]
	v_cvt_pk_bf16_f32 v19, v28, v29
	v_lshlrev_b64 v[22:23], 11, v[90:91]
	v_pk_mul_f32 v[24:25], v[26:27], v[110:111] op_sel_hi:[1,0]
	v_lshl_add_u64 v[110:111], v[70:71], 0, v[22:23]
	v_pk_mul_f32 v[26:27], v[4:5], v[122:123]
	global_store_dwordx2 v[110:111], v[18:19], off
	v_pk_mul_f32 v[24:25], v[6:7], v[24:25]
	v_cvt_pk_bf16_f32 v18, v26, v27
	v_cvt_pk_bf16_f32 v19, v24, v25
	v_pk_mul_f32 v[22:23], v[8:9], v[124:125]
	global_store_dwordx2 v[110:111], v[18:19], off offset:512
	v_pk_mul_f32 v[20:21], v[10:11], v[20:21]
	v_cvt_pk_bf16_f32 v18, v22, v23
	v_cvt_pk_bf16_f32 v19, v20, v21
	global_store_dwordx2 v[110:111], v[18:19], off offset:1024
	v_pk_mul_f32 v[18:19], v[12:13], v[126:127]
	v_pk_mul_f32 v[16:17], v[14:15], v[16:17]
	v_cvt_pk_bf16_f32 v124, v18, v19
	ds_read_b128 v[120:123], v118
	v_cvt_pk_bf16_f32 v125, v16, v17
	global_store_dwordx2 v[110:111], v[124:125], off offset:1536
	ds_read_b128 v[124:127], v118 offset:1024
	s_waitcnt lgkmcnt(1)
; #define LAS __attribute__((address_space(3)))
; __device__ __forceinline__ void phase_prologue(const Params& P, LAS unsigned char* lds) {
;     ...
;         for (int r = 0; r < 16; ++r) {
;             float sacc[RP];
; #pragma unroll
;             for (int q = 0; q < RP; ++q) sacc[q] = 0.f;
; #pragma unroll
;             for (int j = 0; j < 4; ++j) { const f32x4 wv = *(const LAS f32x4*)(Wl + r * 1024 + 4 * lane + 256 * j);
; #pragma unroll
;                 for (int q = 0; q < RP; ++q) sacc[q] += (v[q][j][0] * wv[0] + v[q][j][1] * wv[1]) + (v[q][j][2] * wv[2] + v[q][j][3] * wv[3]); }
;             asm volatile("" : "+v"(sacc[0]), "+v"(sacc[1]), "+v"(sacc[2]), "+v"(sacc[3]) :: "memory");
; #pragma unroll
;             for (int q = 0; q < RP; ++q) a[q][r] = sacc[q];
;         }
	v_mul_f32_e32 v110, v109, v121
	v_mul_f32_e32 v111, v107, v123
	v_mul_f32_e32 v128, v39, v121
	v_mul_f32_e32 v129, v37, v123
	v_mul_f32_e32 v130, v55, v121
	v_mul_f32_e32 v131, v53, v123
	v_mul_f32_e32 v132, v121, v31
	v_mul_f32_e32 v133, v123, v29
	v_fmac_f32_e32 v110, v108, v120
	v_fmac_f32_e32 v111, v106, v122
	v_fmac_f32_e32 v128, v38, v120
	v_fmac_f32_e32 v129, v36, v122
	v_fmac_f32_e32 v130, v54, v120
	v_fmac_f32_e32 v131, v52, v122
	v_fmac_f32_e32 v132, v120, v30
	v_fmac_f32_e32 v133, v122, v28
	ds_read_b128 v[120:123], v118 offset:2048
	s_waitcnt lgkmcnt(1)
	v_mul_f32_e32 v134, v105, v125
	v_mul_f32_e32 v135, v103, v127
	v_mul_f32_e32 v136, v35, v125
	v_mul_f32_e32 v137, v33, v127
	v_mul_f32_e32 v138, v51, v125
	v_mul_f32_e32 v139, v49, v127
	v_mul_f32_e32 v140, v125, v27
	v_mul_f32_e32 v141, v127, v25
	v_fmac_f32_e32 v134, v104, v124
	v_fmac_f32_e32 v135, v102, v126
	v_fmac_f32_e32 v136, v34, v124
	v_fmac_f32_e32 v137, v32, v126
	v_fmac_f32_e32 v138, v50, v124
	v_fmac_f32_e32 v139, v48, v126
	v_fmac_f32_e32 v140, v124, v26
	v_fmac_f32_e32 v141, v126, v24
	ds_read_b128 v[124:127], v118 offset:3072
	s_waitcnt lgkmcnt(1)
	v_mul_f32_e32 v142, v97, v121
	v_mul_f32_e32 v144, v45, v121
	v_mul_f32_e32 v146, v63, v121
	v_mul_f32_e32 v121, v121, v23
	v_fmac_f32_e32 v142, v96, v120
	v_mul_f32_e32 v143, v95, v123
	v_fmac_f32_e32 v144, v44, v120
	v_mul_f32_e32 v145, v43, v123
	v_fmac_f32_e32 v146, v62, v120
	v_mul_f32_e32 v147, v59, v123
	v_fmac_f32_e32 v121, v120, v22
	v_mul_f32_e32 v120, v123, v21
	v_fmac_f32_e32 v143, v94, v122
	v_fmac_f32_e32 v145, v42, v122
	v_fmac_f32_e32 v147, v58, v122
	v_fmac_f32_e32 v120, v122, v20
	s_waitcnt lgkmcnt(0)
	v_mul_f32_e32 v122, v101, v125
	v_mul_f32_e32 v148, v47, v125
	v_mul_f32_e32 v150, v61, v125
	v_mul_f32_e32 v125, v125, v19
	v_add_f32_e32 v110, v110, v111
	v_fmac_f32_e32 v122, v100, v124
	v_mul_f32_e32 v123, v99, v127
	v_fmac_f32_e32 v148, v46, v124
	v_mul_f32_e32 v149, v41, v127
	v_fmac_f32_e32 v150, v60, v124
	v_mul_f32_e32 v151, v57, v127
	v_fmac_f32_e32 v125, v124, v18
	v_mul_f32_e32 v124, v127, v17
	v_add_f32_e32 v111, v128, v129
	v_add_f32_e32 v128, v134, v135
	v_add_f32_e32 v110, 0, v110
	v_fmac_f32_e32 v123, v98, v126
	v_fmac_f32_e32 v149, v40, v126
	v_fmac_f32_e32 v151, v56, v126
	v_fmac_f32_e32 v124, v126, v16
	v_add_f32_e32 v126, v130, v131
	v_add_f32_e32 v110, v110, v128
	v_add_f32_e32 v128, v136, v137
	v_add_f32_e32 v111, 0, v111
	v_add_f32_e32 v127, v132, v133
	v_add_f32_e32 v111, v111, v128
	v_add_f32_e32 v128, v138, v139
	v_add_f32_e32 v126, 0, v126
	v_add_f32_e32 v126, v126, v128
	v_add_f32_e32 v128, v140, v141
	v_add_f32_e32 v127, 0, v127
	v_add_f32_e32 v127, v128, v127
	v_add_f32_e32 v128, v142, v143
	v_add_f32_e32 v120, v121, v120
	v_add_f32_e32 v110, v110, v128
	v_add_f32_e32 v128, v144, v145
	v_add_f32_e32 v121, v120, v127
	v_add_f32_e32 v120, v122, v123
	v_add_f32_e32 v111, v111, v128
	v_add_f32_e32 v128, v146, v147
	v_add_f32_e32 v122, v110, v120
	v_add_f32_e32 v110, v148, v149
	v_add_f32_e32 v126, v126, v128
	v_add_f32_e32 v120, v111, v110
	v_add_f32_e32 v110, v150, v151
	v_add_f32_e32 v111, v126, v110
	v_add_f32_e32 v110, v125, v124
	v_add_f32_e32 v110, v110, v121
	ds_read_b128 v[124:127], v118 offset:4096
	ds_read_b128 v[128:131], v118 offset:5120
	s_waitcnt lgkmcnt(1)
	v_mul_f32_e32 v121, v109, v125
	v_mul_f32_e32 v123, v107, v127
	v_mul_f32_e32 v132, v39, v125
	v_mul_f32_e32 v133, v37, v127
	v_mul_f32_e32 v134, v55, v125
	v_mul_f32_e32 v135, v53, v127
	v_mul_f32_e32 v136, v125, v31
	v_mul_f32_e32 v137, v127, v29
	v_fmac_f32_e32 v121, v108, v124
	v_fmac_f32_e32 v123, v106, v126
	v_fmac_f32_e32 v132, v38, v124
	v_fmac_f32_e32 v133, v36, v126
	v_fmac_f32_e32 v134, v54, v124
	v_fmac_f32_e32 v135, v52, v126
	v_fmac_f32_e32 v136, v124, v30
	v_fmac_f32_e32 v137, v126, v28
	ds_read_b128 v[124:127], v118 offset:6144
	s_waitcnt lgkmcnt(1)
	v_mul_f32_e32 v138, v105, v129
	v_mul_f32_e32 v139, v103, v131
	v_mul_f32_e32 v140, v35, v129
	v_mul_f32_e32 v141, v33, v131
	v_mul_f32_e32 v142, v51, v129
	v_mul_f32_e32 v143, v49, v131
	v_mul_f32_e32 v144, v27, v129
	v_mul_f32_e32 v145, v25, v131
	v_fmac_f32_e32 v138, v104, v128
	v_fmac_f32_e32 v139, v102, v130
	v_fmac_f32_e32 v140, v34, v128
	v_fmac_f32_e32 v141, v32, v130
	v_fmac_f32_e32 v142, v50, v128
	v_fmac_f32_e32 v143, v48, v130
	v_fmac_f32_e32 v144, v26, v128
	v_fmac_f32_e32 v145, v24, v130
	ds_read_b128 v[128:131], v118 offset:7168
	s_waitcnt lgkmcnt(1)
	v_mul_f32_e32 v146, v97, v125
	v_mul_f32_e32 v148, v45, v125
	v_mul_f32_e32 v150, v63, v125
	v_mul_f32_e32 v125, v23, v125
	v_fmac_f32_e32 v146, v96, v124
	v_mul_f32_e32 v147, v95, v127
	v_fmac_f32_e32 v148, v44, v124
	v_mul_f32_e32 v149, v43, v127
	v_fmac_f32_e32 v150, v62, v124
	v_mul_f32_e32 v151, v59, v127
	v_fmac_f32_e32 v125, v22, v124
	v_mul_f32_e32 v124, v21, v127
	v_fmac_f32_e32 v147, v94, v126
	v_fmac_f32_e32 v149, v42, v126
	v_fmac_f32_e32 v151, v58, v126
	v_fmac_f32_e32 v124, v20, v126
	s_waitcnt lgkmcnt(0)
; #define LAS __attribute__((address_space(3)))
; __device__ __forceinline__ void phase_prologue(const Params& P, LAS unsigned char* lds) {
;     ...
;         for (int r = 0; r < 16; ++r) {
;             float sacc[RP];
; #pragma unroll
;             for (int q = 0; q < RP; ++q) sacc[q] = 0.f;
; #pragma unroll
;             for (int j = 0; j < 4; ++j) { const f32x4 wv = *(const LAS f32x4*)(Wl + r * 1024 + 4 * lane + 256 * j);
; #pragma unroll
;                 for (int q = 0; q < RP; ++q) sacc[q] += (v[q][j][0] * wv[0] + v[q][j][1] * wv[1]) + (v[q][j][2] * wv[2] + v[q][j][3] * wv[3]); }
;             asm volatile("" : "+v"(sacc[0]), "+v"(sacc[1]), "+v"(sacc[2]), "+v"(sacc[3]) :: "memory");
; #pragma unroll
;             for (int q = 0; q < RP; ++q) a[q][r] = sacc[q];
;         }
	v_mul_f32_e32 v126, v101, v129
	v_mul_f32_e32 v152, v47, v129
	v_mul_f32_e32 v154, v61, v129
	v_mul_f32_e32 v129, v19, v129
	v_add_f32_e32 v121, v121, v123
	v_fmac_f32_e32 v126, v100, v128
	v_mul_f32_e32 v127, v99, v131
	v_fmac_f32_e32 v152, v46, v128
	v_mul_f32_e32 v153, v41, v131
	v_fmac_f32_e32 v154, v60, v128
	v_mul_f32_e32 v155, v57, v131
	v_fmac_f32_e32 v129, v18, v128
	v_mul_f32_e32 v128, v17, v131
	v_add_f32_e32 v123, v132, v133
	v_add_f32_e32 v132, v138, v139
	v_add_f32_e32 v121, 0, v121
	v_fmac_f32_e32 v127, v98, v130
	v_fmac_f32_e32 v153, v40, v130
	v_fmac_f32_e32 v155, v56, v130
	v_fmac_f32_e32 v128, v16, v130
	v_add_f32_e32 v130, v134, v135
	v_add_f32_e32 v121, v121, v132
	v_add_f32_e32 v132, v140, v141
	v_add_f32_e32 v123, 0, v123
	v_add_f32_e32 v131, v136, v137
	v_add_f32_e32 v123, v123, v132
	v_add_f32_e32 v132, v142, v143
	v_add_f32_e32 v130, 0, v130
	v_add_f32_e32 v130, v130, v132
	v_add_f32_e32 v132, v144, v145
	v_add_f32_e32 v131, 0, v131
	v_add_f32_e32 v131, v131, v132
	v_add_f32_e32 v132, v146, v147
	v_add_f32_e32 v124, v125, v124
	v_add_f32_e32 v121, v121, v132
	v_add_f32_e32 v132, v148, v149
	v_add_f32_e32 v125, v131, v124
	v_add_f32_e32 v124, v126, v127
	v_add_f32_e32 v123, v123, v132
	v_add_f32_e32 v132, v150, v151
	v_add_f32_e32 v126, v121, v124
	v_add_f32_e32 v121, v152, v153
	v_add_f32_e32 v130, v130, v132
	v_add_f32_e32 v124, v123, v121
	v_add_f32_e32 v121, v154, v155
	v_add_f32_e32 v123, v130, v121
	v_add_f32_e32 v121, v129, v128
	v_add_f32_e32 v121, v125, v121
	ds_read_b128 v[128:131], v118 offset:8192
	ds_read_b128 v[132:135], v118 offset:9216
	s_waitcnt lgkmcnt(1)
	v_mul_f32_e32 v125, v109, v129
	v_mul_f32_e32 v127, v107, v131
	v_mul_f32_e32 v136, v39, v129
	v_mul_f32_e32 v137, v37, v131
	v_mul_f32_e32 v138, v55, v129
	v_mul_f32_e32 v139, v53, v131
	v_mul_f32_e32 v140, v31, v129
	v_mul_f32_e32 v141, v29, v131
	v_fmac_f32_e32 v125, v108, v128
	v_fmac_f32_e32 v127, v106, v130
	v_fmac_f32_e32 v136, v38, v128
	v_fmac_f32_e32 v137, v36, v130
	v_fmac_f32_e32 v138, v54, v128
	v_fmac_f32_e32 v139, v52, v130
	v_fmac_f32_e32 v140, v30, v128
	v_fmac_f32_e32 v141, v28, v130
	ds_read_b128 v[128:131], v118 offset:10240
	s_waitcnt lgkmcnt(1)
	v_mul_f32_e32 v142, v105, v133
	v_mul_f32_e32 v143, v103, v135
	v_mul_f32_e32 v144, v35, v133
	v_mul_f32_e32 v145, v33, v135
	v_mul_f32_e32 v146, v51, v133
	v_mul_f32_e32 v147, v49, v135
	v_mul_f32_e32 v148, v27, v133
	v_mul_f32_e32 v149, v25, v135
	v_fmac_f32_e32 v142, v104, v132
	v_fmac_f32_e32 v143, v102, v134
	v_fmac_f32_e32 v144, v34, v132
	v_fmac_f32_e32 v145, v32, v134
	v_fmac_f32_e32 v146, v50, v132
	v_fmac_f32_e32 v147, v48, v134
	v_fmac_f32_e32 v148, v26, v132
	v_fmac_f32_e32 v149, v24, v134
	ds_read_b128 v[132:135], v118 offset:11264
	s_waitcnt lgkmcnt(1)
	v_mul_f32_e32 v150, v97, v129
	v_mul_f32_e32 v152, v45, v129
	v_mul_f32_e32 v154, v63, v129
	v_mul_f32_e32 v129, v23, v129
	v_fmac_f32_e32 v150, v96, v128
	v_mul_f32_e32 v151, v95, v131
	v_fmac_f32_e32 v152, v44, v128
	v_mul_f32_e32 v153, v43, v131
	v_fmac_f32_e32 v154, v62, v128
	v_mul_f32_e32 v155, v59, v131
	v_fmac_f32_e32 v129, v22, v128
	v_mul_f32_e32 v128, v21, v131
	v_fmac_f32_e32 v151, v94, v130
	v_fmac_f32_e32 v153, v42, v130
	v_fmac_f32_e32 v155, v58, v130
	v_fmac_f32_e32 v128, v20, v130
	s_waitcnt lgkmcnt(0)
	v_mul_f32_e32 v130, v101, v133
	v_mul_f32_e32 v156, v47, v133
	v_mul_f32_e32 v158, v61, v133
	v_mul_f32_e32 v133, v19, v133
	v_add_f32_e32 v125, v125, v127
	v_fmac_f32_e32 v130, v100, v132
	v_mul_f32_e32 v131, v99, v135
	v_fmac_f32_e32 v156, v46, v132
	v_mul_f32_e32 v157, v41, v135
	v_fmac_f32_e32 v158, v60, v132
	v_mul_f32_e32 v159, v57, v135
	v_fmac_f32_e32 v133, v18, v132
	v_mul_f32_e32 v132, v17, v135
	v_add_f32_e32 v127, v136, v137
	v_add_f32_e32 v136, v142, v143
	v_add_f32_e32 v125, 0, v125
	v_fmac_f32_e32 v131, v98, v134
	v_fmac_f32_e32 v157, v40, v134
	v_fmac_f32_e32 v159, v56, v134
	v_fmac_f32_e32 v132, v16, v134
	v_add_f32_e32 v134, v138, v139
	v_add_f32_e32 v125, v125, v136
	v_add_f32_e32 v136, v144, v145
	v_add_f32_e32 v127, 0, v127
	v_add_f32_e32 v135, v140, v141
	v_add_f32_e32 v127, v127, v136
	v_add_f32_e32 v136, v146, v147
	v_add_f32_e32 v134, 0, v134
	v_add_f32_e32 v134, v134, v136
	v_add_f32_e32 v136, v148, v149
	v_add_f32_e32 v135, 0, v135
	v_add_f32_e32 v135, v135, v136
	v_add_f32_e32 v136, v150, v151
	v_add_f32_e32 v128, v129, v128
	v_add_f32_e32 v125, v125, v136
	v_add_f32_e32 v136, v152, v153
	v_add_f32_e32 v129, v135, v128
	v_add_f32_e32 v128, v130, v131
	v_add_f32_e32 v127, v127, v136
	v_add_f32_e32 v136, v154, v155
	v_add_f32_e32 v130, v125, v128
	v_add_f32_e32 v125, v156, v157
	v_add_f32_e32 v134, v134, v136
	v_add_f32_e32 v128, v127, v125
	v_add_f32_e32 v125, v158, v159
	v_add_f32_e32 v127, v134, v125
	v_add_f32_e32 v125, v133, v132
	v_add_f32_e32 v125, v129, v125
	ds_read_b128 v[132:135], v118 offset:12288
	ds_read_b128 v[136:139], v118 offset:13312
	s_waitcnt lgkmcnt(1)
	v_mul_f32_e32 v129, v109, v133
	v_mul_f32_e32 v131, v107, v135
	v_mul_f32_e32 v140, v39, v133
	v_mul_f32_e32 v141, v37, v135
	v_mul_f32_e32 v142, v55, v133
	v_mul_f32_e32 v143, v53, v135
	v_mul_f32_e32 v144, v31, v133
	v_mul_f32_e32 v145, v29, v135
	v_fmac_f32_e32 v129, v108, v132
	v_fmac_f32_e32 v131, v106, v134
	v_fmac_f32_e32 v140, v38, v132
	v_fmac_f32_e32 v141, v36, v134
	v_fmac_f32_e32 v142, v54, v132
	v_fmac_f32_e32 v143, v52, v134
	v_fmac_f32_e32 v144, v30, v132
	v_fmac_f32_e32 v145, v28, v134
	ds_read_b128 v[132:135], v118 offset:14336
	s_waitcnt lgkmcnt(1)
; #define LAS __attribute__((address_space(3)))
; __device__ __forceinline__ void phase_prologue(const Params& P, LAS unsigned char* lds) {
;     ...
;         for (int r = 0; r < 16; ++r) {
;             float sacc[RP];
; #pragma unroll
;             for (int q = 0; q < RP; ++q) sacc[q] = 0.f;
; #pragma unroll
;             for (int j = 0; j < 4; ++j) { const f32x4 wv = *(const LAS f32x4*)(Wl + r * 1024 + 4 * lane + 256 * j);
; #pragma unroll
;                 for (int q = 0; q < RP; ++q) sacc[q] += (v[q][j][0] * wv[0] + v[q][j][1] * wv[1]) + (v[q][j][2] * wv[2] + v[q][j][3] * wv[3]); }
;             asm volatile("" : "+v"(sacc[0]), "+v"(sacc[1]), "+v"(sacc[2]), "+v"(sacc[3]) :: "memory");
; #pragma unroll
;             for (int q = 0; q < RP; ++q) a[q][r] = sacc[q];
;         }
	v_mul_f32_e32 v146, v105, v137
	v_mul_f32_e32 v147, v103, v139
	v_mul_f32_e32 v148, v35, v137
	v_mul_f32_e32 v149, v33, v139
	v_mul_f32_e32 v150, v51, v137
	v_mul_f32_e32 v151, v49, v139
	v_mul_f32_e32 v152, v27, v137
	v_mul_f32_e32 v153, v25, v139
	v_fmac_f32_e32 v146, v104, v136
	v_fmac_f32_e32 v147, v102, v138
	v_fmac_f32_e32 v148, v34, v136
	v_fmac_f32_e32 v149, v32, v138
	v_fmac_f32_e32 v150, v50, v136
	v_fmac_f32_e32 v151, v48, v138
	v_fmac_f32_e32 v152, v26, v136
	v_fmac_f32_e32 v153, v24, v138
	ds_read_b128 v[136:139], v118 offset:15360
	s_waitcnt lgkmcnt(1)
	v_mul_f32_e32 v154, v97, v133
	v_mul_f32_e32 v156, v45, v133
	v_mul_f32_e32 v158, v63, v133
	v_mul_f32_e32 v133, v23, v133
	v_fmac_f32_e32 v154, v96, v132
	v_mul_f32_e32 v155, v95, v135
	v_fmac_f32_e32 v156, v44, v132
	v_mul_f32_e32 v157, v43, v135
	v_fmac_f32_e32 v158, v62, v132
	v_mul_f32_e32 v159, v59, v135
	v_fmac_f32_e32 v133, v22, v132
	v_mul_f32_e32 v132, v21, v135
	v_fmac_f32_e32 v155, v94, v134
	v_fmac_f32_e32 v157, v42, v134
	v_fmac_f32_e32 v159, v58, v134
	v_fmac_f32_e32 v132, v20, v134
	s_waitcnt lgkmcnt(0)
	v_mul_f32_e32 v134, v101, v137
	v_mul_f32_e32 v160, v47, v137
	v_mul_f32_e32 v162, v61, v137
	v_mul_f32_e32 v137, v19, v137
	v_add_f32_e32 v129, v129, v131
	v_fmac_f32_e32 v134, v100, v136
	v_mul_f32_e32 v135, v99, v139
	v_fmac_f32_e32 v160, v46, v136
	v_mul_f32_e32 v161, v41, v139
	v_fmac_f32_e32 v162, v60, v136
	v_mul_f32_e32 v163, v57, v139
	v_fmac_f32_e32 v137, v18, v136
	v_mul_f32_e32 v136, v17, v139
	v_add_f32_e32 v131, v140, v141
	v_add_f32_e32 v140, v146, v147
	v_add_f32_e32 v129, 0, v129
	v_fmac_f32_e32 v135, v98, v138
	v_fmac_f32_e32 v161, v40, v138
	v_fmac_f32_e32 v163, v56, v138
	v_fmac_f32_e32 v136, v16, v138
	v_add_f32_e32 v138, v142, v143
	v_add_f32_e32 v129, v129, v140
	v_add_f32_e32 v140, v148, v149
	v_add_f32_e32 v131, 0, v131
	v_add_f32_e32 v139, v144, v145
	v_add_f32_e32 v131, v131, v140
	v_add_f32_e32 v140, v150, v151
	v_add_f32_e32 v138, 0, v138
	v_add_f32_e32 v138, v138, v140
	v_add_f32_e32 v140, v152, v153
	v_add_f32_e32 v139, 0, v139
	v_add_f32_e32 v139, v139, v140
	v_add_f32_e32 v140, v154, v155
	v_add_f32_e32 v132, v133, v132
	v_add_f32_e32 v129, v129, v140
	v_add_f32_e32 v140, v156, v157
	v_add_f32_e32 v133, v139, v132
	v_add_f32_e32 v132, v134, v135
	v_add_f32_e32 v131, v131, v140
	v_add_f32_e32 v140, v158, v159
	v_add_f32_e32 v134, v129, v132
	v_add_f32_e32 v129, v160, v161
	v_add_f32_e32 v138, v138, v140
	v_add_f32_e32 v132, v131, v129
	v_add_f32_e32 v129, v162, v163
	v_add_f32_e32 v131, v138, v129
	v_add_f32_e32 v129, v137, v136
	v_add_f32_e32 v129, v133, v129
	ds_read_b128 v[136:139], v118 offset:16384
	ds_read_b128 v[140:143], v118 offset:17408
	s_waitcnt lgkmcnt(1)
	v_mul_f32_e32 v133, v109, v137
	v_mul_f32_e32 v135, v107, v139
	v_mul_f32_e32 v144, v39, v137
	v_mul_f32_e32 v145, v37, v139
	v_mul_f32_e32 v146, v55, v137
	v_mul_f32_e32 v147, v53, v139
	v_mul_f32_e32 v148, v31, v137
	v_mul_f32_e32 v149, v29, v139
	v_fmac_f32_e32 v133, v108, v136
	v_fmac_f32_e32 v135, v106, v138
	v_fmac_f32_e32 v144, v38, v136
	v_fmac_f32_e32 v145, v36, v138
	v_fmac_f32_e32 v146, v54, v136
	v_fmac_f32_e32 v147, v52, v138
	v_fmac_f32_e32 v148, v30, v136
	v_fmac_f32_e32 v149, v28, v138
	ds_read_b128 v[136:139], v118 offset:18432
	s_waitcnt lgkmcnt(1)
	v_mul_f32_e32 v150, v105, v141
	v_mul_f32_e32 v151, v103, v143
	v_mul_f32_e32 v152, v35, v141
	v_mul_f32_e32 v153, v33, v143
	v_mul_f32_e32 v154, v51, v141
	v_mul_f32_e32 v155, v49, v143
	v_mul_f32_e32 v156, v27, v141
	v_mul_f32_e32 v157, v25, v143
	v_fmac_f32_e32 v150, v104, v140
	v_fmac_f32_e32 v151, v102, v142
	v_fmac_f32_e32 v152, v34, v140
	v_fmac_f32_e32 v153, v32, v142
	v_fmac_f32_e32 v154, v50, v140
	v_fmac_f32_e32 v155, v48, v142
	v_fmac_f32_e32 v156, v26, v140
	v_fmac_f32_e32 v157, v24, v142
	ds_read_b128 v[140:143], v118 offset:19456
	s_waitcnt lgkmcnt(1)
	v_mul_f32_e32 v158, v97, v137
	v_mul_f32_e32 v160, v45, v137
	v_mul_f32_e32 v162, v63, v137
	v_mul_f32_e32 v137, v23, v137
	v_fmac_f32_e32 v158, v96, v136
	v_mul_f32_e32 v159, v95, v139
	v_fmac_f32_e32 v160, v44, v136
	v_mul_f32_e32 v161, v43, v139
	v_fmac_f32_e32 v162, v62, v136
	v_mul_f32_e32 v163, v59, v139
	v_fmac_f32_e32 v137, v22, v136
	v_mul_f32_e32 v136, v21, v139
	v_fmac_f32_e32 v159, v94, v138
	v_fmac_f32_e32 v161, v42, v138
	v_fmac_f32_e32 v163, v58, v138
	v_fmac_f32_e32 v136, v20, v138
	s_waitcnt lgkmcnt(0)
	v_mul_f32_e32 v138, v101, v141
	v_mul_f32_e32 v164, v47, v141
	v_mul_f32_e32 v166, v61, v141
	v_mul_f32_e32 v141, v19, v141
	v_add_f32_e32 v133, v133, v135
	v_fmac_f32_e32 v138, v100, v140
	v_mul_f32_e32 v139, v99, v143
	v_fmac_f32_e32 v164, v46, v140
	v_mul_f32_e32 v165, v41, v143
	v_fmac_f32_e32 v166, v60, v140
	v_mul_f32_e32 v167, v57, v143
	v_fmac_f32_e32 v141, v18, v140
	v_mul_f32_e32 v140, v17, v143
	v_add_f32_e32 v135, v144, v145
	v_add_f32_e32 v144, v150, v151
	v_add_f32_e32 v133, 0, v133
	v_fmac_f32_e32 v139, v98, v142
	v_fmac_f32_e32 v165, v40, v142
	v_fmac_f32_e32 v167, v56, v142
	v_fmac_f32_e32 v140, v16, v142
	v_add_f32_e32 v142, v146, v147
	v_add_f32_e32 v133, v133, v144
	v_add_f32_e32 v144, v152, v153
	v_add_f32_e32 v135, 0, v135
	v_add_f32_e32 v143, v148, v149
	v_add_f32_e32 v135, v135, v144
	v_add_f32_e32 v144, v154, v155
	v_add_f32_e32 v142, 0, v142
	v_add_f32_e32 v142, v142, v144
	v_add_f32_e32 v144, v156, v157
	v_add_f32_e32 v143, 0, v143
	v_add_f32_e32 v143, v143, v144
	v_add_f32_e32 v144, v158, v159
	v_add_f32_e32 v136, v137, v136
	v_add_f32_e32 v133, v133, v144
	v_add_f32_e32 v144, v160, v161
	v_add_f32_e32 v137, v143, v136
	v_add_f32_e32 v136, v138, v139
	v_add_f32_e32 v135, v135, v144
	v_add_f32_e32 v144, v162, v163
	v_add_f32_e32 v138, v133, v136
	v_add_f32_e32 v133, v164, v165
	v_add_f32_e32 v142, v142, v144
	v_add_f32_e32 v136, v135, v133
	v_add_f32_e32 v133, v166, v167
	v_add_f32_e32 v135, v142, v133
	v_add_f32_e32 v133, v141, v140
	v_add_f32_e32 v133, v137, v133
	ds_read_b128 v[140:143], v118 offset:20480
	ds_read_b128 v[144:147], v118 offset:21504
	s_waitcnt lgkmcnt(1)
; #define LAS __attribute__((address_space(3)))
; __device__ __forceinline__ void phase_prologue(const Params& P, LAS unsigned char* lds) {
;     ...
;         for (int r = 0; r < 16; ++r) {
;             float sacc[RP];
; #pragma unroll
;             for (int q = 0; q < RP; ++q) sacc[q] = 0.f;
; #pragma unroll
;             for (int j = 0; j < 4; ++j) { const f32x4 wv = *(const LAS f32x4*)(Wl + r * 1024 + 4 * lane + 256 * j);
; #pragma unroll
;                 for (int q = 0; q < RP; ++q) sacc[q] += (v[q][j][0] * wv[0] + v[q][j][1] * wv[1]) + (v[q][j][2] * wv[2] + v[q][j][3] * wv[3]); }
;             asm volatile("" : "+v"(sacc[0]), "+v"(sacc[1]), "+v"(sacc[2]), "+v"(sacc[3]) :: "memory");
; #pragma unroll
;             for (int q = 0; q < RP; ++q) a[q][r] = sacc[q];
;         }
	v_mul_f32_e32 v137, v109, v141
	v_mul_f32_e32 v139, v107, v143
	v_mul_f32_e32 v148, v39, v141
	v_mul_f32_e32 v149, v37, v143
	v_mul_f32_e32 v150, v55, v141
	v_mul_f32_e32 v151, v53, v143
	v_mul_f32_e32 v152, v31, v141
	v_mul_f32_e32 v153, v29, v143
	v_fmac_f32_e32 v137, v108, v140
	v_fmac_f32_e32 v139, v106, v142
	v_fmac_f32_e32 v148, v38, v140
	v_fmac_f32_e32 v149, v36, v142
	v_fmac_f32_e32 v150, v54, v140
	v_fmac_f32_e32 v151, v52, v142
	v_fmac_f32_e32 v152, v30, v140
	v_fmac_f32_e32 v153, v28, v142
	ds_read_b128 v[140:143], v118 offset:22528
	s_waitcnt lgkmcnt(1)
	v_mul_f32_e32 v154, v105, v145
	v_mul_f32_e32 v155, v103, v147
	v_mul_f32_e32 v156, v35, v145
	v_mul_f32_e32 v157, v33, v147
	v_mul_f32_e32 v158, v51, v145
	v_mul_f32_e32 v159, v49, v147
	v_mul_f32_e32 v160, v27, v145
	v_mul_f32_e32 v161, v25, v147
	v_fmac_f32_e32 v154, v104, v144
	v_fmac_f32_e32 v155, v102, v146
	v_fmac_f32_e32 v156, v34, v144
	v_fmac_f32_e32 v157, v32, v146
	v_fmac_f32_e32 v158, v50, v144
	v_fmac_f32_e32 v159, v48, v146
	v_fmac_f32_e32 v160, v26, v144
	v_fmac_f32_e32 v161, v24, v146
	ds_read_b128 v[144:147], v118 offset:23552
	s_waitcnt lgkmcnt(1)
	v_mul_f32_e32 v162, v97, v141
	v_mul_f32_e32 v164, v45, v141
	v_mul_f32_e32 v166, v63, v141
	v_mul_f32_e32 v141, v23, v141
	v_fmac_f32_e32 v162, v96, v140
	v_mul_f32_e32 v163, v95, v143
	v_fmac_f32_e32 v164, v44, v140
	v_mul_f32_e32 v165, v43, v143
	v_fmac_f32_e32 v166, v62, v140
	v_mul_f32_e32 v167, v59, v143
	v_fmac_f32_e32 v141, v22, v140
	v_mul_f32_e32 v140, v21, v143
	v_fmac_f32_e32 v163, v94, v142
	v_fmac_f32_e32 v165, v42, v142
	v_fmac_f32_e32 v167, v58, v142
	v_fmac_f32_e32 v140, v20, v142
	s_waitcnt lgkmcnt(0)
	v_mul_f32_e32 v142, v101, v145
	v_mul_f32_e32 v168, v47, v145
	v_mul_f32_e32 v170, v61, v145
	v_mul_f32_e32 v145, v19, v145
	v_add_f32_e32 v137, v137, v139
	v_fmac_f32_e32 v142, v100, v144
	v_mul_f32_e32 v143, v99, v147
	v_fmac_f32_e32 v168, v46, v144
	v_mul_f32_e32 v169, v41, v147
	v_fmac_f32_e32 v170, v60, v144
	v_mul_f32_e32 v171, v57, v147
	v_fmac_f32_e32 v145, v18, v144
	v_mul_f32_e32 v144, v17, v147
	v_add_f32_e32 v139, v148, v149
	v_add_f32_e32 v148, v154, v155
	v_add_f32_e32 v137, 0, v137
	v_fmac_f32_e32 v143, v98, v146
	v_fmac_f32_e32 v169, v40, v146
	v_fmac_f32_e32 v171, v56, v146
	v_fmac_f32_e32 v144, v16, v146
	v_add_f32_e32 v146, v150, v151
	v_add_f32_e32 v137, v137, v148
	v_add_f32_e32 v148, v156, v157
	v_add_f32_e32 v139, 0, v139
	v_add_f32_e32 v147, v152, v153
	v_add_f32_e32 v139, v139, v148
	v_add_f32_e32 v148, v158, v159
	v_add_f32_e32 v146, 0, v146
	v_add_f32_e32 v146, v146, v148
	v_add_f32_e32 v148, v160, v161
	v_add_f32_e32 v147, 0, v147
	v_add_f32_e32 v147, v147, v148
	v_add_f32_e32 v148, v162, v163
	v_add_f32_e32 v140, v141, v140
	v_add_f32_e32 v137, v137, v148
	v_add_f32_e32 v148, v164, v165
	v_add_f32_e32 v141, v147, v140
	v_add_f32_e32 v140, v142, v143
	v_add_f32_e32 v139, v139, v148
	v_add_f32_e32 v148, v166, v167
	v_add_f32_e32 v142, v137, v140
	v_add_f32_e32 v137, v168, v169
	v_add_f32_e32 v146, v146, v148
	v_add_f32_e32 v140, v139, v137
	v_add_f32_e32 v137, v170, v171
	v_add_f32_e32 v139, v146, v137
	v_add_f32_e32 v137, v145, v144
	v_add_f32_e32 v137, v141, v137
	ds_read_b128 v[144:147], v118 offset:24576
	ds_read_b128 v[148:151], v118 offset:25600
	s_waitcnt lgkmcnt(1)
	v_mul_f32_e32 v141, v109, v145
	v_mul_f32_e32 v143, v107, v147
	v_mul_f32_e32 v152, v39, v145
	v_mul_f32_e32 v153, v37, v147
	v_mul_f32_e32 v154, v55, v145
	v_mul_f32_e32 v155, v53, v147
	v_mul_f32_e32 v156, v31, v145
	v_mul_f32_e32 v157, v29, v147
	v_fmac_f32_e32 v141, v108, v144
	v_fmac_f32_e32 v143, v106, v146
	v_fmac_f32_e32 v152, v38, v144
	v_fmac_f32_e32 v153, v36, v146
	v_fmac_f32_e32 v154, v54, v144
	v_fmac_f32_e32 v155, v52, v146
	v_fmac_f32_e32 v156, v30, v144
	v_fmac_f32_e32 v157, v28, v146
	ds_read_b128 v[144:147], v118 offset:26624
	s_waitcnt lgkmcnt(1)
	v_mul_f32_e32 v158, v105, v149
	v_mul_f32_e32 v159, v103, v151
	v_mul_f32_e32 v160, v35, v149
	v_mul_f32_e32 v161, v33, v151
	v_mul_f32_e32 v162, v51, v149
	v_mul_f32_e32 v163, v49, v151
	v_mul_f32_e32 v164, v27, v149
	v_mul_f32_e32 v165, v25, v151
	v_fmac_f32_e32 v158, v104, v148
	v_fmac_f32_e32 v159, v102, v150
	v_fmac_f32_e32 v160, v34, v148
	v_fmac_f32_e32 v161, v32, v150
	v_fmac_f32_e32 v162, v50, v148
	v_fmac_f32_e32 v163, v48, v150
	v_fmac_f32_e32 v164, v26, v148
	v_fmac_f32_e32 v165, v24, v150
	ds_read_b128 v[148:151], v118 offset:27648
	s_waitcnt lgkmcnt(1)
	v_mul_f32_e32 v166, v97, v145
	v_mul_f32_e32 v168, v45, v145
	v_mul_f32_e32 v170, v63, v145
	v_mul_f32_e32 v145, v23, v145
	v_fmac_f32_e32 v166, v96, v144
	v_mul_f32_e32 v167, v95, v147
	v_fmac_f32_e32 v168, v44, v144
	v_mul_f32_e32 v169, v43, v147
	v_fmac_f32_e32 v170, v62, v144
	v_mul_f32_e32 v171, v59, v147
	v_fmac_f32_e32 v145, v22, v144
	v_mul_f32_e32 v144, v21, v147
	v_fmac_f32_e32 v167, v94, v146
	v_fmac_f32_e32 v169, v42, v146
	v_fmac_f32_e32 v171, v58, v146
	v_fmac_f32_e32 v144, v20, v146
	s_waitcnt lgkmcnt(0)
; #define LAS __attribute__((address_space(3)))
; __device__ __forceinline__ void phase_prologue(const Params& P, LAS unsigned char* lds) {
;     ...
;         for (int r = 0; r < 16; ++r) {
;             float sacc[RP];
; #pragma unroll
;             for (int q = 0; q < RP; ++q) sacc[q] = 0.f;
; #pragma unroll
;             for (int j = 0; j < 4; ++j) { const f32x4 wv = *(const LAS f32x4*)(Wl + r * 1024 + 4 * lane + 256 * j);
; #pragma unroll
;                 for (int q = 0; q < RP; ++q) sacc[q] += (v[q][j][0] * wv[0] + v[q][j][1] * wv[1]) + (v[q][j][2] * wv[2] + v[q][j][3] * wv[3]); }
;             asm volatile("" : "+v"(sacc[0]), "+v"(sacc[1]), "+v"(sacc[2]), "+v"(sacc[3]) :: "memory");
; #pragma unroll
;             for (int q = 0; q < RP; ++q) a[q][r] = sacc[q];
;         }
	v_mul_f32_e32 v146, v101, v149
	v_mul_f32_e32 v172, v47, v149
	v_mul_f32_e32 v174, v61, v149
	v_mul_f32_e32 v149, v19, v149
	v_add_f32_e32 v141, v141, v143
	v_fmac_f32_e32 v146, v100, v148
	v_mul_f32_e32 v147, v99, v151
	v_fmac_f32_e32 v172, v46, v148
	v_mul_f32_e32 v173, v41, v151
	v_fmac_f32_e32 v174, v60, v148
	v_mul_f32_e32 v175, v57, v151
	v_fmac_f32_e32 v149, v18, v148
	v_mul_f32_e32 v148, v17, v151
	v_add_f32_e32 v143, v152, v153
	v_add_f32_e32 v152, v158, v159
	v_add_f32_e32 v141, 0, v141
	v_fmac_f32_e32 v147, v98, v150
	v_fmac_f32_e32 v173, v40, v150
	v_fmac_f32_e32 v175, v56, v150
	v_fmac_f32_e32 v148, v16, v150
	v_add_f32_e32 v150, v154, v155
	v_add_f32_e32 v141, v141, v152
	v_add_f32_e32 v152, v160, v161
	v_add_f32_e32 v143, 0, v143
	v_add_f32_e32 v151, v156, v157
	v_add_f32_e32 v143, v143, v152
	v_add_f32_e32 v152, v162, v163
	v_add_f32_e32 v150, 0, v150
	v_add_f32_e32 v150, v150, v152
	v_add_f32_e32 v152, v164, v165
	v_add_f32_e32 v151, 0, v151
	v_add_f32_e32 v151, v151, v152
	v_add_f32_e32 v152, v166, v167
	v_add_f32_e32 v144, v145, v144
	v_add_f32_e32 v141, v141, v152
	v_add_f32_e32 v152, v168, v169
	v_add_f32_e32 v145, v151, v144
	v_add_f32_e32 v144, v146, v147
	v_add_f32_e32 v143, v143, v152
	v_add_f32_e32 v152, v170, v171
	v_add_f32_e32 v146, v141, v144
	v_add_f32_e32 v141, v172, v173
	v_add_f32_e32 v150, v150, v152
	v_add_f32_e32 v144, v143, v141
	v_add_f32_e32 v141, v174, v175
	v_add_f32_e32 v143, v150, v141
	v_add_f32_e32 v141, v149, v148
	v_add_f32_e32 v141, v145, v141
	ds_read_b128 v[148:151], v118 offset:28672
	ds_read_b128 v[152:155], v118 offset:29696
	s_waitcnt lgkmcnt(1)
	v_mul_f32_e32 v145, v109, v149
	v_mul_f32_e32 v147, v107, v151
	v_mul_f32_e32 v156, v39, v149
	v_mul_f32_e32 v157, v37, v151
	v_mul_f32_e32 v158, v55, v149
	v_mul_f32_e32 v159, v53, v151
	v_mul_f32_e32 v160, v31, v149
	v_mul_f32_e32 v161, v29, v151
	v_fmac_f32_e32 v145, v108, v148
	v_fmac_f32_e32 v147, v106, v150
	v_fmac_f32_e32 v156, v38, v148
	v_fmac_f32_e32 v157, v36, v150
	v_fmac_f32_e32 v158, v54, v148
	v_fmac_f32_e32 v159, v52, v150
	v_fmac_f32_e32 v160, v30, v148
	v_fmac_f32_e32 v161, v28, v150
	ds_read_b128 v[148:151], v118 offset:30720
	s_waitcnt lgkmcnt(1)
	v_mul_f32_e32 v162, v105, v153
	v_mul_f32_e32 v163, v103, v155
	v_mul_f32_e32 v164, v35, v153
	v_mul_f32_e32 v165, v33, v155
	v_mul_f32_e32 v166, v51, v153
	v_mul_f32_e32 v167, v49, v155
	v_mul_f32_e32 v168, v27, v153
	v_mul_f32_e32 v169, v25, v155
	v_fmac_f32_e32 v162, v104, v152
	v_fmac_f32_e32 v163, v102, v154
	v_fmac_f32_e32 v164, v34, v152
	v_fmac_f32_e32 v165, v32, v154
	v_fmac_f32_e32 v166, v50, v152
	v_fmac_f32_e32 v167, v48, v154
	v_fmac_f32_e32 v168, v26, v152
	v_fmac_f32_e32 v169, v24, v154
	ds_read_b128 v[152:155], v118 offset:31744
	s_waitcnt lgkmcnt(1)
	v_mul_f32_e32 v170, v97, v149
	v_mul_f32_e32 v172, v45, v149
	v_mul_f32_e32 v174, v63, v149
	v_mul_f32_e32 v149, v23, v149
	v_fmac_f32_e32 v170, v96, v148
	v_mul_f32_e32 v171, v95, v151
	v_fmac_f32_e32 v172, v44, v148
	v_mul_f32_e32 v173, v43, v151
	v_fmac_f32_e32 v174, v62, v148
	v_mul_f32_e32 v175, v59, v151
	v_fmac_f32_e32 v149, v22, v148
	v_mul_f32_e32 v148, v21, v151
	v_fmac_f32_e32 v171, v94, v150
	v_fmac_f32_e32 v173, v42, v150
	v_fmac_f32_e32 v175, v58, v150
	v_fmac_f32_e32 v148, v20, v150
	s_waitcnt lgkmcnt(0)
	v_mul_f32_e32 v150, v101, v153
	v_mul_f32_e32 v176, v47, v153
	v_mul_f32_e32 v178, v61, v153
	v_mul_f32_e32 v153, v19, v153
	v_add_f32_e32 v145, v145, v147
	v_fmac_f32_e32 v150, v100, v152
	v_mul_f32_e32 v151, v99, v155
	v_fmac_f32_e32 v176, v46, v152
	v_mul_f32_e32 v177, v41, v155
	v_fmac_f32_e32 v178, v60, v152
	v_mul_f32_e32 v179, v57, v155
	v_fmac_f32_e32 v153, v18, v152
	v_mul_f32_e32 v152, v17, v155
	v_add_f32_e32 v147, v156, v157
	v_add_f32_e32 v156, v162, v163
	v_add_f32_e32 v145, 0, v145
	v_fmac_f32_e32 v151, v98, v154
	v_fmac_f32_e32 v177, v40, v154
	v_fmac_f32_e32 v179, v56, v154
	v_fmac_f32_e32 v152, v16, v154
	v_add_f32_e32 v154, v158, v159
	v_add_f32_e32 v145, v145, v156
	v_add_f32_e32 v156, v164, v165
	v_add_f32_e32 v147, 0, v147
	v_add_f32_e32 v155, v160, v161
	v_add_f32_e32 v147, v147, v156
	v_add_f32_e32 v156, v166, v167
	v_add_f32_e32 v154, 0, v154
	v_add_f32_e32 v154, v154, v156
	v_add_f32_e32 v156, v168, v169
	v_add_f32_e32 v155, 0, v155
	v_add_f32_e32 v155, v155, v156
	v_add_f32_e32 v156, v170, v171
	v_add_f32_e32 v148, v149, v148
	v_add_f32_e32 v145, v145, v156
	v_add_f32_e32 v156, v172, v173
	v_add_f32_e32 v155, v155, v148
	v_add_f32_e32 v148, v150, v151
	v_add_f32_e32 v147, v147, v156
	v_add_f32_e32 v156, v174, v175
	v_add_f32_e32 v149, v145, v148
	v_add_f32_e32 v145, v176, v177
	v_add_f32_e32 v154, v154, v156
	v_add_f32_e32 v148, v147, v145
	v_add_f32_e32 v145, v178, v179
	v_add_f32_e32 v147, v154, v145
	v_add_f32_e32 v145, v153, v152
	v_add_f32_e32 v145, v155, v145
	ds_read_b128 v[150:153], v118 offset:32768
	ds_read_b128 v[154:157], v118 offset:33792
	s_waitcnt lgkmcnt(1)
	v_mul_f32_e32 v158, v109, v151
	v_mul_f32_e32 v159, v107, v153
	v_mul_f32_e32 v160, v39, v151
	v_mul_f32_e32 v161, v37, v153
	v_mul_f32_e32 v162, v55, v151
	v_mul_f32_e32 v163, v53, v153
	v_mul_f32_e32 v164, v31, v151
	v_mul_f32_e32 v165, v29, v153
	v_fmac_f32_e32 v158, v108, v150
	v_fmac_f32_e32 v159, v106, v152
	v_fmac_f32_e32 v160, v38, v150
	v_fmac_f32_e32 v161, v36, v152
	v_fmac_f32_e32 v162, v54, v150
	v_fmac_f32_e32 v163, v52, v152
	v_fmac_f32_e32 v164, v30, v150
	v_fmac_f32_e32 v165, v28, v152
	ds_read_b128 v[150:153], v118 offset:34816
	s_waitcnt lgkmcnt(1)
; #define LAS __attribute__((address_space(3)))
; __device__ __forceinline__ void phase_prologue(const Params& P, LAS unsigned char* lds) {
;     ...
;         for (int r = 0; r < 16; ++r) {
;             float sacc[RP];
; #pragma unroll
;             for (int q = 0; q < RP; ++q) sacc[q] = 0.f;
; #pragma unroll
;             for (int j = 0; j < 4; ++j) { const f32x4 wv = *(const LAS f32x4*)(Wl + r * 1024 + 4 * lane + 256 * j);
; #pragma unroll
;                 for (int q = 0; q < RP; ++q) sacc[q] += (v[q][j][0] * wv[0] + v[q][j][1] * wv[1]) + (v[q][j][2] * wv[2] + v[q][j][3] * wv[3]); }
;             asm volatile("" : "+v"(sacc[0]), "+v"(sacc[1]), "+v"(sacc[2]), "+v"(sacc[3]) :: "memory");
; #pragma unroll
;             for (int q = 0; q < RP; ++q) a[q][r] = sacc[q];
;         }
	v_mul_f32_e32 v166, v105, v155
	v_mul_f32_e32 v167, v103, v157
	v_mul_f32_e32 v168, v35, v155
	v_mul_f32_e32 v169, v33, v157
	v_mul_f32_e32 v170, v51, v155
	v_mul_f32_e32 v171, v49, v157
	v_mul_f32_e32 v172, v27, v155
	v_mul_f32_e32 v173, v25, v157
	v_fmac_f32_e32 v166, v104, v154
	v_fmac_f32_e32 v167, v102, v156
	v_fmac_f32_e32 v168, v34, v154
	v_fmac_f32_e32 v169, v32, v156
	v_fmac_f32_e32 v170, v50, v154
	v_fmac_f32_e32 v171, v48, v156
	v_fmac_f32_e32 v172, v26, v154
	v_fmac_f32_e32 v173, v24, v156
	ds_read_b128 v[154:157], v118 offset:35840
	s_waitcnt lgkmcnt(1)
	v_mul_f32_e32 v174, v97, v151
	v_mul_f32_e32 v176, v45, v151
	v_mul_f32_e32 v178, v63, v151
	v_mul_f32_e32 v151, v23, v151
	v_fmac_f32_e32 v174, v96, v150
	v_mul_f32_e32 v175, v95, v153
	v_fmac_f32_e32 v176, v44, v150
	v_mul_f32_e32 v177, v43, v153
	v_fmac_f32_e32 v178, v62, v150
	v_mul_f32_e32 v179, v59, v153
	v_fmac_f32_e32 v151, v22, v150
	v_mul_f32_e32 v150, v21, v153
	v_fmac_f32_e32 v175, v94, v152
	v_fmac_f32_e32 v177, v42, v152
	v_fmac_f32_e32 v179, v58, v152
	v_fmac_f32_e32 v150, v20, v152
	s_waitcnt lgkmcnt(0)
	v_mul_f32_e32 v152, v101, v155
	v_mul_f32_e32 v180, v47, v155
	v_mul_f32_e32 v182, v61, v155
	v_mul_f32_e32 v155, v19, v155
	v_fmac_f32_e32 v152, v100, v154
	v_mul_f32_e32 v153, v99, v157
	v_fmac_f32_e32 v180, v46, v154
	v_mul_f32_e32 v181, v41, v157
	v_fmac_f32_e32 v182, v60, v154
	v_mul_f32_e32 v183, v57, v157
	v_fmac_f32_e32 v155, v18, v154
	v_mul_f32_e32 v157, v17, v157
	v_add_f32_e32 v154, v158, v159
	v_fmac_f32_e32 v153, v98, v156
	v_fmac_f32_e32 v181, v40, v156
	v_fmac_f32_e32 v183, v56, v156
	v_fmac_f32_e32 v157, v16, v156
	v_add_f32_e32 v156, v160, v161
	v_add_f32_e32 v160, v166, v167
	v_add_f32_e32 v154, 0, v154
	v_add_f32_e32 v158, v162, v163
	v_add_f32_e32 v154, v154, v160
	v_add_f32_e32 v160, v168, v169
	v_add_f32_e32 v156, 0, v156
	v_add_f32_e32 v159, v164, v165
	v_add_f32_e32 v156, v156, v160
	v_add_f32_e32 v160, v170, v171
	v_add_f32_e32 v158, 0, v158
	v_add_f32_e32 v158, v158, v160
	v_add_f32_e32 v160, v172, v173
	v_add_f32_e32 v159, 0, v159
	v_add_f32_e32 v159, v159, v160
	v_add_f32_e32 v160, v174, v175
	v_add_f32_e32 v154, v154, v160
	v_add_f32_e32 v160, v176, v177
	v_add_f32_e32 v150, v151, v150
	v_add_f32_e32 v151, v152, v153
	v_add_f32_e32 v156, v156, v160
	v_add_f32_e32 v160, v178, v179
	v_add_f32_e32 v154, v154, v151
	v_add_f32_e32 v151, v180, v181
	v_add_f32_e32 v158, v158, v160
	v_add_f32_e32 v150, v159, v150
	v_add_f32_e32 v152, v156, v151
	v_add_f32_e32 v151, v182, v183
	v_add_f32_e32 v153, v155, v157
	v_add_f32_e32 v151, v158, v151
	v_add_f32_e32 v150, v150, v153
	ds_read_b128 v[156:159], v118 offset:36864
	ds_read_b128 v[160:163], v118 offset:37888
	s_waitcnt lgkmcnt(1)
	v_mul_f32_e32 v153, v109, v157
	v_mul_f32_e32 v155, v107, v159
	v_mul_f32_e32 v164, v39, v157
	v_mul_f32_e32 v165, v37, v159
	v_mul_f32_e32 v166, v55, v157
	v_mul_f32_e32 v167, v53, v159
	v_mul_f32_e32 v168, v31, v157
	v_mul_f32_e32 v169, v29, v159
	v_fmac_f32_e32 v153, v108, v156
	v_fmac_f32_e32 v155, v106, v158
	v_fmac_f32_e32 v164, v38, v156
	v_fmac_f32_e32 v165, v36, v158
	v_fmac_f32_e32 v166, v54, v156
	v_fmac_f32_e32 v167, v52, v158
	v_fmac_f32_e32 v168, v30, v156
	v_fmac_f32_e32 v169, v28, v158
	ds_read_b128 v[156:159], v118 offset:38912
	s_waitcnt lgkmcnt(1)
	v_mul_f32_e32 v170, v105, v161
	v_mul_f32_e32 v171, v103, v163
	v_mul_f32_e32 v172, v35, v161
	v_mul_f32_e32 v173, v33, v163
	v_mul_f32_e32 v174, v51, v161
	v_mul_f32_e32 v175, v49, v163
	v_mul_f32_e32 v176, v27, v161
	v_mul_f32_e32 v177, v25, v163
	v_fmac_f32_e32 v170, v104, v160
	v_fmac_f32_e32 v171, v102, v162
	v_fmac_f32_e32 v172, v34, v160
	v_fmac_f32_e32 v173, v32, v162
	v_fmac_f32_e32 v174, v50, v160
	v_fmac_f32_e32 v175, v48, v162
	v_fmac_f32_e32 v176, v26, v160
	v_fmac_f32_e32 v177, v24, v162
	ds_read_b128 v[160:163], v118 offset:39936
	s_waitcnt lgkmcnt(1)
	v_mul_f32_e32 v178, v97, v157
	v_mul_f32_e32 v180, v45, v157
	v_mul_f32_e32 v182, v63, v157
	v_mul_f32_e32 v157, v23, v157
	v_fmac_f32_e32 v178, v96, v156
	v_mul_f32_e32 v179, v95, v159
	v_fmac_f32_e32 v180, v44, v156
	v_mul_f32_e32 v181, v43, v159
	v_fmac_f32_e32 v182, v62, v156
	v_mul_f32_e32 v183, v59, v159
	v_fmac_f32_e32 v157, v22, v156
	v_mul_f32_e32 v156, v21, v159
	v_fmac_f32_e32 v179, v94, v158
	v_fmac_f32_e32 v181, v42, v158
	v_fmac_f32_e32 v183, v58, v158
	v_fmac_f32_e32 v156, v20, v158
	s_waitcnt lgkmcnt(0)
	v_mul_f32_e32 v158, v101, v161
	v_mul_f32_e32 v184, v47, v161
	v_mul_f32_e32 v186, v61, v161
	v_mul_f32_e32 v161, v19, v161
	v_add_f32_e32 v153, v153, v155
	v_fmac_f32_e32 v158, v100, v160
	v_mul_f32_e32 v159, v99, v163
	v_fmac_f32_e32 v184, v46, v160
	v_mul_f32_e32 v185, v41, v163
	v_fmac_f32_e32 v186, v60, v160
	v_mul_f32_e32 v187, v57, v163
	v_fmac_f32_e32 v161, v18, v160
	v_mul_f32_e32 v160, v17, v163
	v_add_f32_e32 v155, v164, v165
	v_add_f32_e32 v164, v170, v171
	v_add_f32_e32 v153, 0, v153
	v_fmac_f32_e32 v159, v98, v162
	v_fmac_f32_e32 v185, v40, v162
	v_fmac_f32_e32 v187, v56, v162
	v_fmac_f32_e32 v160, v16, v162
	v_add_f32_e32 v162, v166, v167
	v_add_f32_e32 v153, v153, v164
	v_add_f32_e32 v164, v172, v173
	v_add_f32_e32 v155, 0, v155
	v_add_f32_e32 v163, v168, v169
	v_add_f32_e32 v155, v155, v164
	v_add_f32_e32 v164, v174, v175
	v_add_f32_e32 v162, 0, v162
	v_add_f32_e32 v162, v162, v164
	v_add_f32_e32 v164, v176, v177
	v_add_f32_e32 v163, 0, v163
	v_add_f32_e32 v163, v163, v164
	v_add_f32_e32 v164, v178, v179
	v_add_f32_e32 v156, v157, v156
	v_add_f32_e32 v153, v153, v164
	v_add_f32_e32 v164, v180, v181
	v_add_f32_e32 v157, v163, v156
	v_add_f32_e32 v156, v158, v159
	v_add_f32_e32 v155, v155, v164
	v_add_f32_e32 v164, v182, v183
	v_add_f32_e32 v158, v153, v156
	v_add_f32_e32 v153, v184, v185
	v_add_f32_e32 v162, v162, v164
	v_add_f32_e32 v156, v155, v153
	v_add_f32_e32 v153, v186, v187
	v_add_f32_e32 v155, v162, v153
	v_add_f32_e32 v153, v161, v160
	v_add_f32_e32 v153, v157, v153
	ds_read_b128 v[160:163], v118 offset:40960
	ds_read_b128 v[164:167], v118 offset:41984
	s_waitcnt lgkmcnt(1)
; #define LAS __attribute__((address_space(3)))
; __device__ __forceinline__ void phase_prologue(const Params& P, LAS unsigned char* lds) {
;     ...
;         for (int r = 0; r < 16; ++r) {
;             float sacc[RP];
; #pragma unroll
;             for (int q = 0; q < RP; ++q) sacc[q] = 0.f;
; #pragma unroll
;             for (int j = 0; j < 4; ++j) { const f32x4 wv = *(const LAS f32x4*)(Wl + r * 1024 + 4 * lane + 256 * j);
; #pragma unroll
;                 for (int q = 0; q < RP; ++q) sacc[q] += (v[q][j][0] * wv[0] + v[q][j][1] * wv[1]) + (v[q][j][2] * wv[2] + v[q][j][3] * wv[3]); }
;             asm volatile("" : "+v"(sacc[0]), "+v"(sacc[1]), "+v"(sacc[2]), "+v"(sacc[3]) :: "memory");
; #pragma unroll
;             for (int q = 0; q < RP; ++q) a[q][r] = sacc[q];
;         }
	v_mul_f32_e32 v157, v109, v161
	v_mul_f32_e32 v159, v107, v163
	v_mul_f32_e32 v168, v39, v161
	v_mul_f32_e32 v169, v37, v163
	v_mul_f32_e32 v170, v55, v161
	v_mul_f32_e32 v171, v53, v163
	v_mul_f32_e32 v172, v31, v161
	v_mul_f32_e32 v173, v29, v163
	v_fmac_f32_e32 v157, v108, v160
	v_fmac_f32_e32 v159, v106, v162
	v_fmac_f32_e32 v168, v38, v160
	v_fmac_f32_e32 v169, v36, v162
	v_fmac_f32_e32 v170, v54, v160
	v_fmac_f32_e32 v171, v52, v162
	v_fmac_f32_e32 v172, v30, v160
	v_fmac_f32_e32 v173, v28, v162
	ds_read_b128 v[160:163], v118 offset:43008
	s_waitcnt lgkmcnt(1)
	v_mul_f32_e32 v174, v105, v165
	v_mul_f32_e32 v175, v103, v167
	v_mul_f32_e32 v176, v35, v165
	v_mul_f32_e32 v177, v33, v167
	v_mul_f32_e32 v178, v51, v165
	v_mul_f32_e32 v179, v49, v167
	v_mul_f32_e32 v180, v27, v165
	v_mul_f32_e32 v181, v25, v167
	v_fmac_f32_e32 v174, v104, v164
	v_fmac_f32_e32 v175, v102, v166
	v_fmac_f32_e32 v176, v34, v164
	v_fmac_f32_e32 v177, v32, v166
	v_fmac_f32_e32 v178, v50, v164
	v_fmac_f32_e32 v179, v48, v166
	v_fmac_f32_e32 v180, v26, v164
	v_fmac_f32_e32 v181, v24, v166
	ds_read_b128 v[164:167], v118 offset:44032
	s_waitcnt lgkmcnt(1)
	v_mul_f32_e32 v182, v97, v161
	v_mul_f32_e32 v184, v45, v161
	v_mul_f32_e32 v186, v63, v161
	v_mul_f32_e32 v161, v23, v161
	v_fmac_f32_e32 v182, v96, v160
	v_mul_f32_e32 v183, v95, v163
	v_fmac_f32_e32 v184, v44, v160
	v_mul_f32_e32 v185, v43, v163
	v_fmac_f32_e32 v186, v62, v160
	v_mul_f32_e32 v187, v59, v163
	v_fmac_f32_e32 v161, v22, v160
	v_mul_f32_e32 v160, v21, v163
	v_fmac_f32_e32 v183, v94, v162
	v_fmac_f32_e32 v185, v42, v162
	v_fmac_f32_e32 v187, v58, v162
	v_fmac_f32_e32 v160, v20, v162
	s_waitcnt lgkmcnt(0)
	v_mul_f32_e32 v162, v101, v165
	v_mul_f32_e32 v188, v47, v165
	v_mul_f32_e32 v190, v61, v165
	v_mul_f32_e32 v165, v19, v165
	v_add_f32_e32 v157, v157, v159
	v_fmac_f32_e32 v162, v100, v164
	v_mul_f32_e32 v163, v99, v167
	v_fmac_f32_e32 v188, v46, v164
	v_mul_f32_e32 v189, v41, v167
	v_fmac_f32_e32 v190, v60, v164
	v_mul_f32_e32 v191, v57, v167
	v_fmac_f32_e32 v165, v18, v164
	v_mul_f32_e32 v164, v17, v167
	v_add_f32_e32 v159, v168, v169
	v_add_f32_e32 v168, v174, v175
	v_add_f32_e32 v157, 0, v157
	v_fmac_f32_e32 v163, v98, v166
	v_fmac_f32_e32 v189, v40, v166
	v_fmac_f32_e32 v191, v56, v166
	v_fmac_f32_e32 v164, v16, v166
	v_add_f32_e32 v166, v170, v171
	v_add_f32_e32 v157, v157, v168
	v_add_f32_e32 v168, v176, v177
	v_add_f32_e32 v159, 0, v159
	v_add_f32_e32 v167, v172, v173
	v_add_f32_e32 v159, v159, v168
	v_add_f32_e32 v168, v178, v179
	v_add_f32_e32 v166, 0, v166
	v_add_f32_e32 v166, v166, v168
	v_add_f32_e32 v168, v180, v181
	v_add_f32_e32 v167, 0, v167
	v_add_f32_e32 v167, v167, v168
	v_add_f32_e32 v168, v182, v183
	v_add_f32_e32 v160, v161, v160
	v_add_f32_e32 v157, v157, v168
	v_add_f32_e32 v168, v184, v185
	v_add_f32_e32 v161, v167, v160
	v_add_f32_e32 v160, v162, v163
	v_add_f32_e32 v159, v159, v168
	v_add_f32_e32 v168, v186, v187
	v_add_f32_e32 v162, v157, v160
	v_add_f32_e32 v157, v188, v189
	v_add_f32_e32 v166, v166, v168
	v_add_f32_e32 v160, v159, v157
	v_add_f32_e32 v157, v190, v191
	v_add_f32_e32 v159, v166, v157
	v_add_f32_e32 v157, v165, v164
	v_add_f32_e32 v157, v161, v157
	ds_read_b128 v[164:167], v118 offset:45056
	ds_read_b128 v[168:171], v118 offset:46080
	s_waitcnt lgkmcnt(1)
	v_mul_f32_e32 v161, v109, v165
	v_mul_f32_e32 v163, v107, v167
	v_mul_f32_e32 v172, v39, v165
	v_mul_f32_e32 v173, v37, v167
	v_mul_f32_e32 v174, v55, v165
	v_mul_f32_e32 v175, v53, v167
	v_mul_f32_e32 v176, v31, v165
	v_mul_f32_e32 v177, v29, v167
	v_fmac_f32_e32 v161, v108, v164
	v_fmac_f32_e32 v163, v106, v166
	v_fmac_f32_e32 v172, v38, v164
	v_fmac_f32_e32 v173, v36, v166
	v_fmac_f32_e32 v174, v54, v164
	v_fmac_f32_e32 v175, v52, v166
	v_fmac_f32_e32 v176, v30, v164
	v_fmac_f32_e32 v177, v28, v166
	ds_read_b128 v[164:167], v118 offset:47104
	s_waitcnt lgkmcnt(1)
	v_mul_f32_e32 v178, v105, v169
	v_mul_f32_e32 v179, v103, v171
	v_mul_f32_e32 v180, v35, v169
	v_mul_f32_e32 v181, v33, v171
	v_mul_f32_e32 v182, v51, v169
	v_mul_f32_e32 v183, v49, v171
	v_mul_f32_e32 v184, v27, v169
	v_mul_f32_e32 v185, v25, v171
	v_fmac_f32_e32 v178, v104, v168
	v_fmac_f32_e32 v179, v102, v170
	v_fmac_f32_e32 v180, v34, v168
	v_fmac_f32_e32 v181, v32, v170
	v_fmac_f32_e32 v182, v50, v168
	v_fmac_f32_e32 v183, v48, v170
	v_fmac_f32_e32 v184, v26, v168
	v_fmac_f32_e32 v185, v24, v170
	ds_read_b128 v[168:171], v118 offset:48128
	s_waitcnt lgkmcnt(1)
	v_mul_f32_e32 v186, v97, v165
	v_mul_f32_e32 v188, v45, v165
	v_mul_f32_e32 v190, v63, v165
	v_mul_f32_e32 v165, v23, v165
	v_fmac_f32_e32 v186, v96, v164
	v_mul_f32_e32 v187, v95, v167
	v_fmac_f32_e32 v188, v44, v164
	v_mul_f32_e32 v189, v43, v167
	v_fmac_f32_e32 v190, v62, v164
	v_mul_f32_e32 v191, v59, v167
	v_fmac_f32_e32 v165, v22, v164
	v_mul_f32_e32 v164, v21, v167
	v_fmac_f32_e32 v187, v94, v166
	v_fmac_f32_e32 v189, v42, v166
	v_fmac_f32_e32 v191, v58, v166
	v_fmac_f32_e32 v164, v20, v166
	s_waitcnt lgkmcnt(0)
; #define LAS __attribute__((address_space(3)))
; __device__ __forceinline__ void phase_prologue(const Params& P, LAS unsigned char* lds) {
;     ...
;         for (int r = 0; r < 16; ++r) {
;             float sacc[RP];
; #pragma unroll
;             for (int q = 0; q < RP; ++q) sacc[q] = 0.f;
; #pragma unroll
;             for (int j = 0; j < 4; ++j) { const f32x4 wv = *(const LAS f32x4*)(Wl + r * 1024 + 4 * lane + 256 * j);
; #pragma unroll
;                 for (int q = 0; q < RP; ++q) sacc[q] += (v[q][j][0] * wv[0] + v[q][j][1] * wv[1]) + (v[q][j][2] * wv[2] + v[q][j][3] * wv[3]); }
;             asm volatile("" : "+v"(sacc[0]), "+v"(sacc[1]), "+v"(sacc[2]), "+v"(sacc[3]) :: "memory");
; #pragma unroll
;             for (int q = 0; q < RP; ++q) a[q][r] = sacc[q];
;         }
	v_mul_f32_e32 v166, v101, v169
	v_mul_f32_e32 v192, v47, v169
	v_mul_f32_e32 v196, v61, v169
	v_mul_f32_e32 v169, v19, v169
	v_add_f32_e32 v161, v161, v163
	v_fmac_f32_e32 v166, v100, v168
	v_mul_f32_e32 v167, v99, v171
	v_fmac_f32_e32 v192, v46, v168
	v_mul_f32_e32 v193, v41, v171
	v_fmac_f32_e32 v196, v60, v168
	v_mul_f32_e32 v197, v57, v171
	v_fmac_f32_e32 v169, v18, v168
	v_mul_f32_e32 v168, v17, v171
	v_add_f32_e32 v163, v172, v173
	v_add_f32_e32 v172, v178, v179
	v_add_f32_e32 v161, 0, v161
	v_fmac_f32_e32 v167, v98, v170
	v_fmac_f32_e32 v193, v40, v170
	v_fmac_f32_e32 v197, v56, v170
	v_fmac_f32_e32 v168, v16, v170
	v_add_f32_e32 v170, v174, v175
	v_add_f32_e32 v161, v161, v172
	v_add_f32_e32 v172, v180, v181
	v_add_f32_e32 v163, 0, v163
	v_add_f32_e32 v171, v176, v177
	v_add_f32_e32 v163, v163, v172
	v_add_f32_e32 v172, v182, v183
	v_add_f32_e32 v170, 0, v170
	v_add_f32_e32 v170, v170, v172
	v_add_f32_e32 v172, v184, v185
	v_add_f32_e32 v171, 0, v171
	v_add_f32_e32 v171, v171, v172
	v_add_f32_e32 v172, v186, v187
	v_add_f32_e32 v164, v165, v164
	v_add_f32_e32 v161, v161, v172
	v_add_f32_e32 v172, v188, v189
	v_add_f32_e32 v165, v171, v164
	v_add_f32_e32 v164, v166, v167
	v_add_f32_e32 v163, v163, v172
	v_add_f32_e32 v172, v190, v191
	v_add_f32_e32 v166, v161, v164
	v_add_f32_e32 v161, v192, v193
	v_add_f32_e32 v170, v170, v172
	v_add_f32_e32 v164, v163, v161
	v_add_f32_e32 v161, v196, v197
	v_add_f32_e32 v163, v170, v161
	v_add_f32_e32 v161, v169, v168
	v_add_f32_e32 v161, v165, v161
	ds_read_b128 v[168:171], v118 offset:49152
	ds_read_b128 v[172:175], v118 offset:50176
	s_waitcnt lgkmcnt(1)
	v_mul_f32_e32 v165, v109, v169
	v_mul_f32_e32 v167, v107, v171
	v_mul_f32_e32 v176, v39, v169
	v_mul_f32_e32 v177, v37, v171
	v_mul_f32_e32 v178, v55, v169
	v_mul_f32_e32 v179, v53, v171
	v_mul_f32_e32 v180, v31, v169
	v_mul_f32_e32 v181, v29, v171
	v_fmac_f32_e32 v165, v108, v168
	v_fmac_f32_e32 v167, v106, v170
	v_fmac_f32_e32 v176, v38, v168
	v_fmac_f32_e32 v177, v36, v170
	v_fmac_f32_e32 v178, v54, v168
	v_fmac_f32_e32 v179, v52, v170
	v_fmac_f32_e32 v180, v30, v168
	v_fmac_f32_e32 v181, v28, v170
	ds_read_b128 v[168:171], v118 offset:51200
	s_waitcnt lgkmcnt(1)
	v_mul_f32_e32 v182, v105, v173
	v_mul_f32_e32 v183, v103, v175
	v_mul_f32_e32 v184, v35, v173
	v_mul_f32_e32 v185, v33, v175
	v_mul_f32_e32 v186, v51, v173
	v_mul_f32_e32 v187, v49, v175
	v_mul_f32_e32 v188, v27, v173
	v_mul_f32_e32 v189, v25, v175
	v_fmac_f32_e32 v182, v104, v172
	v_fmac_f32_e32 v183, v102, v174
	v_fmac_f32_e32 v184, v34, v172
	v_fmac_f32_e32 v185, v32, v174
	v_fmac_f32_e32 v186, v50, v172
	v_fmac_f32_e32 v187, v48, v174
	v_fmac_f32_e32 v188, v26, v172
	v_fmac_f32_e32 v189, v24, v174
	ds_read_b128 v[172:175], v118 offset:52224
	s_waitcnt lgkmcnt(1)
	v_mul_f32_e32 v190, v97, v169
	v_mul_f32_e32 v192, v45, v169
	v_mul_f32_e32 v196, v63, v169
	v_mul_f32_e32 v169, v23, v169
	v_fmac_f32_e32 v190, v96, v168
	v_mul_f32_e32 v191, v95, v171
	v_fmac_f32_e32 v192, v44, v168
	v_mul_f32_e32 v193, v43, v171
	v_fmac_f32_e32 v196, v62, v168
	v_mul_f32_e32 v197, v59, v171
	v_fmac_f32_e32 v169, v22, v168
	v_mul_f32_e32 v168, v21, v171
	v_fmac_f32_e32 v191, v94, v170
	v_fmac_f32_e32 v193, v42, v170
	v_fmac_f32_e32 v197, v58, v170
	v_fmac_f32_e32 v168, v20, v170
	s_waitcnt lgkmcnt(0)
	v_mul_f32_e32 v170, v101, v173
	v_mul_f32_e32 v198, v47, v173
	v_mul_f32_e32 v200, v61, v173
	v_mul_f32_e32 v173, v19, v173
	v_add_f32_e32 v165, v165, v167
	v_fmac_f32_e32 v170, v100, v172
	v_mul_f32_e32 v171, v99, v175
	v_fmac_f32_e32 v198, v46, v172
	v_mul_f32_e32 v199, v41, v175
	v_fmac_f32_e32 v200, v60, v172
	v_mul_f32_e32 v201, v57, v175
	v_fmac_f32_e32 v173, v18, v172
	v_mul_f32_e32 v172, v17, v175
	v_add_f32_e32 v167, v176, v177
	v_add_f32_e32 v176, v182, v183
	v_add_f32_e32 v165, 0, v165
	v_fmac_f32_e32 v171, v98, v174
	v_fmac_f32_e32 v199, v40, v174
	v_fmac_f32_e32 v201, v56, v174
	v_fmac_f32_e32 v172, v16, v174
	v_add_f32_e32 v174, v178, v179
	v_add_f32_e32 v165, v165, v176
	v_add_f32_e32 v176, v184, v185
	v_add_f32_e32 v167, 0, v167
	v_add_f32_e32 v175, v180, v181
	v_add_f32_e32 v167, v167, v176
	v_add_f32_e32 v176, v186, v187
	v_add_f32_e32 v174, 0, v174
	v_add_f32_e32 v174, v174, v176
	v_add_f32_e32 v176, v188, v189
	v_add_f32_e32 v175, 0, v175
	v_add_f32_e32 v175, v175, v176
	v_add_f32_e32 v176, v190, v191
	v_add_f32_e32 v168, v169, v168
	v_add_f32_e32 v165, v165, v176
	v_add_f32_e32 v176, v192, v193
	v_add_f32_e32 v169, v175, v168
	v_add_f32_e32 v168, v170, v171
	v_add_f32_e32 v167, v167, v176
	v_add_f32_e32 v176, v196, v197
	v_add_f32_e32 v170, v165, v168
	v_add_f32_e32 v165, v198, v199
	v_add_f32_e32 v174, v174, v176
	v_add_f32_e32 v168, v167, v165
	v_add_f32_e32 v165, v200, v201
	v_add_f32_e32 v167, v174, v165
	v_add_f32_e32 v165, v173, v172
	v_add_f32_e32 v165, v169, v165
	ds_read_b128 v[172:175], v118 offset:53248
	ds_read_b128 v[176:179], v118 offset:54272
	s_waitcnt lgkmcnt(1)
	v_mul_f32_e32 v169, v109, v173
	v_mul_f32_e32 v171, v107, v175
	v_mul_f32_e32 v180, v39, v173
	v_mul_f32_e32 v181, v37, v175
	v_mul_f32_e32 v182, v55, v173
	v_mul_f32_e32 v183, v53, v175
	v_mul_f32_e32 v184, v31, v173
	v_mul_f32_e32 v185, v29, v175
	v_fmac_f32_e32 v169, v108, v172
	v_fmac_f32_e32 v171, v106, v174
	v_fmac_f32_e32 v180, v38, v172
	v_fmac_f32_e32 v181, v36, v174
	v_fmac_f32_e32 v182, v54, v172
	v_fmac_f32_e32 v183, v52, v174
	v_fmac_f32_e32 v184, v30, v172
	v_fmac_f32_e32 v185, v28, v174
	ds_read_b128 v[172:175], v118 offset:55296
	s_waitcnt lgkmcnt(1)
; #define LAS __attribute__((address_space(3)))
; __device__ __forceinline__ void phase_prologue(const Params& P, LAS unsigned char* lds) {
;     ...
;         for (int r = 0; r < 16; ++r) {
;             float sacc[RP];
; #pragma unroll
;             for (int q = 0; q < RP; ++q) sacc[q] = 0.f;
; #pragma unroll
;             for (int j = 0; j < 4; ++j) { const f32x4 wv = *(const LAS f32x4*)(Wl + r * 1024 + 4 * lane + 256 * j);
; #pragma unroll
;                 for (int q = 0; q < RP; ++q) sacc[q] += (v[q][j][0] * wv[0] + v[q][j][1] * wv[1]) + (v[q][j][2] * wv[2] + v[q][j][3] * wv[3]); }
;             asm volatile("" : "+v"(sacc[0]), "+v"(sacc[1]), "+v"(sacc[2]), "+v"(sacc[3]) :: "memory");
; #pragma unroll
;             for (int q = 0; q < RP; ++q) a[q][r] = sacc[q];
;         }
	v_mul_f32_e32 v186, v105, v177
	v_mul_f32_e32 v187, v103, v179
	v_mul_f32_e32 v188, v35, v177
	v_mul_f32_e32 v189, v33, v179
	v_mul_f32_e32 v190, v51, v177
	v_mul_f32_e32 v191, v49, v179
	v_mul_f32_e32 v192, v27, v177
	v_mul_f32_e32 v193, v25, v179
	v_fmac_f32_e32 v186, v104, v176
	v_fmac_f32_e32 v187, v102, v178
	v_fmac_f32_e32 v188, v34, v176
	v_fmac_f32_e32 v189, v32, v178
	v_fmac_f32_e32 v190, v50, v176
	v_fmac_f32_e32 v191, v48, v178
	v_fmac_f32_e32 v192, v26, v176
	v_fmac_f32_e32 v193, v24, v178
	ds_read_b128 v[176:179], v118 offset:56320
	s_waitcnt lgkmcnt(1)
	v_mul_f32_e32 v196, v97, v173
	v_mul_f32_e32 v198, v45, v173
	v_mul_f32_e32 v200, v63, v173
	v_mul_f32_e32 v173, v23, v173
	v_fmac_f32_e32 v196, v96, v172
	v_mul_f32_e32 v197, v95, v175
	v_fmac_f32_e32 v198, v44, v172
	v_mul_f32_e32 v199, v43, v175
	v_fmac_f32_e32 v200, v62, v172
	v_mul_f32_e32 v201, v59, v175
	v_fmac_f32_e32 v173, v22, v172
	v_mul_f32_e32 v172, v21, v175
	v_fmac_f32_e32 v197, v94, v174
	v_fmac_f32_e32 v199, v42, v174
	v_fmac_f32_e32 v201, v58, v174
	v_fmac_f32_e32 v172, v20, v174
	s_waitcnt lgkmcnt(0)
	v_mul_f32_e32 v174, v101, v177
	v_mul_f32_e32 v202, v47, v177
	v_mul_f32_e32 v204, v61, v177
	v_mul_f32_e32 v177, v19, v177
	v_add_f32_e32 v169, v169, v171
	v_fmac_f32_e32 v174, v100, v176
	v_mul_f32_e32 v175, v99, v179
	v_fmac_f32_e32 v202, v46, v176
	v_mul_f32_e32 v203, v41, v179
	v_fmac_f32_e32 v204, v60, v176
	v_mul_f32_e32 v205, v57, v179
	v_fmac_f32_e32 v177, v18, v176
	v_mul_f32_e32 v176, v17, v179
	v_add_f32_e32 v171, v180, v181
	v_add_f32_e32 v180, v186, v187
	v_add_f32_e32 v169, 0, v169
	v_fmac_f32_e32 v175, v98, v178
	v_fmac_f32_e32 v203, v40, v178
	v_fmac_f32_e32 v205, v56, v178
	v_fmac_f32_e32 v176, v16, v178
	v_add_f32_e32 v178, v182, v183
	v_add_f32_e32 v169, v169, v180
	v_add_f32_e32 v180, v188, v189
	v_add_f32_e32 v171, 0, v171
	v_add_f32_e32 v179, v184, v185
	v_add_f32_e32 v171, v171, v180
	v_add_f32_e32 v180, v190, v191
	v_add_f32_e32 v178, 0, v178
	v_add_f32_e32 v178, v178, v180
	v_add_f32_e32 v180, v192, v193
	v_add_f32_e32 v179, 0, v179
	v_add_f32_e32 v179, v179, v180
	v_add_f32_e32 v180, v196, v197
	v_add_f32_e32 v172, v173, v172
	v_add_f32_e32 v169, v169, v180
	v_add_f32_e32 v180, v198, v199
	v_add_f32_e32 v173, v179, v172
	v_add_f32_e32 v172, v174, v175
	v_add_f32_e32 v171, v171, v180
	v_add_f32_e32 v180, v200, v201
	v_add_f32_e32 v174, v169, v172
	v_add_f32_e32 v169, v202, v203
	v_add_f32_e32 v178, v178, v180
	v_add_f32_e32 v172, v171, v169
	v_add_f32_e32 v169, v204, v205
	v_add_f32_e32 v171, v178, v169
	v_add_f32_e32 v169, v177, v176
	v_add_f32_e32 v169, v173, v169
	ds_read_b128 v[176:179], v118 offset:57344
	ds_read_b128 v[180:183], v118 offset:58368
	s_waitcnt lgkmcnt(1)
	v_mul_f32_e32 v173, v109, v177
	v_mul_f32_e32 v175, v107, v179
	v_mul_f32_e32 v184, v39, v177
	v_mul_f32_e32 v185, v37, v179
	v_mul_f32_e32 v186, v55, v177
	v_mul_f32_e32 v187, v53, v179
	v_mul_f32_e32 v188, v31, v177
	v_mul_f32_e32 v189, v29, v179
	v_fmac_f32_e32 v173, v108, v176
	v_fmac_f32_e32 v175, v106, v178
	v_fmac_f32_e32 v184, v38, v176
	v_fmac_f32_e32 v185, v36, v178
	v_fmac_f32_e32 v186, v54, v176
	v_fmac_f32_e32 v187, v52, v178
	v_fmac_f32_e32 v188, v30, v176
	v_fmac_f32_e32 v189, v28, v178
	ds_read_b128 v[176:179], v118 offset:59392
	s_waitcnt lgkmcnt(1)
	v_mul_f32_e32 v190, v105, v181
	v_mul_f32_e32 v191, v103, v183
	v_mul_f32_e32 v192, v35, v181
	v_mul_f32_e32 v193, v33, v183
	v_mul_f32_e32 v196, v51, v181
	v_mul_f32_e32 v197, v49, v183
	v_mul_f32_e32 v198, v27, v181
	v_mul_f32_e32 v199, v25, v183
	v_fmac_f32_e32 v190, v104, v180
	v_fmac_f32_e32 v191, v102, v182
	v_fmac_f32_e32 v192, v34, v180
	v_fmac_f32_e32 v193, v32, v182
	v_fmac_f32_e32 v196, v50, v180
	v_fmac_f32_e32 v197, v48, v182
	v_fmac_f32_e32 v198, v26, v180
	v_fmac_f32_e32 v199, v24, v182
	ds_read_b128 v[180:183], v118 offset:60416
	s_waitcnt lgkmcnt(1)
	v_mul_f32_e32 v200, v97, v177
	v_mul_f32_e32 v202, v45, v177
	v_mul_f32_e32 v204, v63, v177
	v_mul_f32_e32 v177, v23, v177
	v_fmac_f32_e32 v200, v96, v176
	v_mul_f32_e32 v201, v95, v179
	v_fmac_f32_e32 v202, v44, v176
	v_mul_f32_e32 v203, v43, v179
	v_fmac_f32_e32 v204, v62, v176
	v_mul_f32_e32 v205, v59, v179
	v_fmac_f32_e32 v177, v22, v176
	v_mul_f32_e32 v176, v21, v179
	v_fmac_f32_e32 v201, v94, v178
	v_fmac_f32_e32 v203, v42, v178
	v_fmac_f32_e32 v205, v58, v178
	v_fmac_f32_e32 v176, v20, v178
	s_waitcnt lgkmcnt(0)
	v_mul_f32_e32 v178, v101, v181
	v_mul_f32_e32 v206, v47, v181
	v_mul_f32_e32 v208, v61, v181
	v_mul_f32_e32 v181, v19, v181
	v_add_f32_e32 v173, v173, v175
	v_fmac_f32_e32 v178, v100, v180
	v_mul_f32_e32 v179, v99, v183
	v_fmac_f32_e32 v206, v46, v180
	v_mul_f32_e32 v207, v41, v183
	v_fmac_f32_e32 v208, v60, v180
	v_mul_f32_e32 v209, v57, v183
	v_fmac_f32_e32 v181, v18, v180
	v_mul_f32_e32 v180, v17, v183
	v_add_f32_e32 v175, v184, v185
	v_add_f32_e32 v184, v190, v191
	v_add_f32_e32 v173, 0, v173
	v_fmac_f32_e32 v179, v98, v182
	v_fmac_f32_e32 v207, v40, v182
	v_fmac_f32_e32 v209, v56, v182
	v_fmac_f32_e32 v180, v16, v182
	v_add_f32_e32 v182, v186, v187
	v_add_f32_e32 v173, v173, v184
	v_add_f32_e32 v184, v192, v193
	v_add_f32_e32 v175, 0, v175
	v_add_f32_e32 v183, v188, v189
	v_add_f32_e32 v175, v175, v184
	v_add_f32_e32 v184, v196, v197
	v_add_f32_e32 v182, 0, v182
	v_add_f32_e32 v182, v182, v184
	v_add_f32_e32 v184, v198, v199
	v_add_f32_e32 v183, 0, v183
	v_add_f32_e32 v183, v183, v184
	v_add_f32_e32 v184, v200, v201
	v_add_f32_e32 v176, v177, v176
	v_add_f32_e32 v173, v173, v184
	v_add_f32_e32 v184, v202, v203
	v_add_f32_e32 v177, v183, v176
	v_add_f32_e32 v176, v178, v179
	v_add_f32_e32 v175, v175, v184
	v_add_f32_e32 v184, v204, v205
	v_add_f32_e32 v186, v173, v176
	v_add_f32_e32 v173, v206, v207
	v_add_f32_e32 v182, v182, v184
	v_add_f32_e32 v176, v175, v173
	v_add_f32_e32 v173, v208, v209
	v_add_f32_e32 v175, v182, v173
	v_add_f32_e32 v173, v181, v180
	v_add_f32_e32 v173, v177, v173
	ds_read_b128 v[178:181], v118 offset:61440
	ds_read_b128 v[182:185], v118 offset:62464
	s_waitcnt lgkmcnt(1)
; __device__ __forceinline__ void phase_prologue(const Params& P, LAS unsigned char* lds) {
;     ...
; #pragma unroll
;         for (int q = 0; q < RP; ++q) {
;             float r8[8], r4[4], r2[2], r1;
;             const bool h5 = lane & 32, h4 = lane & 16, h3 = lane & 8, h2 = lane & 4;
; #pragma unroll
;             for (int i = 0; i < 8; ++i) r8[i] = (h5 ? a[q][i + 8] : a[q][i]) + __shfl_xor(h5 ? a[q][i] : a[q][i + 8], 32);
; #pragma unroll
;             for (int i = 0; i < 4; ++i) r4[i] = (h4 ? r8[i + 4] : r8[i]) + __shfl_xor(h4 ? r8[i] : r8[i + 4], 16);
; #pragma unroll
;             for (int i = 0; i < 2; ++i) r2[i] = (h3 ? r4[i + 2] : r4[i]) + __shfl_xor(h3 ? r4[i] : r4[i + 2], 8);
;             r1 = (h2 ? r2[1] : r2[0]) + __shfl_xor(h2 ? r2[0] : r2[1], 4);
;             r1 += __shfl_xor(r1, 2); r1 += __shfl_xor(r1, 1);
;             if ((lane & 3) == 0) LR[(size_t)(m0 + q * NGW) * 16 + (lane >> 2)] = r1;
;         }
	v_mul_f32_e32 v39, v39, v179
	v_fmac_f32_e32 v39, v38, v178
	v_mul_f32_e32 v38, v53, v181
	v_fmac_f32_e32 v38, v52, v180
	v_mul_f32_e32 v52, v31, v179
	v_mul_f32_e32 v53, v29, v181
	s_waitcnt lgkmcnt(0)
	v_mul_f32_e32 v35, v35, v183
	v_fmac_f32_e32 v52, v30, v178
	v_fmac_f32_e32 v53, v28, v180
	v_fmac_f32_e32 v35, v34, v182
	v_mul_f32_e32 v34, v49, v185
	ds_read_b128 v[28:31], v118 offset:63488
	v_fmac_f32_e32 v34, v48, v184
	v_mul_f32_e32 v48, v27, v183
	v_mul_f32_e32 v49, v25, v185
	v_fmac_f32_e32 v48, v26, v182
	v_fmac_f32_e32 v49, v24, v184
	ds_read_b128 v[24:27], v118 offset:64512
	v_mul_f32_e32 v33, v33, v185
	v_fmac_f32_e32 v33, v32, v184
	v_mul_f32_e32 v32, v51, v183
	s_waitcnt lgkmcnt(1)
	v_mul_f32_e32 v45, v45, v29
	v_mul_f32_e32 v43, v43, v31
	v_mul_f32_e32 v37, v37, v181
	v_fmac_f32_e32 v32, v50, v182
	v_mul_f32_e32 v50, v97, v29
	v_mul_f32_e32 v51, v95, v31
	v_fmac_f32_e32 v45, v44, v28
	v_fmac_f32_e32 v43, v42, v30
	v_mul_f32_e32 v42, v63, v29
	v_mul_f32_e32 v44, v59, v31
	v_mul_f32_e32 v23, v23, v29
	v_mul_f32_e32 v21, v21, v31
	v_mul_f32_e32 v109, v109, v179
	v_mul_f32_e32 v107, v107, v181
	v_fmac_f32_e32 v37, v36, v180
	v_mul_f32_e32 v36, v55, v179
	v_fmac_f32_e32 v50, v96, v28
	v_fmac_f32_e32 v51, v94, v30
	v_fmac_f32_e32 v42, v62, v28
	v_fmac_f32_e32 v44, v58, v30
	v_fmac_f32_e32 v23, v22, v28
	v_fmac_f32_e32 v21, v20, v30
	s_waitcnt lgkmcnt(0)
	v_mul_f32_e32 v20, v101, v25
	v_mul_f32_e32 v28, v47, v25
	v_mul_f32_e32 v30, v61, v25
	v_mul_f32_e32 v19, v19, v25
	v_fmac_f32_e32 v109, v108, v178
	v_fmac_f32_e32 v107, v106, v180
	v_fmac_f32_e32 v36, v54, v178
	v_mul_f32_e32 v54, v105, v183
	v_mul_f32_e32 v55, v103, v185
	v_fmac_f32_e32 v20, v100, v24
	v_fmac_f32_e32 v28, v46, v24
	v_fmac_f32_e32 v30, v60, v24
	v_fmac_f32_e32 v19, v18, v24
	v_mul_f32_e32 v24, v17, v27
	v_fmac_f32_e32 v54, v104, v182
	v_fmac_f32_e32 v55, v102, v184
	v_mul_f32_e32 v22, v99, v27
	v_mul_f32_e32 v29, v41, v27
	v_mul_f32_e32 v31, v57, v27
	v_fmac_f32_e32 v24, v16, v26
	v_add_f32_e32 v16, v109, v107
	v_fmac_f32_e32 v22, v98, v26
	v_fmac_f32_e32 v29, v40, v26
	v_fmac_f32_e32 v31, v56, v26
	v_add_f32_e32 v17, v39, v37
	v_add_f32_e32 v26, v54, v55
	v_add_f32_e32 v16, 0, v16
	v_add_f32_e32 v18, v36, v38
	v_add_f32_e32 v16, v16, v26
	v_add_f32_e32 v26, v35, v33
	v_add_f32_e32 v17, 0, v17
	v_add_f32_e32 v25, v52, v53
	v_add_f32_e32 v17, v17, v26
	v_add_f32_e32 v26, v32, v34
	v_add_f32_e32 v18, 0, v18
	v_add_f32_e32 v18, v18, v26
	v_add_f32_e32 v26, v48, v49
	v_add_f32_e32 v25, 0, v25
	v_add_f32_e32 v25, v25, v26
	v_add_f32_e32 v26, v50, v51
	v_add_f32_e32 v16, v16, v26
	v_add_f32_e32 v26, v45, v43
	v_add_f32_e32 v17, v17, v26
	v_add_f32_e32 v26, v42, v44
	v_add_f32_e32 v26, v18, v26
	v_add_f32_e32 v18, v23, v21
	v_add_f32_e32 v21, v25, v18
	v_add_f32_e32 v18, v20, v22
	v_add_f32_e32 v20, v16, v18
	v_add_f32_e32 v16, v28, v29
	v_add_f32_e32 v18, v17, v16
	v_add_f32_e32 v16, v30, v31
	v_add_f32_e32 v17, v26, v16
	v_add_f32_e32 v16, v19, v24
	v_add_f32_e32 v16, v21, v16
	v_cndmask_b32_e64 v21, v122, v154, s[4:5]
	ds_bpermute_b32 v21, v117, v21
	v_cndmask_b32_e64 v22, v126, v158, s[4:5]
	ds_bpermute_b32 v22, v117, v22
	v_cndmask_b32_e64 v23, v130, v162, s[4:5]
	ds_bpermute_b32 v23, v117, v23
	v_cndmask_b32_e64 v24, v134, v166, s[4:5]
	ds_bpermute_b32 v24, v117, v24
	v_cndmask_b32_e64 v25, v138, v170, s[4:5]
	v_cndmask_b32_e64 v19, v154, v122, s[4:5]
	ds_bpermute_b32 v25, v117, v25
	v_cndmask_b32_e64 v26, v142, v174, s[4:5]
	s_waitcnt lgkmcnt(4)
	v_add_f32_e32 v19, v19, v21
	v_cndmask_b32_e64 v21, v158, v126, s[4:5]
	ds_bpermute_b32 v26, v117, v26
	v_cndmask_b32_e64 v27, v146, v186, s[4:5]
	s_waitcnt lgkmcnt(4)
	v_add_f32_e32 v21, v21, v22
	v_cndmask_b32_e64 v28, v149, v20, s[4:5]
	v_cndmask_b32_e64 v22, v162, v130, s[4:5]
	ds_bpermute_b32 v27, v117, v27
	ds_bpermute_b32 v28, v117, v28
	s_waitcnt lgkmcnt(5)
	v_add_f32_e32 v22, v22, v23
	v_cndmask_b32_e64 v23, v166, v134, s[4:5]
	s_waitcnt lgkmcnt(4)
	v_add_f32_e32 v23, v23, v24
	v_cndmask_b32_e64 v24, v170, v138, s[4:5]
	s_waitcnt lgkmcnt(3)
	v_add_f32_e32 v24, v24, v25
	v_cndmask_b32_e64 v25, v174, v142, s[4:5]
	s_waitcnt lgkmcnt(2)
	v_add_f32_e32 v25, v25, v26
	v_cndmask_b32_e64 v26, v186, v146, s[4:5]
	v_cndmask_b32_e64 v20, v20, v149, s[4:5]
	s_waitcnt lgkmcnt(1)
	v_add_f32_e32 v26, v26, v27
	s_waitcnt lgkmcnt(0)
	v_add_f32_e32 v20, v20, v28
	v_cndmask_b32_e64 v29, v19, v24, s[6:7]
	v_cndmask_b32_e64 v19, v24, v19, s[6:7]
	v_cndmask_b32_e64 v24, v25, v21, s[6:7]
	v_cndmask_b32_e64 v21, v21, v25, s[6:7]
	v_cndmask_b32_e64 v25, v22, v26, s[6:7]
	v_cndmask_b32_e64 v27, v23, v20, s[6:7]
	ds_bpermute_b32 v29, v116, v29
	ds_bpermute_b32 v21, v116, v21
	ds_bpermute_b32 v25, v116, v25
	ds_bpermute_b32 v27, v116, v27
	v_cndmask_b32_e64 v22, v26, v22, s[6:7]
	v_cndmask_b32_e64 v20, v20, v23, s[6:7]
	s_waitcnt lgkmcnt(3)
	v_add_f32_e32 v19, v19, v29
	s_waitcnt lgkmcnt(2)
	v_add_f32_e32 v21, v24, v21
	s_waitcnt lgkmcnt(1)
	v_add_f32_e32 v22, v22, v25
	s_waitcnt lgkmcnt(0)
	v_add_f32_e32 v20, v20, v27
	v_cndmask_b32_e64 v23, v19, v22, s[8:9]
	v_cndmask_b32_e64 v24, v21, v20, s[8:9]
	ds_bpermute_b32 v23, v115, v23
	ds_bpermute_b32 v24, v115, v24
	v_cndmask_b32_e64 v19, v22, v19, s[8:9]
	v_cndmask_b32_e64 v20, v20, v21, s[8:9]
	s_waitcnt lgkmcnt(1)
	v_add_f32_e32 v19, v19, v23
	s_waitcnt lgkmcnt(0)
	v_add_f32_e32 v20, v20, v24
	v_cndmask_b32_e64 v21, v19, v20, s[10:11]
	ds_bpermute_b32 v21, v114, v21
	v_cndmask_b32_e64 v19, v20, v19, s[10:11]
	s_waitcnt lgkmcnt(0)
	v_add_f32_e32 v19, v19, v21
	ds_bpermute_b32 v20, v113, v19
	s_waitcnt lgkmcnt(0)
	v_add_f32_e32 v19, v19, v20
	ds_bpermute_b32 v20, v112, v19
	s_and_saveexec_b64 s[14:15], s[12:13]
	s_cbranch_execz .LBB0_102
	s_waitcnt lgkmcnt(0)
	v_add_f32_e32 v19, v19, v20
	v_lshl_add_u64 v[20:21], v[88:89], 0, v[86:87]
	global_store_dword v[20:21], v19, off

; #define PG8_STAGE(bufoff, gbase, voff) do { _Pragma("unroll") for (int _i = 0; _i < 2; ++_i) \
;         __builtin_amdgcn_global_load_lds((const unsigned*)((const char*)(gbase) + (voff)[_i]), (LAS unsigned*)(lds + (bufoff) + ldsw + _i * 8192), 16, 0, 0); } while (0)
; #define PG8_LDA(dst, b, h) do { _Pragma("unroll") for (int m = 0; m < 4; ++m) _Pragma("unroll") for (int k = 0; k < 2; ++k) dst[m][k] = *(const LAS bf16x8*)(lds + PG8_SA(b, h) + aoff + m * 2048 + k * 1024); } while (0)
; #define PG8_LDB(dst, b, h) do { _Pragma("unroll") for (int n = 0; n < 2; ++n) _Pragma("unroll") for (int k = 0; k < 2; ++k) dst[n][k] = *(const LAS bf16x8*)(lds + PG8_SB(b, h) + boff + n * 2048 + k * 1024); } while (0)
; #define PG8_MMA(ai, bj, At, Bt) do { __builtin_amdgcn_s_setprio(1); _Pragma("unroll") for (int m = 0; m < 4; ++m) _Pragma("unroll") for (int n = 0; n < 2; ++n) _Pragma("unroll") for (int k = 0; k < 2; ++k) \
;         acc[ai][bj][m][n] = __builtin_amdgcn_mfma_f32_16x16x32_bf16(Bt[n][k], At[m][k], acc[ai][bj][m][n], 0, 0, 0); __builtin_amdgcn_s_setprio(0); } while (0)
; #define PG8_WAIT_V(n) asm volatile("s_waitcnt vmcnt(" #n ")" ::: "memory")
; #define PG8_WAIT_L(n) asm volatile("s_waitcnt lgkmcnt(" #n ")" ::: "memory")
; #define PG8_BAR __builtin_amdgcn_s_barrier()
; #define PG8_SCHED __builtin_amdgcn_sched_barrier(0)
; template <class Epi>
; __device__ __forceinline__ void gemm_phase(LAS unsigned char* lds, const Gemm g, const StaticOrder& S, const Epi& E) {
;     ...
;             const bool last = (t == nt - 2);
;             const char* a1 = cA + (size_t)(t + 1) * kstep;
;             const char* a2 = last ? nA : cA + (size_t)(t + 2) * kstep; const char* b2 = last ? nB : cB + (size_t)(t + 2) * kstep;
;             const char* a3 = a2 + kstep; const char* b3 = b2 + kstep;
;             PG8_LDB(B0, 0, 0); PG8_LDB(B1, 0, 1); PG8_SCHED; PG8_LDA(At, 0, 0); PG8_STAGE(PG8_SA(1, 1), a1 + hstepA, voffA);
;             PG8_WAIT_V(8); PG8_WAIT_L(0); PG8_BAR; PG8_MMA(0, 0, At, B0); PG8_MMA(0, 1, At, B1); PG8_BAR; PG8_SCHED;
;     ...
; #pragma unroll
;         for (int a = 0; a < 2; ++a)
; #pragma unroll
;             for (int b = 0; b < 2; ++b)
; #pragma unroll
;                 for (int m = 0; m < 4; ++m)
; #pragma unroll
;                     for (int n = 0; n < 2; ++n) acc[a][b][m][n] = (f32x4){0.f, 0.f, 0.f, 0.f};
;         cur = nxt; cA = nA; cB = nB; ++ui;
.LBB0_159:
	s_ashr_i32 s79, s78, 31
	s_lshl_b64 s[16:17], s[78:79], 19
	s_add_u32 s80, s68, s16
	s_addc_u32 s81, s69, s17
	s_and_b64 s[16:17], s[4:5], exec
	s_cselect_b32 s7, s81, s9
	s_cselect_b32 s12, s80, s8
	s_ashr_i32 s77, s76, 31
	s_lshl_b64 s[16:17], s[76:77], 19
	s_add_u32 s82, s18, s16
	s_addc_u32 s83, s19, s17
	s_and_b64 s[16:17], s[4:5], exec
	s_cselect_b32 s16, s83, s87
	s_cselect_b32 s17, s82, s86
	s_add_u32 s8, s8, 0x40080
	s_addc_u32 s9, s9, 0
	s_add_u32 s77, s86, 0x100
	v_mov_b32_e32 v0, 0
	s_addc_u32 s79, s87, 0
	s_mov_b32 s88, -2
	v_mov_b32_e32 v1, v0
	v_mov_b32_e32 v2, v0
	v_mov_b32_e32 v3, v0
	v_mov_b32_e32 v8, v0
	v_mov_b32_e32 v9, v0
	v_mov_b32_e32 v10, v0
	v_mov_b32_e32 v11, v0
	v_mov_b32_e32 v16, v0
	v_mov_b32_e32 v17, v0
	v_mov_b32_e32 v18, v0
	v_mov_b32_e32 v19, v0
	v_mov_b32_e32 v24, v0
	v_mov_b32_e32 v25, v0
	v_mov_b32_e32 v26, v0
	v_mov_b32_e32 v27, v0
	v_mov_b32_e32 v32, v0
	v_mov_b32_e32 v33, v0
	v_mov_b32_e32 v34, v0
	v_mov_b32_e32 v35, v0
	v_mov_b32_e32 v40, v0
	v_mov_b32_e32 v41, v0
	v_mov_b32_e32 v42, v0
	v_mov_b32_e32 v43, v0
	v_mov_b32_e32 v48, v0
	v_mov_b32_e32 v49, v0
	v_mov_b32_e32 v50, v0
	v_mov_b32_e32 v51, v0
	v_mov_b32_e32 v56, v0
	v_mov_b32_e32 v57, v0
	v_mov_b32_e32 v58, v0
	v_mov_b32_e32 v59, v0
	v_mov_b32_e32 v4, v0
	v_mov_b32_e32 v5, v0
	v_mov_b32_e32 v6, v0
	v_mov_b32_e32 v7, v0
	v_mov_b32_e32 v12, v0
	v_mov_b32_e32 v13, v0
	v_mov_b32_e32 v14, v0
	v_mov_b32_e32 v15, v0
	v_mov_b32_e32 v20, v0
	v_mov_b32_e32 v21, v0
	v_mov_b32_e32 v22, v0
	v_mov_b32_e32 v23, v0
	v_mov_b32_e32 v28, v0
	v_mov_b32_e32 v29, v0
	v_mov_b32_e32 v30, v0
	v_mov_b32_e32 v31, v0
	v_mov_b32_e32 v36, v0
	v_mov_b32_e32 v37, v0
	v_mov_b32_e32 v38, v0
	v_mov_b32_e32 v39, v0
	v_mov_b32_e32 v44, v0
	v_mov_b32_e32 v45, v0
	v_mov_b32_e32 v46, v0
	v_mov_b32_e32 v47, v0
	v_mov_b32_e32 v52, v0
	v_mov_b32_e32 v53, v0
	v_mov_b32_e32 v54, v0
	v_mov_b32_e32 v55, v0
	v_mov_b32_e32 v60, v0
	v_mov_b32_e32 v61, v0
	v_mov_b32_e32 v62, v0
	v_mov_b32_e32 v63, v0
	v_mov_b32_e32 v64, v0
	v_mov_b32_e32 v65, v0
	v_mov_b32_e32 v66, v0
	v_mov_b32_e32 v67, v0
	v_mov_b32_e32 v72, v0
	v_mov_b32_e32 v73, v0
	v_mov_b32_e32 v74, v0
	v_mov_b32_e32 v75, v0
	v_mov_b32_e32 v80, v0
	v_mov_b32_e32 v81, v0
	v_mov_b32_e32 v82, v0
	v_mov_b32_e32 v83, v0
	v_mov_b32_e32 v88, v0
	v_mov_b32_e32 v89, v0
	v_mov_b32_e32 v90, v0
	v_mov_b32_e32 v91, v0
	v_mov_b32_e32 v96, v0
	v_mov_b32_e32 v97, v0
	v_mov_b32_e32 v98, v0
	v_mov_b32_e32 v99, v0
	v_mov_b32_e32 v104, v0
	v_mov_b32_e32 v105, v0
	v_mov_b32_e32 v106, v0
	v_mov_b32_e32 v107, v0
	v_mov_b32_e32 v112, v0
	v_mov_b32_e32 v113, v0
	v_mov_b32_e32 v114, v0
	v_mov_b32_e32 v115, v0
	v_mov_b32_e32 v120, v0
	v_mov_b32_e32 v121, v0
	v_mov_b32_e32 v122, v0
	v_mov_b32_e32 v123, v0
	v_mov_b32_e32 v68, v0
	v_mov_b32_e32 v69, v0
	v_mov_b32_e32 v70, v0
	v_mov_b32_e32 v71, v0
	v_mov_b32_e32 v76, v0
	v_mov_b32_e32 v77, v0
	v_mov_b32_e32 v78, v0
	v_mov_b32_e32 v79, v0
	v_mov_b32_e32 v84, v0
	v_mov_b32_e32 v85, v0
	v_mov_b32_e32 v86, v0
	v_mov_b32_e32 v87, v0
	v_mov_b32_e32 v92, v0
	v_mov_b32_e32 v93, v0
	v_mov_b32_e32 v94, v0
	v_mov_b32_e32 v95, v0
	v_mov_b32_e32 v100, v0
	v_mov_b32_e32 v101, v0
	v_mov_b32_e32 v102, v0
	v_mov_b32_e32 v103, v0
	v_mov_b32_e32 v108, v0
	v_mov_b32_e32 v109, v0
	v_mov_b32_e32 v110, v0
	v_mov_b32_e32 v111, v0
	v_mov_b32_e32 v116, v0
	v_mov_b32_e32 v117, v0
	v_mov_b32_e32 v118, v0
	v_mov_b32_e32 v119, v0
	v_mov_b32_e32 v124, v0
	v_mov_b32_e32 v125, v0
	v_mov_b32_e32 v126, v0
	v_mov_b32_e32 v127, v0
	s_cmp_eq_u32 s21, 1
	s_cbranch_scc1 .LBB0_160
	ds_read_b128 v[146:149], v164
	ds_read_b128 v[150:153], v164 offset:1024
	ds_read_b128 v[154:157], v164 offset:2048
	ds_read_b128 v[158:161], v164 offset:3072
	ds_read_b128 v[168:171], v165
	ds_read_b128 v[172:175], v165 offset:1024
	ds_read_b128 v[176:179], v165 offset:2048
	ds_read_b128 v[180:183], v165 offset:3072
	s_add_u32 s42, s8, 0xfffc0080
	s_addc_u32 s43, s9, -1
	s_cmp_eq_u32 s88, 12
	s_cselect_b32 s43, s7, s43
	s_cselect_b32 s42, s12, s42
	s_cselect_b32 s87, s16, s79
	s_cselect_b32 s86, s17, s77
	v_lshl_add_u64 v[192:193], s[8:9], 0, v[138:139]
	s_add_i32 m0, s27, 0xc000
	ds_read_b128 v[184:187], v166
	ds_read_b128 v[188:191], v166 offset:1024
	ds_read_b128 v[196:199], v166 offset:2048
	ds_read_b128 v[200:203], v166 offset:3072
	ds_read_b128 v[204:207], v166 offset:4096
	ds_read_b128 v[208:211], v166 offset:5120
	ds_read_b128 v[212:215], v166 offset:6144
	ds_read_b128 v[216:219], v166 offset:7168
	global_load_lds_dwordx4 v[192:193], off
	v_lshl_add_u64 v[192:193], s[8:9], 0, v[140:141]
	s_add_i32 m0, s27, 0xe000
	s_nop 0
	global_load_lds_dwordx4 v[192:193], off
	s_waitcnt vmcnt(24)
	s_waitcnt lgkmcnt(0)
	s_barrier
; #define PG8_STAGE(bufoff, gbase, voff) do { _Pragma("unroll") for (int _i = 0; _i < 2; ++_i) \
;         __builtin_amdgcn_global_load_lds((const unsigned*)((const char*)(gbase) + (voff)[_i]), (LAS unsigned*)(lds + (bufoff) + ldsw + _i * 8192), 16, 0, 0); } while (0)
; #define PG8_LDA(dst, b, h) do { _Pragma("unroll") for (int m = 0; m < 4; ++m) _Pragma("unroll") for (int k = 0; k < 2; ++k) dst[m][k] = *(const LAS bf16x8*)(lds + PG8_SA(b, h) + aoff + m * 2048 + k * 1024); } while (0)
; #define PG8_MMA(ai, bj, At, Bt) do { __builtin_amdgcn_s_setprio(1); _Pragma("unroll") for (int m = 0; m < 4; ++m) _Pragma("unroll") for (int n = 0; n < 2; ++n) _Pragma("unroll") for (int k = 0; k < 2; ++k) \
;         acc[ai][bj][m][n] = __builtin_amdgcn_mfma_f32_16x16x32_bf16(Bt[n][k], At[m][k], acc[ai][bj][m][n], 0, 0, 0); __builtin_amdgcn_s_setprio(0); } while (0)
; #define PG8_WAIT_V(n) asm volatile("s_waitcnt vmcnt(" #n ")" ::: "memory")
; #define PG8_WAIT_L(n) asm volatile("s_waitcnt lgkmcnt(" #n ")" ::: "memory")
; #define PG8_BAR __builtin_amdgcn_s_barrier()
; #define PG8_SCHED __builtin_amdgcn_sched_barrier(0)
; template <class Epi>
; __device__ __forceinline__ void gemm_phase(LAS unsigned char* lds, const Gemm g, const StaticOrder& S, const Epi& E) {
;     ...
;             PG8_WAIT_V(8); PG8_WAIT_L(0); PG8_BAR; PG8_MMA(0, 0, At, B0); PG8_MMA(0, 1, At, B1); PG8_BAR; PG8_SCHED;
;             PG8_LDA(At, 0, 1); PG8_STAGE(PG8_SB(0, 0), b2, voffB); PG8_STAGE(PG8_SB(0, 1), b2 + hstepB, voffB); PG8_STAGE(PG8_SA(0, 0), a2, voffA);
;             PG8_WAIT_V(8); PG8_WAIT_L(0); PG8_BAR; PG8_MMA(1, 0, At, B0); PG8_MMA(1, 1, At, B1); PG8_BAR; PG8_SCHED;
	s_setprio 1
	s_waitcnt lgkmcnt(0)
	v_mfma_f32_16x16x32_bf16 v[124:127], v[146:149], v[184:187], v[124:127]
	v_mfma_f32_16x16x32_bf16 v[116:119], v[154:157], v[184:187], v[116:119]
	v_mfma_f32_16x16x32_bf16 v[108:111], v[146:149], v[196:199], v[108:111]
	v_mfma_f32_16x16x32_bf16 v[100:103], v[154:157], v[196:199], v[100:103]
	v_mfma_f32_16x16x32_bf16 v[92:95], v[146:149], v[204:207], v[92:95]
	v_mfma_f32_16x16x32_bf16 v[84:87], v[154:157], v[204:207], v[84:87]
	v_mfma_f32_16x16x32_bf16 v[76:79], v[146:149], v[212:215], v[76:79]
	v_mfma_f32_16x16x32_bf16 v[68:71], v[154:157], v[212:215], v[68:71]
	v_mfma_f32_16x16x32_bf16 v[124:127], v[150:153], v[188:191], v[124:127]
	v_mfma_f32_16x16x32_bf16 v[116:119], v[158:161], v[188:191], v[116:119]
	v_mfma_f32_16x16x32_bf16 v[108:111], v[150:153], v[200:203], v[108:111]
	v_mfma_f32_16x16x32_bf16 v[100:103], v[158:161], v[200:203], v[100:103]
	v_mfma_f32_16x16x32_bf16 v[92:95], v[150:153], v[208:211], v[92:95]
	v_mfma_f32_16x16x32_bf16 v[84:87], v[158:161], v[208:211], v[84:87]
	v_mfma_f32_16x16x32_bf16 v[76:79], v[150:153], v[216:219], v[76:79]
	v_mfma_f32_16x16x32_bf16 v[68:71], v[158:161], v[216:219], v[68:71]
	s_setprio 0
	s_setprio 1
	v_mfma_f32_16x16x32_bf16 v[120:123], v[168:171], v[184:187], v[120:123]
	v_mfma_f32_16x16x32_bf16 v[112:115], v[176:179], v[184:187], v[112:115]
	v_mfma_f32_16x16x32_bf16 v[104:107], v[168:171], v[196:199], v[104:107]
	v_mfma_f32_16x16x32_bf16 v[96:99], v[176:179], v[196:199], v[96:99]
	v_mfma_f32_16x16x32_bf16 v[88:91], v[168:171], v[204:207], v[88:91]
	v_mfma_f32_16x16x32_bf16 v[80:83], v[176:179], v[204:207], v[80:83]
	v_mfma_f32_16x16x32_bf16 v[72:75], v[168:171], v[212:215], v[72:75]
	v_mfma_f32_16x16x32_bf16 v[64:67], v[176:179], v[212:215], v[64:67]
	v_mfma_f32_16x16x32_bf16 v[120:123], v[172:175], v[188:191], v[120:123]
	v_mfma_f32_16x16x32_bf16 v[112:115], v[180:183], v[188:191], v[112:115]
	v_mfma_f32_16x16x32_bf16 v[104:107], v[172:175], v[200:203], v[104:107]
	v_mfma_f32_16x16x32_bf16 v[96:99], v[180:183], v[200:203], v[96:99]
	v_mfma_f32_16x16x32_bf16 v[88:91], v[172:175], v[208:211], v[88:91]
	v_mfma_f32_16x16x32_bf16 v[80:83], v[180:183], v[208:211], v[80:83]
	v_mfma_f32_16x16x32_bf16 v[72:75], v[172:175], v[216:219], v[72:75]
	v_mfma_f32_16x16x32_bf16 v[64:67], v[180:183], v[216:219], v[64:67]
	s_setprio 0
	s_barrier
	s_add_i32 s89, s1, s3
	v_lshl_add_u64 v[192:193], s[86:87], 0, v[130:131]
	s_mov_b32 m0, s89
	ds_read_b128 v[184:187], v166 offset:16384
	ds_read_b128 v[188:191], v166 offset:17408
	ds_read_b128 v[196:199], v166 offset:18432
	ds_read_b128 v[200:203], v166 offset:19456
	ds_read_b128 v[204:207], v166 offset:20480
	ds_read_b128 v[208:211], v166 offset:21504
	ds_read_b128 v[212:215], v166 offset:22528
	ds_read_b128 v[216:219], v166 offset:23552
	global_load_lds_dwordx4 v[192:193], off
	s_add_i32 m0, s89, 0x2000
	s_add_u32 s90, s86, 0x40000
	v_lshl_add_u64 v[220:221], s[86:87], 0, v[134:135]
	s_addc_u32 s91, s87, 0
	s_add_i32 s89, s20, s3
	global_load_lds_dwordx4 v[220:221], off
	v_lshl_add_u64 v[222:223], s[90:91], 0, v[130:131]
	s_mov_b32 m0, s89
	v_lshl_add_u64 v[224:225], s[42:43], 0, v[132:133]
	global_load_lds_dwordx4 v[222:223], off
	v_lshl_add_u64 v[222:223], s[90:91], 0, v[134:135]
	s_add_i32 m0, s89, 0x2000
	s_nop 0
	global_load_lds_dwordx4 v[222:223], off
	v_lshl_add_u64 v[222:223], s[42:43], 0, v[128:129]
	s_mov_b32 m0, s27
	s_nop 0
	global_load_lds_dwordx4 v[222:223], off
	s_mov_b32 m0, s29
	s_nop 0
	global_load_lds_dwordx4 v[224:225], off
	s_waitcnt vmcnt(24)
	s_waitcnt lgkmcnt(0)
	s_barrier
	s_setprio 1
	s_waitcnt lgkmcnt(0)
	v_mfma_f32_16x16x32_bf16 v[60:63], v[146:149], v[184:187], v[60:63]
	v_mfma_f32_16x16x32_bf16 v[52:55], v[154:157], v[184:187], v[52:55]
	v_mfma_f32_16x16x32_bf16 v[44:47], v[146:149], v[196:199], v[44:47]
	v_mfma_f32_16x16x32_bf16 v[36:39], v[154:157], v[196:199], v[36:39]
	v_mfma_f32_16x16x32_bf16 v[28:31], v[146:149], v[204:207], v[28:31]
	v_mfma_f32_16x16x32_bf16 v[20:23], v[154:157], v[204:207], v[20:23]
	v_mfma_f32_16x16x32_bf16 v[12:15], v[146:149], v[212:215], v[12:15]
	v_mfma_f32_16x16x32_bf16 v[4:7], v[154:157], v[212:215], v[4:7]
	v_mfma_f32_16x16x32_bf16 v[60:63], v[150:153], v[188:191], v[60:63]
	v_mfma_f32_16x16x32_bf16 v[52:55], v[158:161], v[188:191], v[52:55]
	v_mfma_f32_16x16x32_bf16 v[44:47], v[150:153], v[200:203], v[44:47]
	v_mfma_f32_16x16x32_bf16 v[36:39], v[158:161], v[200:203], v[36:39]
	v_mfma_f32_16x16x32_bf16 v[28:31], v[150:153], v[208:211], v[28:31]
	v_mfma_f32_16x16x32_bf16 v[20:23], v[158:161], v[208:211], v[20:23]
	v_mfma_f32_16x16x32_bf16 v[12:15], v[150:153], v[216:219], v[12:15]
	v_mfma_f32_16x16x32_bf16 v[4:7], v[158:161], v[216:219], v[4:7]
	s_setprio 0
	s_setprio 1
	v_mfma_f32_16x16x32_bf16 v[56:59], v[168:171], v[184:187], v[56:59]
	v_mfma_f32_16x16x32_bf16 v[48:51], v[176:179], v[184:187], v[48:51]
	v_mfma_f32_16x16x32_bf16 v[40:43], v[168:171], v[196:199], v[40:43]
	v_mfma_f32_16x16x32_bf16 v[32:35], v[176:179], v[196:199], v[32:35]
	v_mfma_f32_16x16x32_bf16 v[24:27], v[168:171], v[204:207], v[24:27]
	v_mfma_f32_16x16x32_bf16 v[16:19], v[176:179], v[204:207], v[16:19]
	v_mfma_f32_16x16x32_bf16 v[8:11], v[168:171], v[212:215], v[8:11]
	v_mfma_f32_16x16x32_bf16 v[0:3], v[176:179], v[212:215], v[0:3]
	v_mfma_f32_16x16x32_bf16 v[56:59], v[172:175], v[188:191], v[56:59]
	v_mfma_f32_16x16x32_bf16 v[48:51], v[180:183], v[188:191], v[48:51]
	v_mfma_f32_16x16x32_bf16 v[40:43], v[172:175], v[200:203], v[40:43]
	v_mfma_f32_16x16x32_bf16 v[32:35], v[180:183], v[200:203], v[32:35]
	v_mfma_f32_16x16x32_bf16 v[24:27], v[172:175], v[208:211], v[24:27]
	v_mfma_f32_16x16x32_bf16 v[16:19], v[180:183], v[208:211], v[16:19]
	v_mfma_f32_16x16x32_bf16 v[8:11], v[172:175], v[216:219], v[8:11]
	v_mfma_f32_16x16x32_bf16 v[0:3], v[180:183], v[216:219], v[0:3]
	s_setprio 0
	s_barrier
; #define PG8_STAGE(bufoff, gbase, voff) do { _Pragma("unroll") for (int _i = 0; _i < 2; ++_i) \
;         __builtin_amdgcn_global_load_lds((const unsigned*)((const char*)(gbase) + (voff)[_i]), (LAS unsigned*)(lds + (bufoff) + ldsw + _i * 8192), 16, 0, 0); } while (0)
; #define PG8_LDA(dst, b, h) do { _Pragma("unroll") for (int m = 0; m < 4; ++m) _Pragma("unroll") for (int k = 0; k < 2; ++k) dst[m][k] = *(const LAS bf16x8*)(lds + PG8_SA(b, h) + aoff + m * 2048 + k * 1024); } while (0)
; #define PG8_LDB(dst, b, h) do { _Pragma("unroll") for (int n = 0; n < 2; ++n) _Pragma("unroll") for (int k = 0; k < 2; ++k) dst[n][k] = *(const LAS bf16x8*)(lds + PG8_SB(b, h) + boff + n * 2048 + k * 1024); } while (0)
; #define PG8_MMA(ai, bj, At, Bt) do { __builtin_amdgcn_s_setprio(1); _Pragma("unroll") for (int m = 0; m < 4; ++m) _Pragma("unroll") for (int n = 0; n < 2; ++n) _Pragma("unroll") for (int k = 0; k < 2; ++k) \
;         acc[ai][bj][m][n] = __builtin_amdgcn_mfma_f32_16x16x32_bf16(Bt[n][k], At[m][k], acc[ai][bj][m][n], 0, 0, 0); __builtin_amdgcn_s_setprio(0); } while (0)
; #define PG8_WAIT_V(n) asm volatile("s_waitcnt vmcnt(" #n ")" ::: "memory")
; #define PG8_WAIT_L(n) asm volatile("s_waitcnt lgkmcnt(" #n ")" ::: "memory")
; #define PG8_BAR __builtin_amdgcn_s_barrier()
; #define PG8_SCHED __builtin_amdgcn_sched_barrier(0)
; template <class Epi>
; __device__ __forceinline__ void gemm_phase(LAS unsigned char* lds, const Gemm g, const StaticOrder& S, const Epi& E) {
;     ...
;             PG8_LDB(B0, 1, 0); PG8_LDB(B1, 1, 1); PG8_SCHED; PG8_LDA(At, 1, 0); PG8_STAGE(PG8_SA(0, 1), a2 + hstepA, voffA);
;             PG8_WAIT_V(8); PG8_WAIT_L(0); PG8_BAR; PG8_MMA(0, 0, At, B0); PG8_MMA(0, 1, At, B1); PG8_BAR; PG8_SCHED;
	s_add_i32 s89, 0, 0x18000
	s_add_i32 s90, 0, 0x1c000
	v_add_u32_e32 v158, s89, v163
	v_add_u32_e32 v167, s90, v163
	ds_read_b128 v[146:149], v158
	ds_read_b128 v[150:153], v158 offset:1024
	ds_read_b128 v[154:157], v158 offset:2048
	ds_read_b128 v[158:161], v158 offset:3072
	ds_read_b128 v[168:171], v167
	ds_read_b128 v[172:175], v167 offset:1024
	ds_read_b128 v[176:179], v167 offset:2048
	ds_read_b128 v[180:183], v167 offset:3072
	s_add_u32 s42, s42, 0x40000
	s_addc_u32 s43, s43, 0
	s_mov_b32 m0, s31
	v_lshl_add_u64 v[226:227], s[42:43], 0, v[128:129]
	ds_read_b128 v[184:187], v166 offset:32768
	ds_read_b128 v[188:191], v166 offset:33792
	ds_read_b128 v[196:199], v166 offset:34816
	ds_read_b128 v[200:203], v166 offset:35840
	ds_read_b128 v[204:207], v166 offset:36864
	ds_read_b128 v[208:211], v166 offset:37888
	ds_read_b128 v[212:215], v166 offset:38912
	ds_read_b128 v[216:219], v166 offset:39936
	global_load_lds_dwordx4 v[226:227], off
	v_lshl_add_u64 v[226:227], s[42:43], 0, v[132:133]
	s_mov_b32 m0, s35
	s_nop 0
	global_load_lds_dwordx4 v[226:227], off
	s_waitcnt vmcnt(8)
	s_waitcnt lgkmcnt(0)
	s_barrier
	s_setprio 1
	s_waitcnt lgkmcnt(0)
	v_mfma_f32_16x16x32_bf16 v[124:127], v[146:149], v[184:187], v[124:127]
	v_mfma_f32_16x16x32_bf16 v[116:119], v[154:157], v[184:187], v[116:119]
	v_mfma_f32_16x16x32_bf16 v[108:111], v[146:149], v[196:199], v[108:111]
	v_mfma_f32_16x16x32_bf16 v[100:103], v[154:157], v[196:199], v[100:103]
	v_mfma_f32_16x16x32_bf16 v[92:95], v[146:149], v[204:207], v[92:95]
	v_mfma_f32_16x16x32_bf16 v[84:87], v[154:157], v[204:207], v[84:87]
	v_mfma_f32_16x16x32_bf16 v[76:79], v[146:149], v[212:215], v[76:79]
	v_mfma_f32_16x16x32_bf16 v[68:71], v[154:157], v[212:215], v[68:71]
	v_mfma_f32_16x16x32_bf16 v[124:127], v[150:153], v[188:191], v[124:127]
	v_mfma_f32_16x16x32_bf16 v[116:119], v[158:161], v[188:191], v[116:119]
	v_mfma_f32_16x16x32_bf16 v[108:111], v[150:153], v[200:203], v[108:111]
	v_mfma_f32_16x16x32_bf16 v[100:103], v[158:161], v[200:203], v[100:103]
	v_mfma_f32_16x16x32_bf16 v[92:95], v[150:153], v[208:211], v[92:95]
	v_mfma_f32_16x16x32_bf16 v[84:87], v[158:161], v[208:211], v[84:87]
	v_mfma_f32_16x16x32_bf16 v[76:79], v[150:153], v[216:219], v[76:79]
	v_mfma_f32_16x16x32_bf16 v[68:71], v[158:161], v[216:219], v[68:71]
	s_setprio 0
	s_setprio 1
	v_mfma_f32_16x16x32_bf16 v[120:123], v[168:171], v[184:187], v[120:123]
	v_mfma_f32_16x16x32_bf16 v[112:115], v[176:179], v[184:187], v[112:115]
	v_mfma_f32_16x16x32_bf16 v[104:107], v[168:171], v[196:199], v[104:107]
	v_mfma_f32_16x16x32_bf16 v[96:99], v[176:179], v[196:199], v[96:99]
	v_mfma_f32_16x16x32_bf16 v[88:91], v[168:171], v[204:207], v[88:91]
	v_mfma_f32_16x16x32_bf16 v[80:83], v[176:179], v[204:207], v[80:83]
	v_mfma_f32_16x16x32_bf16 v[72:75], v[168:171], v[212:215], v[72:75]
	v_mfma_f32_16x16x32_bf16 v[64:67], v[176:179], v[212:215], v[64:67]
	v_mfma_f32_16x16x32_bf16 v[120:123], v[172:175], v[188:191], v[120:123]
	v_mfma_f32_16x16x32_bf16 v[112:115], v[180:183], v[188:191], v[112:115]
	v_mfma_f32_16x16x32_bf16 v[104:107], v[172:175], v[200:203], v[104:107]
	v_mfma_f32_16x16x32_bf16 v[96:99], v[180:183], v[200:203], v[96:99]
	v_mfma_f32_16x16x32_bf16 v[88:91], v[172:175], v[208:211], v[88:91]
	v_mfma_f32_16x16x32_bf16 v[80:83], v[180:183], v[208:211], v[80:83]
	v_mfma_f32_16x16x32_bf16 v[72:75], v[172:175], v[216:219], v[72:75]
	v_mfma_f32_16x16x32_bf16 v[64:67], v[180:183], v[216:219], v[64:67]
	s_setprio 0
	s_barrier
; #define PG8_STAGE(bufoff, gbase, voff) do { _Pragma("unroll") for (int _i = 0; _i < 2; ++_i) \
;         __builtin_amdgcn_global_load_lds((const unsigned*)((const char*)(gbase) + (voff)[_i]), (LAS unsigned*)(lds + (bufoff) + ldsw + _i * 8192), 16, 0, 0); } while (0)
; #define PG8_LDA(dst, b, h) do { _Pragma("unroll") for (int m = 0; m < 4; ++m) _Pragma("unroll") for (int k = 0; k < 2; ++k) dst[m][k] = *(const LAS bf16x8*)(lds + PG8_SA(b, h) + aoff + m * 2048 + k * 1024); } while (0)
; #define PG8_MMA(ai, bj, At, Bt) do { __builtin_amdgcn_s_setprio(1); _Pragma("unroll") for (int m = 0; m < 4; ++m) _Pragma("unroll") for (int n = 0; n < 2; ++n) _Pragma("unroll") for (int k = 0; k < 2; ++k) \
;         acc[ai][bj][m][n] = __builtin_amdgcn_mfma_f32_16x16x32_bf16(Bt[n][k], At[m][k], acc[ai][bj][m][n], 0, 0, 0); __builtin_amdgcn_s_setprio(0); } while (0)
; #define PG8_WAIT_V(n) asm volatile("s_waitcnt vmcnt(" #n ")" ::: "memory")
; #define PG8_WAIT_L(n) asm volatile("s_waitcnt lgkmcnt(" #n ")" ::: "memory")
; #define PG8_BAR __builtin_amdgcn_s_barrier()
; #define PG8_SCHED __builtin_amdgcn_sched_barrier(0)
; template <class Epi>
; __device__ __forceinline__ void gemm_phase(LAS unsigned char* lds, const Gemm g, const StaticOrder& S, const Epi& E) {
;     ...
;         for (int t = hf * nth; t < (hf + 1) * nth; t += 2) {
;     ...
;             PG8_LDA(At, 1, 1); PG8_STAGE(PG8_SB(1, 0), b3, voffB); PG8_STAGE(PG8_SB(1, 1), b3 + hstepB, voffB); PG8_STAGE(PG8_SA(1, 0), a3, voffA);
;             PG8_WAIT_V(8); PG8_WAIT_L(0); PG8_BAR; PG8_MMA(1, 0, At, B0); PG8_MMA(1, 1, At, B1); PG8_BAR; PG8_SCHED;
	s_add_i32 s42, s89, s3
	v_lshl_add_u64 v[192:193], v[192:193], 0, s[22:23]
	s_mov_b32 m0, s42
	ds_read_b128 v[184:187], v166 offset:49152
	ds_read_b128 v[188:191], v166 offset:50176
	ds_read_b128 v[196:199], v166 offset:51200
	ds_read_b128 v[200:203], v166 offset:52224
	ds_read_b128 v[204:207], v166 offset:53248
	ds_read_b128 v[208:211], v166 offset:54272
	ds_read_b128 v[212:215], v166 offset:55296
	ds_read_b128 v[216:219], v166 offset:56320
	global_load_lds_dwordx4 v[192:193], off
	s_add_i32 m0, s42, 0x2000
	s_add_u32 s42, s86, 0x40080
	v_lshl_add_u64 v[192:193], v[220:221], 0, s[22:23]
	s_addc_u32 s43, s87, 0
	s_add_i32 s86, s90, s3
	global_load_lds_dwordx4 v[192:193], off
	v_lshl_add_u64 v[192:193], s[42:43], 0, v[130:131]
	s_mov_b32 m0, s86
	s_nop 0
	global_load_lds_dwordx4 v[192:193], off
	v_lshl_add_u64 v[192:193], s[42:43], 0, v[134:135]
	s_add_i32 m0, s86, 0x2000
	s_nop 0
	global_load_lds_dwordx4 v[192:193], off
	v_lshl_add_u64 v[192:193], v[222:223], 0, s[22:23]
	s_mov_b32 m0, s37
	s_nop 0
	global_load_lds_dwordx4 v[192:193], off
	v_lshl_add_u64 v[192:193], v[224:225], 0, s[22:23]
	s_mov_b32 m0, s51
	s_nop 0
	global_load_lds_dwordx4 v[192:193], off
	s_waitcnt vmcnt(8)
	s_waitcnt lgkmcnt(0)
	s_barrier
	s_setprio 1
	s_waitcnt lgkmcnt(0)
	v_mfma_f32_16x16x32_bf16 v[60:63], v[146:149], v[184:187], v[60:63]
	v_mfma_f32_16x16x32_bf16 v[52:55], v[154:157], v[184:187], v[52:55]
	v_mfma_f32_16x16x32_bf16 v[44:47], v[146:149], v[196:199], v[44:47]
	v_mfma_f32_16x16x32_bf16 v[36:39], v[154:157], v[196:199], v[36:39]
	v_mfma_f32_16x16x32_bf16 v[28:31], v[146:149], v[204:207], v[28:31]
	v_mfma_f32_16x16x32_bf16 v[20:23], v[154:157], v[204:207], v[20:23]
	v_mfma_f32_16x16x32_bf16 v[12:15], v[146:149], v[212:215], v[12:15]
	v_mfma_f32_16x16x32_bf16 v[4:7], v[154:157], v[212:215], v[4:7]
	v_mfma_f32_16x16x32_bf16 v[60:63], v[150:153], v[188:191], v[60:63]
	v_mfma_f32_16x16x32_bf16 v[52:55], v[158:161], v[188:191], v[52:55]
	v_mfma_f32_16x16x32_bf16 v[44:47], v[150:153], v[200:203], v[44:47]
	v_mfma_f32_16x16x32_bf16 v[36:39], v[158:161], v[200:203], v[36:39]
	v_mfma_f32_16x16x32_bf16 v[28:31], v[150:153], v[208:211], v[28:31]
	v_mfma_f32_16x16x32_bf16 v[20:23], v[158:161], v[208:211], v[20:23]
	v_mfma_f32_16x16x32_bf16 v[12:15], v[150:153], v[216:219], v[12:15]
	v_mfma_f32_16x16x32_bf16 v[4:7], v[158:161], v[216:219], v[4:7]
	s_setprio 0
	s_setprio 1
	v_mfma_f32_16x16x32_bf16 v[56:59], v[168:171], v[184:187], v[56:59]
	v_mfma_f32_16x16x32_bf16 v[48:51], v[176:179], v[184:187], v[48:51]
	v_mfma_f32_16x16x32_bf16 v[40:43], v[168:171], v[196:199], v[40:43]
	v_mfma_f32_16x16x32_bf16 v[32:35], v[176:179], v[196:199], v[32:35]
	v_mfma_f32_16x16x32_bf16 v[24:27], v[168:171], v[204:207], v[24:27]
	v_mfma_f32_16x16x32_bf16 v[16:19], v[176:179], v[204:207], v[16:19]
	v_mfma_f32_16x16x32_bf16 v[8:11], v[168:171], v[212:215], v[8:11]
	v_mfma_f32_16x16x32_bf16 v[0:3], v[176:179], v[212:215], v[0:3]
	v_mfma_f32_16x16x32_bf16 v[56:59], v[172:175], v[188:191], v[56:59]
	v_mfma_f32_16x16x32_bf16 v[48:51], v[180:183], v[188:191], v[48:51]
	v_mfma_f32_16x16x32_bf16 v[40:43], v[172:175], v[200:203], v[40:43]
	v_mfma_f32_16x16x32_bf16 v[32:35], v[180:183], v[200:203], v[32:35]
	v_mfma_f32_16x16x32_bf16 v[24:27], v[172:175], v[208:211], v[24:27]
	v_mfma_f32_16x16x32_bf16 v[16:19], v[180:183], v[208:211], v[16:19]
	v_mfma_f32_16x16x32_bf16 v[8:11], v[172:175], v[216:219], v[8:11]
	v_mfma_f32_16x16x32_bf16 v[0:3], v[180:183], v[216:219], v[0:3]
	s_setprio 0
	s_barrier
	s_add_i32 s88, s88, 2
	s_add_u32 s8, s8, 0x100
	s_addc_u32 s9, s9, 0
	s_add_u32 s77, s77, 0x100
	s_addc_u32 s79, s79, 0

; #define LAS __attribute__((address_space(3)))
; __device__ __forceinline__ void phase_gla_pre(const Params& P, LAS unsigned char* lds, bool dry) {
;     ...
;     const int te = tid >> 3, kc = tid & 7;
;     u32x4 rq[2], rk[2]; f32x4 rl = (f32x4){0.f, 0.f, 0.f, 0.f};
;     int item = blockIdx.x;
;     if (item < 2048) {
;         const int bh = item >> 6, row0 = (bh >> 2) * SEQ + (item & 63) * 64; const bf16_t* p_ = PJ + ((size_t)bh * SEQ + (item & 63) * 64 + te) * 128 + 16 * kc;
;         rq[0] = *(const u32x4*)(p_ + T_Q); rq[1] = *(const u32x4*)(p_ + T_Q + 8); rk[0] = *(const u32x4*)(p_ + T_K); rk[1] = *(const u32x4*)(p_ + T_K + 8);
;         if (tid < 256) rl = *(const f32x4*)(LR + (size_t)row0 * 16 + 4 * tid);
;     }
;     for (; item < 2048; item += gridDim.x) {
;         const int bh = item >> 6, c = item & 63, b = bh >> 2, h = bh & 3, row0 = b * SEQ + c * 64;
;         if (tid < 256) *(LAS f32x4*)(Llr + 4 * tid) = rl;
;         bf16x8 bhi = (bf16x8){0, 0, 0, 0, 0, 0, 0, 0}, blo = bhi;
.LBB0_473:
	s_or_b64 exec, exec, s[4:5]
	s_mov_b32 s98, 0
	s_add_u32 s50, s70, 0x1a00000
	s_addc_u32 s51, s71, 0
	s_add_u32 s72, s70, 0x1e000000
	s_addc_u32 s73, s71, 0
	v_mov_b32_e32 v24, v194
	s_cmpk_gt_i32 s2, 0x7ff
	s_cbranch_scc1 .LBB0_502
	s_ashr_i32 s4, s2, 6
	s_lshl_b32 s1, s2, 6
	s_ashr_i32 s5, s4, 31
	v_ashrrev_i32_e32 v48, 3, v24
	s_and_b32 s3, s1, 0xfc0
	s_lshl_b64 s[4:5], s[4:5], 12
	s_or_b32 s4, s4, s3
	v_ashrrev_i32_e32 v49, 31, v48
	v_lshl_add_u64 v[0:1], s[4:5], 0, v[48:49]
	v_lshlrev_b64 v[0:1], 8, v[0:1]
	v_and_b32_e32 v25, 7, v24
	v_lshl_add_u64 v[2:3], s[44:45], 0, v[0:1]
	v_mov_b32_e32 v0, 0
	v_lshlrev_b32_e32 v20, 5, v25
	v_mov_b32_e32 v21, v0
	v_lshl_add_u64 v[2:3], v[2:3], 0, v[20:21]
	s_mov_b64 s[4:5], 0x8000000
	v_lshl_add_u64 v[12:13], v[2:3], 0, s[4:5]
	s_brev_b32 s4, 16
	v_add_co_u32_e32 v14, vcc, s4, v2
	s_mov_b64 s[4:5], 0xa000000
	s_nop 0
	v_addc_co_u32_e32 v15, vcc, 0, v3, vcc
	v_lshl_add_u64 v[16:17], v[2:3], 0, s[4:5]
	v_add_co_u32_e32 v2, vcc, 0xa000000, v2
	global_load_dwordx4 v[4:7], v[14:15], off
	global_load_dwordx4 v[8:11], v[12:13], off offset:16
	v_addc_co_u32_e32 v3, vcc, 0, v3, vcc
	global_load_dwordx4 v[12:15], v[2:3], off
	s_nop 0
	global_load_dwordx4 v[16:19], v[16:17], off offset:16
	s_movk_i32 s4, 0x100
	s_movk_i32 s6, 0xff
	v_lshlrev_b32_e32 v21, 4, v25
	v_cmp_gt_i32_e64 s[4:5], s4, v24
	v_cmp_lt_i32_e32 vcc, s6, v24
	v_lshlrev_b32_e32 v22, 2, v24
	s_and_saveexec_b64 s[6:7], vcc
	s_xor_b64 s[6:7], exec, s[6:7]
	v_mov_b32_e32 v23, v0
	s_or_saveexec_b64 s[6:7], s[6:7]
	s_mov_b32 s75, 0
	v_mov_b32_e32 v1, v0
	v_mov_b32_e32 v2, v0
	v_mov_b32_e32 v3, v0
	s_xor_b64 exec, exec, s[6:7]
	s_cbranch_execz .LBB0_478
	s_lshl_b32 s8, s2, 4
	s_and_b32 s8, s8, 0xfffff000
	s_or_b32 s8, s8, s3
	s_ashr_i32 s9, s8, 31
	s_lshl_b64 s[8:9], s[8:9], 6
	s_add_u32 s8, s76, s8
	s_addc_u32 s9, s77, s9
	v_ashrrev_i32_e32 v23, 31, v22
	v_lshl_add_u64 v[0:1], v[22:23], 2, s[8:9]
	global_load_dwordx4 v[0:3], v[0:1], off

; __device__ __forceinline__ float bf2f(unsigned b) { return __uint_as_float(b << 16); }
; __device__ __forceinline__ unsigned f2bf(float f) { unsigned u = __float_as_uint(f); return (u + 0x7fffu + ((u >> 16) & 1u)) >> 16; }
; __device__ __forceinline__ void split8(const f32x4 x0, const f32x4 x1, bf16x8& hi, bf16x8& lo) {
; #pragma unroll
;     for (int j = 0; j < 8; ++j) { const float x = j < 4 ? x0[j & 3] : x1[j & 3]; const unsigned h = f2bf(x); const unsigned l = f2bf(x - bf2f(h)); hi[j] = (short)h; lo[j] = (short)l; }
; }
; __device__ __forceinline__ void phase_gla_pre(const Params& P, LAS unsigned char* lds, bool dry) {
;     ...
;         bf16x8 bhi = (bf16x8){0, 0, 0, 0, 0, 0, 0, 0}, blo = bhi;
;         if (g < 2) { f32x4 w0, w1;
; #pragma unroll
;             for (int j = 0; j < 4; ++j) { w0[j] = P.w_gate_up[(8 * g + j) * 512 + h * 128 + 16 * w + fr]; w1[j] = P.w_gate_up[(8 * g + 4 + j) * 512 + h * 128 + 16 * w + fr]; }
;             split8(w0, w1, bhi, blo); }
;         const float bg = P.b_gate_up[h * 128 + 16 * w + fr];
.LBB0_482:
	s_or_b64 exec, exec, s[36:37]
	s_ashr_i32 s82, s80, 6
	s_lshl_b32 s36, s82, 7
	s_and_b32 s42, s36, 0x180
	v_mov_b32_e32 v32, 0
	v_mov_b32_e32 v24, 0
	v_mov_b32_e32 v25, 0
	v_mov_b32_e32 v26, 0
	v_mov_b32_e32 v27, 0
	v_mov_b32_e32 v20, 0
	v_mov_b32_e32 v21, 0
	v_mov_b32_e32 v22, 0
	v_mov_b32_e32 v23, 0
	s_cmp_lg_u32 s98, 0
	s_cbranch_scc1 .Lp2_hoisted
	s_and_saveexec_b64 s[36:37], s[6:7]
	s_cbranch_execz .LBB0_484
	v_or_b32_e32 v28, s42, v80
	v_or_b32_e32 v26, 0x400, v28
	v_add_u32_e32 v20, v28, v81
	v_add_u32_e32 v24, v26, v81
	v_add_u32_e32 v26, v26, v82
	v_or_b32_e32 v30, 0x600, v28
	v_ashrrev_i32_e32 v21, 31, v20
	v_add_u32_e32 v22, v28, v82
	v_ashrrev_i32_e32 v25, 31, v24
	v_ashrrev_i32_e32 v27, 31, v26
	v_add_u32_e32 v28, v30, v81
	v_add_u32_e32 v30, v30, v82
	v_lshl_add_u64 v[20:21], v[20:21], 2, s[54:55]
	v_ashrrev_i32_e32 v23, 31, v22
	v_lshl_add_u64 v[24:25], v[24:25], 2, s[54:55]
	v_lshl_add_u64 v[26:27], v[26:27], 2, s[54:55]
	v_ashrrev_i32_e32 v29, 31, v28
	v_ashrrev_i32_e32 v31, 31, v30
	v_lshl_add_u64 v[22:23], v[22:23], 2, s[54:55]
	v_lshl_add_u64 v[28:29], v[28:29], 2, s[54:55]
	v_lshl_add_u64 v[30:31], v[30:31], 2, s[54:55]
	global_load_dword v34, v[20:21], off
	global_load_dword v36, v[22:23], off
	global_load_dword v37, v[22:23], off offset:2048
	s_nop 0
	global_load_dword v24, v[24:25], off
	s_nop 0
	global_load_dword v26, v[26:27], off
	s_nop 0
	global_load_dword v25, v[28:29], off
	global_load_dword v27, v[30:31], off
	global_load_dword v35, v[20:21], off offset:2048
	s_waitcnt vmcnt(7)
	v_and_b32_sdwa v20, v34, v95 dst_sel:DWORD dst_unused:UNUSED_PAD src0_sel:WORD_1 src1_sel:DWORD
	s_waitcnt vmcnt(6)
	v_and_b32_sdwa v22, v36, v95 dst_sel:DWORD dst_unused:UNUSED_PAD src0_sel:WORD_1 src1_sel:DWORD
	s_waitcnt vmcnt(5)
	v_and_b32_sdwa v21, v37, v95 dst_sel:DWORD dst_unused:UNUSED_PAD src0_sel:WORD_1 src1_sel:DWORD
	v_add3_u32 v33, v34, v20, s86
	s_waitcnt vmcnt(4)
	v_and_b32_sdwa v29, v24, v95 dst_sel:DWORD dst_unused:UNUSED_PAD src0_sel:WORD_1 src1_sel:DWORD
	s_waitcnt vmcnt(2)
	v_and_b32_sdwa v20, v25, v95 dst_sel:DWORD dst_unused:UNUSED_PAD src0_sel:WORD_1 src1_sel:DWORD
	s_waitcnt vmcnt(1)
	v_and_b32_sdwa v31, v27, v95 dst_sel:DWORD dst_unused:UNUSED_PAD src0_sel:WORD_1 src1_sel:DWORD
	s_waitcnt vmcnt(0)
	v_and_b32_sdwa v23, v35, v95 dst_sel:DWORD dst_unused:UNUSED_PAD src0_sel:WORD_1 src1_sel:DWORD
	v_and_b32_sdwa v38, v26, v95 dst_sel:DWORD dst_unused:UNUSED_PAD src0_sel:WORD_1 src1_sel:DWORD
	v_add3_u32 v30, v37, v21, s86
	v_add3_u32 v22, v36, v22, s86
	v_add3_u32 v23, v35, v23, s86
	v_add3_u32 v40, v25, v20, s86
	v_add3_u32 v41, v24, v29, s86
	v_add3_u32 v42, v27, v31, s86
	v_add3_u32 v43, v26, v38, s86
	v_and_b32_e32 v28, 0xffff0000, v33
	v_and_b32_e32 v21, 0xffff0000, v30
	v_and_b32_e32 v20, 0xffff0000, v22
	v_cvt_pk_bf16_f32 v22, v36, v37
	v_and_b32_e32 v29, 0xffff0000, v23
	v_and_b32_e32 v31, 0xffff0000, v40
	v_and_b32_e32 v30, 0xffff0000, v41
	v_and_b32_e32 v39, 0xffff0000, v42
	v_and_b32_e32 v38, 0xffff0000, v43
	v_pk_add_f32 v[36:37], v[36:37], v[20:21] neg_lo:[0,1] neg_hi:[0,1]
	v_pk_add_f32 v[28:29], v[34:35], v[28:29] neg_lo:[0,1] neg_hi:[0,1]
	v_pk_add_f32 v[24:25], v[24:25], v[30:31] neg_lo:[0,1] neg_hi:[0,1]
	v_pk_add_f32 v[26:27], v[26:27], v[38:39] neg_lo:[0,1] neg_hi:[0,1]
	v_cvt_pk_bf16_f32 v20, v34, v35
	v_bfe_u32 v23, v37, 16, 1
	v_bfe_u32 v30, v36, 16, 1
	v_bfe_u32 v31, v29, 16, 1
	v_bfe_u32 v33, v28, 16, 1
	v_bfe_u32 v34, v25, 16, 1
	v_bfe_u32 v35, v24, 16, 1
	v_bfe_u32 v38, v27, 16, 1
	v_bfe_u32 v39, v26, 16, 1
	v_add3_u32 v30, v36, v30, s86
	v_add3_u32 v23, v37, v23, s86
	v_add3_u32 v36, v26, v39, s86
	v_add3_u32 v27, v27, v38, s86
	v_add3_u32 v35, v24, v35, s86
	v_add3_u32 v25, v25, v34, s86
	v_add3_u32 v24, v28, v33, s86
	v_add3_u32 v28, v29, v31, s86
	v_perm_b32 v21, v40, v41, s88
	v_perm_b32 v26, v23, v30, s88
	v_perm_b32 v24, v28, v24, s88
	v_perm_b32 v25, v25, v35, s88
	v_perm_b32 v27, v27, v36, s88
	v_perm_b32 v23, v42, v43, s88
.LBB0_484:
	s_or_b64 exec, exec, s[36:37]
	v_add_u32_e32 v28, s42, v81
	v_ashrrev_i32_e32 v29, 31, v28
	v_lshl_add_u64 v[28:29], v[28:29], 2, s[56:57]
	global_load_dword v28, v[28:29], off
	s_branch .Lp2_join
.Lp2_hoisted:
	v_mov_b32_e32 v20, v140
	v_mov_b32_e32 v21, v141
	v_mov_b32_e32 v22, v142
	v_mov_b32_e32 v23, v143
	v_mov_b32_e32 v24, v144
	v_mov_b32_e32 v25, v145
	v_mov_b32_e32 v26, v146
	v_mov_b32_e32 v27, v147
	v_mov_b32_e32 v28, v148
; #define LAS __attribute__((address_space(3)))
; __device__ __forceinline__ void phase_gla_pre(const Params& P, LAS unsigned char* lds, bool dry) {
;     ...
;         __syncthreads();
;         float run = 0.f;
; #pragma unroll
;         for (int tt = 0; tt < 4; ++tt) {
;             bf16x8 ahi = (bf16x8){0, 0, 0, 0, 0, 0, 0, 0}, alo = ahi;
;             if (g < 2) { const f32x4 l0 = *(const LAS f32x4*)(Llr + (16 * tt + fr) * 16 + 8 * g), l1 = *(const LAS f32x4*)(Llr + (16 * tt + fr) * 16 + 8 * g + 4); split8(l0, l1, ahi, alo); }
.Lp2_join:
	v_mov_b32_e32 v33, 0
	v_mov_b32_e32 v34, 0
	v_mov_b32_e32 v35, 0
	v_mov_b32_e32 v36, 0
	v_mov_b32_e32 v37, 0
	v_mov_b32_e32 v38, 0
	v_mov_b32_e32 v39, 0
	s_waitcnt lgkmcnt(0)
	s_barrier
	s_and_saveexec_b64 s[36:37], s[6:7]
	s_cbranch_execz .LBB0_486
	ds_read_b128 v[30:33], v96
	ds_read_b128 v[34:37], v96 offset:16
	s_waitcnt lgkmcnt(1)
	v_and_b32_sdwa v29, v31, v95 dst_sel:DWORD dst_unused:UNUSED_PAD src0_sel:WORD_1 src1_sel:DWORD
	v_and_b32_sdwa v38, v30, v95 dst_sel:DWORD dst_unused:UNUSED_PAD src0_sel:WORD_1 src1_sel:DWORD
	v_add3_u32 v29, v31, v29, s86
	v_add3_u32 v40, v30, v38, s86
	v_and_b32_e32 v39, 0xffff0000, v29
	v_and_b32_e32 v38, 0xffff0000, v40
	v_pk_add_f32 v[30:31], v[30:31], v[38:39] neg_lo:[0,1] neg_hi:[0,1]
	v_and_b32_sdwa v38, v33, v95 dst_sel:DWORD dst_unused:UNUSED_PAD src0_sel:WORD_1 src1_sel:DWORD
	v_and_b32_sdwa v39, v32, v95 dst_sel:DWORD dst_unused:UNUSED_PAD src0_sel:WORD_1 src1_sel:DWORD
	v_add3_u32 v41, v33, v38, s86
	v_add3_u32 v42, v32, v39, s86
	v_and_b32_e32 v39, 0xffff0000, v41
	v_and_b32_e32 v38, 0xffff0000, v42
	v_pk_add_f32 v[32:33], v[32:33], v[38:39] neg_lo:[0,1] neg_hi:[0,1]
	s_waitcnt lgkmcnt(0)
	v_and_b32_sdwa v38, v35, v95 dst_sel:DWORD dst_unused:UNUSED_PAD src0_sel:WORD_1 src1_sel:DWORD
	v_and_b32_sdwa v39, v34, v95 dst_sel:DWORD dst_unused:UNUSED_PAD src0_sel:WORD_1 src1_sel:DWORD
	v_add3_u32 v43, v35, v38, s86
	v_add3_u32 v44, v34, v39, s86
	v_and_b32_e32 v39, 0xffff0000, v43
	v_and_b32_e32 v38, 0xffff0000, v44
	v_pk_add_f32 v[34:35], v[34:35], v[38:39] neg_lo:[0,1] neg_hi:[0,1]
	v_and_b32_sdwa v38, v37, v95 dst_sel:DWORD dst_unused:UNUSED_PAD src0_sel:WORD_1 src1_sel:DWORD
	v_and_b32_sdwa v39, v36, v95 dst_sel:DWORD dst_unused:UNUSED_PAD src0_sel:WORD_1 src1_sel:DWORD
	v_add3_u32 v45, v37, v38, s86
	v_add3_u32 v46, v36, v39, s86
	v_and_b32_e32 v39, 0xffff0000, v45
	v_and_b32_e32 v38, 0xffff0000, v46
	v_pk_add_f32 v[36:37], v[36:37], v[38:39] neg_lo:[0,1] neg_hi:[0,1]
	v_bfe_u32 v38, v31, 16, 1
	v_bfe_u32 v39, v30, 16, 1
	v_bfe_u32 v47, v33, 16, 1
	v_bfe_u32 v60, v32, 16, 1
	v_bfe_u32 v61, v35, 16, 1
	v_bfe_u32 v62, v34, 16, 1
	v_bfe_u32 v63, v37, 16, 1
	v_bfe_u32 v64, v36, 16, 1
	v_add3_u32 v36, v36, v64, s86
	v_add3_u32 v37, v37, v63, s86
	v_add3_u32 v34, v34, v62, s86
	v_add3_u32 v35, v35, v61, s86
	v_add3_u32 v60, v32, v60, s86
	v_add3_u32 v33, v33, v47, s86
	v_add3_u32 v30, v30, v39, s86
	v_add3_u32 v31, v31, v38, s86
	v_perm_b32 v32, v31, v30, s88
	v_perm_b32 v33, v33, v60, s88
	v_perm_b32 v34, v35, v34, s88
	v_perm_b32 v35, v37, v36, s88
	v_perm_b32 v36, v29, v40, s88
	v_perm_b32 v37, v41, v42, s88
	v_perm_b32 v38, v43, v44, s88
	v_perm_b32 v39, v45, v46, s88
; #define LAS __attribute__((address_space(3)))
; __device__ __forceinline__ void phase_gla_pre(const Params& P, LAS unsigned char* lds, bool dry) {
;     ...
;         for (int tt = 0; tt < 4; ++tt) {
;             bf16x8 ahi = (bf16x8){0, 0, 0, 0, 0, 0, 0, 0}, alo = ahi;
;             if (g < 2) { const f32x4 l0 = *(const LAS f32x4*)(Llr + (16 * tt + fr) * 16 + 8 * g), l1 = *(const LAS f32x4*)(Llr + (16 * tt + fr) * 16 + 8 * g + 4); split8(l0, l1, ahi, alo); }
;             f32x4 acc = (f32x4){bg, bg, bg, bg};
;             acc = __builtin_amdgcn_mfma_f32_16x16x32_bf16(alo, bhi, acc, 0, 0, 0); acc = __builtin_amdgcn_mfma_f32_16x16x32_bf16(ahi, blo, acc, 0, 0, 0); acc = __builtin_amdgcn_mfma_f32_16x16x32_bf16(ahi, bhi, acc, 0, 0, 0);
;             float pr[4];
; #pragma unroll
;             for (int r = 0; r < 4; ++r) { const float lg = acc[r]; const float ls = fminf(lg, 0.f) - __logf(1.0f + __expf(-fabsf(lg))); pr[r] = ls * (1.0f / 16.0f) + (r ? pr[r - 1] : 0.f); }
;             const float T = pr[3];
;             const float u1 = __shfl_up(T, 16), s1 = T + (g >= 1 ? u1 : 0.f);
;             const float u2 = __shfl_up(s1, 32), s2 = s1 + (g >= 2 ? u2 : 0.f);
;             const float base = run + (s2 - T); run += __shfl(s2, 48 + fr);
; #pragma unroll
;             for (int r = 0; r < 4; ++r) *(LAS float*)(Lb + (16 * tt + 4 * g + r) * BP + (16 * w + fr) * 4) = base + pr[r];
.LBB0_486:
	s_or_b64 exec, exec, s[36:37]
	s_waitcnt vmcnt(0)
	v_mov_b32_e32 v140, v20
	v_mov_b32_e32 v141, v21
	v_mov_b32_e32 v142, v22
	v_mov_b32_e32 v143, v23
	v_mov_b32_e32 v144, v24
	v_mov_b32_e32 v145, v25
	v_mov_b32_e32 v146, v26
	v_mov_b32_e32 v147, v27
	v_mov_b32_e32 v148, v28
	s_and_b32 s98, s38, 0xff
	s_cselect_b32 s98, 0, 1
	v_mov_b32_e32 v29, v28
	v_mov_b32_e32 v30, v28
	v_mov_b32_e32 v31, v28
	v_mov_b32_e32 v40, 0
	v_mov_b32_e32 v41, 0
	v_mfma_f32_16x16x32_bf16 v[32:35], v[32:35], v[20:23], v[28:31]
	v_mfma_f32_16x16x32_bf16 v[32:35], v[36:39], v[24:27], v[32:35]
	v_mfma_f32_16x16x32_bf16 v[32:35], v[36:39], v[20:23], v[32:35]
	s_nop 7
	v_max_f32_e32 v36, v32, v32
	v_mul_f32_e64 v32, |v32|, s89
	v_exp_f32_e32 v32, v32
	v_mul_f32_e64 v37, |v33|, s89
	v_exp_f32_e32 v37, v37
	v_min_f32_e32 v36, 0, v36
	v_add_f32_e32 v32, 1.0, v32
	v_cmp_gt_f32_e32 vcc, s90, v32
	v_add_f32_e32 v37, 1.0, v37
	v_cmp_gt_f32_e64 s[36:37], s90, v37
	v_cndmask_b32_e64 v38, 0, 32, vcc
	v_ldexp_f32 v32, v32, v38
	v_log_f32_e32 v32, v32
	v_cndmask_b32_e64 v39, 0, 32, s[36:37]
	v_ldexp_f32 v37, v37, v39
	v_log_f32_e32 v37, v37
	v_mul_f32_e32 v39, 0x3f317217, v32
	v_fma_f32 v39, v32, s91, -v39
	v_fmac_f32_e32 v39, 0x3377d1cf, v32
	v_cndmask_b32_e32 v38, 0, v97, vcc
	v_fmac_f32_e32 v39, 0x3f317217, v32
	v_cmp_lt_f32_e64 vcc, |v32|, s92
	v_max_f32_e32 v33, v33, v33
	v_min_f32_e32 v33, 0, v33
	v_cndmask_b32_e32 v32, v32, v39, vcc
	v_sub_f32_e32 v32, v32, v38
	v_sub_f32_e32 v32, v36, v32
	v_mul_f32_e32 v36, 0x3f317217, v37
	v_fma_f32 v36, v37, s91, -v36
	v_fmac_f32_e32 v36, 0x3377d1cf, v37
	v_fmac_f32_e32 v36, 0x3f317217, v37
	v_cmp_lt_f32_e64 vcc, |v37|, s92
	v_cndmask_b32_e64 v38, 0, v97, s[36:37]
	v_fma_f32 v32, v32, s93, 0
	v_cndmask_b32_e32 v36, v37, v36, vcc
	v_mul_f32_e64 v37, |v34|, s89
	v_exp_f32_e32 v37, v37
	v_sub_f32_e32 v36, v36, v38
	v_sub_f32_e32 v33, v33, v36
	v_mov_b32_e32 v39, 0
	v_add_f32_e32 v36, 1.0, v37
	v_cmp_gt_f32_e32 vcc, s90, v36
	s_nop 1
	v_cndmask_b32_e64 v37, 0, 32, vcc
	v_ldexp_f32 v36, v36, v37
	v_log_f32_e32 v36, v36
	v_fmamk_f32 v37, v33, 0x3d800000, v32
	v_max_f32_e32 v33, v34, v34
	v_cndmask_b32_e32 v38, 0, v97, vcc
	v_mul_f32_e32 v34, 0x3f317217, v36
	v_fma_f32 v34, v36, s91, -v34
	v_fmac_f32_e32 v34, 0x3377d1cf, v36
	v_fmac_f32_e32 v34, 0x3f317217, v36
	v_cmp_lt_f32_e64 s[36:37], |v36|, s92
	v_min_f32_e32 v33, 0, v33
	s_nop 0
	v_cndmask_b32_e64 v34, v36, v34, s[36:37]
	v_mul_f32_e64 v36, |v35|, s89
	v_exp_f32_e32 v36, v36
	v_sub_f32_e32 v34, v34, v38
	v_sub_f32_e32 v33, v33, v34
	v_add_u32_e32 v38, 0x8800, v98
	v_add_f32_e32 v34, 1.0, v36
	v_cmp_gt_f32_e32 vcc, s90, v34
	s_nop 1
	v_cndmask_b32_e64 v36, 0, 32, vcc
	v_ldexp_f32 v34, v34, v36
	v_log_f32_e32 v34, v34
	v_fmamk_f32 v36, v33, 0x3d800000, v37
	v_max_f32_e32 v33, v35, v35
	v_min_f32_e32 v33, 0, v33
	v_mul_f32_e32 v35, 0x3f317217, v34
	v_fma_f32 v35, v34, s91, -v35
	v_fmac_f32_e32 v35, 0x3377d1cf, v34
	v_fmac_f32_e32 v35, 0x3f317217, v34
	v_cmp_lt_f32_e64 s[36:37], |v34|, s92
	s_nop 1
	v_cndmask_b32_e64 v34, v34, v35, s[36:37]
	v_cndmask_b32_e32 v35, 0, v97, vcc
	v_sub_f32_e32 v34, v34, v35
	v_sub_f32_e32 v33, v33, v34
	v_fmamk_f32 v34, v33, 0x3d800000, v36
	ds_bpermute_b32 v33, v83, v34
	s_waitcnt lgkmcnt(0)
	v_cndmask_b32_e64 v33, v33, 0, s[8:9]
	v_add_f32_e32 v33, v33, v34
	ds_bpermute_b32 v35, v84, v33
	s_waitcnt lgkmcnt(0)
	v_cndmask_b32_e64 v35, 0, v35, s[10:11]
	v_add_f32_e32 v33, v35, v33
	v_sub_f32_e32 v35, v33, v34
	ds_bpermute_b32 v33, v85, v33
	v_add_f32_e32 v35, 0, v35
	v_add_f32_e32 v32, v32, v35
	v_add_f32_e32 v37, v37, v35
	ds_write2_b32 v38, v32, v37 offset1:132
	v_add_f32_e32 v32, v36, v35
	v_add_f32_e32 v34, v34, v35
	v_add_u32_e32 v35, 0x8c00, v98
	ds_write2_b32 v35, v32, v34 offset0:8 offset1:140
	v_mov_b32_e32 v32, 0
	v_mov_b32_e32 v34, 0
	v_mov_b32_e32 v35, 0
	v_mov_b32_e32 v36, 0
	v_mov_b32_e32 v37, 0
	v_mov_b32_e32 v38, 0
	s_and_saveexec_b64 s[36:37], s[6:7]
	s_cbranch_execz .LBB0_488
	ds_read_b128 v[34:37], v96 offset:1024
	ds_read_b128 v[38:41], v96 offset:1040
	s_waitcnt lgkmcnt(1)
	v_and_b32_sdwa v42, v35, v95 dst_sel:DWORD dst_unused:UNUSED_PAD src0_sel:WORD_1 src1_sel:DWORD
	v_and_b32_sdwa v43, v34, v95 dst_sel:DWORD dst_unused:UNUSED_PAD src0_sel:WORD_1 src1_sel:DWORD
	v_add3_u32 v44, v35, v42, s86
	v_add3_u32 v45, v34, v43, s86
	v_and_b32_e32 v43, 0xffff0000, v44
	v_and_b32_e32 v42, 0xffff0000, v45
	v_pk_add_f32 v[34:35], v[34:35], v[42:43] neg_lo:[0,1] neg_hi:[0,1]
	v_and_b32_sdwa v42, v37, v95 dst_sel:DWORD dst_unused:UNUSED_PAD src0_sel:WORD_1 src1_sel:DWORD
	v_and_b32_sdwa v43, v36, v95 dst_sel:DWORD dst_unused:UNUSED_PAD src0_sel:WORD_1 src1_sel:DWORD
	v_add3_u32 v46, v37, v42, s86
	v_add3_u32 v47, v36, v43, s86
	v_and_b32_e32 v43, 0xffff0000, v46
	v_and_b32_e32 v42, 0xffff0000, v47
	v_pk_add_f32 v[36:37], v[36:37], v[42:43] neg_lo:[0,1] neg_hi:[0,1]
	s_waitcnt lgkmcnt(0)
	v_and_b32_sdwa v42, v39, v95 dst_sel:DWORD dst_unused:UNUSED_PAD src0_sel:WORD_1 src1_sel:DWORD
	v_and_b32_sdwa v43, v38, v95 dst_sel:DWORD dst_unused:UNUSED_PAD src0_sel:WORD_1 src1_sel:DWORD
	v_add3_u32 v60, v39, v42, s86
	v_add3_u32 v61, v38, v43, s86
	v_and_b32_e32 v43, 0xffff0000, v60
	v_and_b32_e32 v42, 0xffff0000, v61
	v_pk_add_f32 v[38:39], v[38:39], v[42:43] neg_lo:[0,1] neg_hi:[0,1]
	v_and_b32_sdwa v42, v41, v95 dst_sel:DWORD dst_unused:UNUSED_PAD src0_sel:WORD_1 src1_sel:DWORD
	v_and_b32_sdwa v43, v40, v95 dst_sel:DWORD dst_unused:UNUSED_PAD src0_sel:WORD_1 src1_sel:DWORD
	v_add3_u32 v62, v41, v42, s86
	v_add3_u32 v63, v40, v43, s86
	v_and_b32_e32 v43, 0xffff0000, v62
	v_and_b32_e32 v42, 0xffff0000, v63
	v_pk_add_f32 v[40:41], v[40:41], v[42:43] neg_lo:[0,1] neg_hi:[0,1]
	v_bfe_u32 v42, v35, 16, 1
	v_bfe_u32 v43, v34, 16, 1
	v_bfe_u32 v64, v37, 16, 1
	v_bfe_u32 v65, v36, 16, 1
	v_bfe_u32 v66, v39, 16, 1
	v_bfe_u32 v67, v38, 16, 1
	v_bfe_u32 v68, v41, 16, 1
	v_bfe_u32 v69, v40, 16, 1
	v_add3_u32 v40, v40, v69, s86
	v_add3_u32 v41, v41, v68, s86
	v_add3_u32 v38, v38, v67, s86
	v_add3_u32 v39, v39, v66, s86
	v_add3_u32 v36, v36, v65, s86
	v_add3_u32 v37, v37, v64, s86
	v_add3_u32 v34, v34, v43, s86
	v_add3_u32 v35, v35, v42, s86
	v_perm_b32 v34, v35, v34, s88
	v_perm_b32 v35, v37, v36, s88
	v_perm_b32 v36, v39, v38, s88
	v_perm_b32 v37, v41, v40, s88
	v_perm_b32 v38, v44, v45, s88
	v_perm_b32 v39, v46, v47, s88
	v_perm_b32 v40, v60, v61, s88
	v_perm_b32 v41, v62, v63, s88

; #define LAS __attribute__((address_space(3)))
; __device__ __forceinline__ float bflo(unsigned w) { return __uint_as_float(w << 16); }
; __device__ __forceinline__ float bfhi(unsigned w) { return __uint_as_float(w & 0xffff0000u); }
; __device__ __forceinline__ void phase_gla_pre(const Params& P, LAS unsigned char* lds, bool dry) {
;     ...
;             acc = __builtin_amdgcn_mfma_f32_16x16x32_bf16(alo, bhi, acc, 0, 0, 0); acc = __builtin_amdgcn_mfma_f32_16x16x32_bf16(ahi, blo, acc, 0, 0, 0); acc = __builtin_amdgcn_mfma_f32_16x16x32_bf16(ahi, bhi, acc, 0, 0, 0);
;             float pr[4];
; #pragma unroll
;             for (int r = 0; r < 4; ++r) { const float lg = acc[r]; const float ls = fminf(lg, 0.f) - __logf(1.0f + __expf(-fabsf(lg))); pr[r] = ls * (1.0f / 16.0f) + (r ? pr[r - 1] : 0.f); }
;             const float T = pr[3];
;             const float u1 = __shfl_up(T, 16), s1 = T + (g >= 1 ? u1 : 0.f);
;             const float u2 = __shfl_up(s1, 32), s2 = s1 + (g >= 2 ? u2 : 0.f);
;             const float base = run + (s2 - T); run += __shfl(s2, 48 + fr);
; #pragma unroll
;             for (int r = 0; r < 4; ++r) *(LAS float*)(Lb + (16 * tt + 4 * g + r) * BP + (16 * w + fr) * 4) = base + pr[r];
;         }
;         __syncthreads();
;         {
;             f32x4 bb[4], bm[4], bl[4];
; #pragma unroll
;             for (int i = 0; i < 4; ++i) { bb[i] = *(const LAS f32x4*)(Lb + te * BP + (16 * kc + 4 * i) * 4); bm[i] = *(const LAS f32x4*)(Lb + 31 * BP + (16 * kc + 4 * i) * 4); bl[i] = *(const LAS f32x4*)(Lb + 63 * BP + (16 * kc + 4 * i) * 4); }
;             unsigned oqi[8], oki[8], oqd[8], oks[8];
; #pragma unroll
;             for (int e2 = 0; e2 < 8; ++e2) {
;                 const unsigned qw = e2 < 4 ? rq[0][e2] : rq[1][e2 - 4], kw = e2 < 4 ? rk[0][e2] : rk[1][e2 - 4];
;                 float vqi[2], vki[2], vqd[2], vks[2];
; #pragma unroll
;                 for (int hh = 0; hh < 2; ++hh) {
;                     const int e = 2 * e2 + hh; const float bv = bb[e >> 2][e & 3], bmv = bm[e >> 2][e & 3], blv = bl[e >> 2][e & 3];
;                     const float qv = hh ? bfhi(qw) : bflo(qw), kv = hh ? bfhi(kw) : bflo(kw);
;                     const float e1 = __expf(bv - bmv);
;                     vqi[hh] = qv * e1; vki[hh] = kv * __builtin_amdgcn_rcpf(e1); vqd[hh] = qv * __expf(bv); vks[hh] = kv * __expf(blv - bv);
.LBB0_492:
	s_or_b64 exec, exec, s[36:37]
	v_mfma_f32_16x16x32_bf16 v[28:31], v[32:35], v[20:23], v[28:31]
	v_and_b32_e32 v111, 0xffff0000, v5
	v_and_b32_e32 v110, 0xffff0000, v4
	v_and_b32_e32 v117, 0xffff0000, v13
	v_mfma_f32_16x16x32_bf16 v[24:27], v[36:39], v[24:27], v[28:31]
	v_and_b32_e32 v116, 0xffff0000, v12
	v_and_b32_e32 v121, 0xffff0000, v7
	v_and_b32_e32 v120, 0xffff0000, v6
	v_mfma_f32_16x16x32_bf16 v[20:23], v[36:39], v[20:23], v[24:27]
	v_and_b32_e32 v127, 0xffff0000, v17
	v_and_b32_e32 v126, 0xffff0000, v16
	v_lshlrev_b32_e32 v125, 16, v17
	v_lshlrev_b32_e32 v124, 16, v16
	v_lshlrev_b32_e32 v133, 16, v11
	s_nop 2
	v_max_f32_e32 v24, v20, v20
	v_mul_f32_e64 v20, |v20|, s89
	v_exp_f32_e32 v20, v20
	v_mul_f32_e64 v25, |v21|, s89
	v_exp_f32_e32 v25, v25
	v_min_f32_e32 v24, 0, v24
	v_add_f32_e32 v20, 1.0, v20
	v_cmp_gt_f32_e32 vcc, s90, v20
	v_add_f32_e32 v25, 1.0, v25
	v_cmp_gt_f32_e64 s[36:37], s90, v25
	v_cndmask_b32_e64 v26, 0, 32, vcc
	v_ldexp_f32 v20, v20, v26
	v_log_f32_e32 v20, v20
	v_cndmask_b32_e64 v27, 0, 32, s[36:37]
	v_ldexp_f32 v25, v25, v27
	v_log_f32_e32 v25, v25
	v_mul_f32_e32 v27, 0x3f317217, v20
	v_fma_f32 v27, v20, s91, -v27
	v_fmac_f32_e32 v27, 0x3377d1cf, v20
	v_cndmask_b32_e32 v26, 0, v97, vcc
	v_fmac_f32_e32 v27, 0x3f317217, v20
	v_cmp_lt_f32_e64 vcc, |v20|, s92
	v_mul_f32_e32 v28, 0x3f317217, v25
	v_max_f32_e32 v21, v21, v21
	v_cndmask_b32_e32 v20, v20, v27, vcc
	v_sub_f32_e32 v20, v20, v26
	v_sub_f32_e32 v20, v24, v20
	v_fma_f32 v24, v25, s91, -v28
	v_fmac_f32_e32 v24, 0x3377d1cf, v25
	v_fmac_f32_e32 v24, 0x3f317217, v25
	v_cmp_lt_f32_e64 vcc, |v25|, s92
	v_cndmask_b32_e64 v26, 0, v97, s[36:37]
	v_min_f32_e32 v21, 0, v21
	v_cndmask_b32_e32 v24, v25, v24, vcc
	v_mul_f32_e64 v25, |v22|, s89
	v_exp_f32_e32 v25, v25
	v_sub_f32_e32 v24, v24, v26
	v_sub_f32_e32 v21, v21, v24
	v_max_f32_e32 v22, v22, v22
	v_add_f32_e32 v24, 1.0, v25
	v_cmp_gt_f32_e32 vcc, s90, v24
	v_min_f32_e32 v22, 0, v22
	v_fma_f32 v20, v20, s93, 0
	v_cndmask_b32_e64 v25, 0, 32, vcc
	v_ldexp_f32 v24, v24, v25
	v_log_f32_e32 v24, v24
	v_cndmask_b32_e32 v26, 0, v97, vcc
	v_fmamk_f32 v21, v21, 0x3d800000, v20
	v_lshlrev_b32_e32 v132, 16, v10
	v_mul_f32_e32 v25, 0x3f317217, v24
	v_fma_f32 v25, v24, s91, -v25
	v_fmac_f32_e32 v25, 0x3377d1cf, v24
	v_fmac_f32_e32 v25, 0x3f317217, v24
	v_cmp_lt_f32_e64 s[36:37], |v24|, s92
	v_and_b32_e32 v135, 0xffff0000, v11
	v_and_b32_e32 v134, 0xffff0000, v10
	v_cndmask_b32_e64 v24, v24, v25, s[36:37]
	v_mul_f32_e64 v25, |v23|, s89
	v_exp_f32_e32 v25, v25
	v_sub_f32_e32 v24, v24, v26
	v_sub_f32_e32 v22, v22, v24
	v_max_f32_e32 v23, v23, v23
	v_add_f32_e32 v24, 1.0, v25
	v_cmp_gt_f32_e32 vcc, s90, v24
	v_min_f32_e32 v23, 0, v23
	v_fmamk_f32 v22, v22, 0x3d800000, v21
	v_cndmask_b32_e64 v25, 0, 32, vcc
	v_ldexp_f32 v24, v24, v25
	v_log_f32_e32 v24, v24
	s_waitcnt lgkmcnt(2)
	v_add_f32_e32 v26, v40, v41
	s_and_b32 s74, s1, 0xfc0
	s_ashr_i32 s83, s82, 31
	v_mul_f32_e32 v25, 0x3f317217, v24
	v_fma_f32 v25, v24, s91, -v25
	v_fmac_f32_e32 v25, 0x3377d1cf, v24
	v_fmac_f32_e32 v25, 0x3f317217, v24
	v_cmp_lt_f32_e64 s[36:37], |v24|, s92
	s_nop 1
	v_cndmask_b32_e64 v24, v24, v25, s[36:37]
	v_cndmask_b32_e32 v25, 0, v97, vcc
	v_sub_f32_e32 v24, v24, v25
	v_sub_f32_e32 v23, v23, v24
	v_fmamk_f32 v23, v23, 0x3d800000, v22
	ds_bpermute_b32 v24, v83, v23
	s_lshl_b64 s[36:37], s[82:83], 20
	s_waitcnt lgkmcnt(0)
	v_cndmask_b32_e64 v24, v24, 0, s[8:9]
	v_add_f32_e32 v24, v24, v23
	ds_bpermute_b32 v25, v84, v24
	s_waitcnt lgkmcnt(0)
	v_cndmask_b32_e64 v25, 0, v25, s[10:11]
	v_add_f32_e32 v24, v25, v24
	v_sub_f32_e32 v24, v24, v23
	v_add_f32_e32 v24, v26, v24
	v_add_f32_e32 v20, v20, v24
	v_add_f32_e32 v21, v21, v24
	v_add_u32_e32 v25, 0xea00, v98
	ds_write2_b32 v25, v20, v21 offset0:64 offset1:196
	v_add_f32_e32 v20, v22, v24
	v_add_f32_e32 v21, v23, v24
	v_add_u32_e32 v22, 0xee00, v98
	ds_write2_b32 v22, v20, v21 offset0:72 offset1:204
	v_add_u32_e32 v22, s94, v87
	s_waitcnt lgkmcnt(0)
	s_barrier
	v_add_u32_e32 v20, v86, v87
	v_add_u32_e32 v21, 0, v87
	ds_read_b128 v[32:35], v22
	ds_read_b128 v[24:27], v89
	ds_read_b128 v[60:63], v21 offset:51184
	ds_read_b128 v[64:67], v20 offset:34816
	ds_read_b128 v[74:77], v20 offset:34832
	ds_read_b128 v[44:47], v20 offset:34848
	ds_read_b128 v[36:39], v20 offset:34864
	ds_read_b128 v[100:103], v21 offset:51200
	s_waitcnt lgkmcnt(4)
	v_sub_f32_e32 v61, v65, v61
	v_mul_f32_e32 v61, 0x3fb8aa3b, v61
	v_sub_f32_e32 v63, v67, v63
	v_exp_f32_e32 v72, v61
	v_sub_f32_e32 v61, v32, v64
	v_mul_f32_e32 v63, 0x3fb8aa3b, v63
	v_mul_f32_e32 v61, 0x3fb8aa3b, v61
	v_exp_f32_e32 v73, v63
	v_exp_f32_e32 v78, v61
	v_mul_f32_e32 v61, 0x3fb8aa3b, v65
	v_sub_f32_e32 v20, v64, v60
	v_exp_f32_e32 v108, v61
	v_sub_f32_e32 v61, v66, v62
	v_mul_f32_e32 v20, 0x3fb8aa3b, v20
	v_mul_f32_e32 v69, 0x3fb8aa3b, v64
	v_mul_f32_e32 v61, 0x3fb8aa3b, v61
	v_sub_f32_e32 v62, v33, v65
	v_mul_f32_e32 v65, 0x3fb8aa3b, v66
	v_sub_f32_e32 v63, v34, v66
	v_exp_f32_e32 v60, v20
	v_exp_f32_e32 v70, v69
	v_rcp_f32_e32 v64, v72
	v_exp_f32_e32 v61, v61
	v_exp_f32_e32 v71, v65
	v_mul_f32_e32 v63, 0x3fb8aa3b, v63
	v_rcp_f32_e32 v65, v73
	v_exp_f32_e32 v79, v63
	v_mul_f32_e32 v63, 0x3fb8aa3b, v67
	v_exp_f32_e32 v109, v63
	v_sub_f32_e32 v63, v35, v67
	v_lshlrev_b32_e32 v67, 16, v5
	v_lshlrev_b32_e32 v66, 16, v4
	v_pk_mul_f32 v[112:113], v[60:61], v[66:67]
	v_pk_mul_f32 v[114:115], v[72:73], v[110:111]
	v_pk_mul_f32 v[72:73], v[64:65], v[116:117]
	v_pk_mul_f32 v[64:65], v[70:71], v[66:67]
	s_waitcnt lgkmcnt(0)
; #define LAS __attribute__((address_space(3)))
; __device__ __forceinline__ float bflo(unsigned w) { return __uint_as_float(w << 16); }
; __device__ __forceinline__ float bfhi(unsigned w) { return __uint_as_float(w & 0xffff0000u); }
; __device__ __forceinline__ unsigned pk2(float lo, float hi) { return f2bf(lo) | (f2bf(hi) << 16); }
; __device__ __forceinline__ void phase_gla_pre(const Params& P, LAS unsigned char* lds, bool dry) {
;     ...
;             for (int i = 0; i < 4; ++i) { bb[i] = *(const LAS f32x4*)(Lb + te * BP + (16 * kc + 4 * i) * 4); bm[i] = *(const LAS f32x4*)(Lb + 31 * BP + (16 * kc + 4 * i) * 4); bl[i] = *(const LAS f32x4*)(Lb + 63 * BP + (16 * kc + 4 * i) * 4); }
;             unsigned oqi[8], oki[8], oqd[8], oks[8];
; #pragma unroll
;             for (int e2 = 0; e2 < 8; ++e2) {
;                 const unsigned qw = e2 < 4 ? rq[0][e2] : rq[1][e2 - 4], kw = e2 < 4 ? rk[0][e2] : rk[1][e2 - 4];
;                 float vqi[2], vki[2], vqd[2], vks[2];
; #pragma unroll
;                 for (int hh = 0; hh < 2; ++hh) {
;                     const int e = 2 * e2 + hh; const float bv = bb[e >> 2][e & 3], bmv = bm[e >> 2][e & 3], blv = bl[e >> 2][e & 3];
;                     const float qv = hh ? bfhi(qw) : bflo(qw), kv = hh ? bfhi(kw) : bflo(kw);
;                     const float e1 = __expf(bv - bmv);
;                     vqi[hh] = qv * e1; vki[hh] = kv * __builtin_amdgcn_rcpf(e1); vqd[hh] = qv * __expf(bv); vks[hh] = kv * __expf(blv - bv);
;                 }
;                 oqi[e2] = pk2(vqi[0], vqi[1]); oki[e2] = pk2(vki[0], vki[1]); oqd[e2] = pk2(vqd[0], vqd[1]); oks[e2] = pk2(vks[0], vks[1]);
;             }
;             *(LAS u32x4*)(Lqi + te * QP + 32 * kc) = (u32x4){oqi[0], oqi[1], oqi[2], oqi[3]}; *(LAS u32x4*)(Lqi + te * QP + 32 * kc + 16) = (u32x4){oqi[4], oqi[5], oqi[6], oqi[7]};
	v_sub_f32_e32 v66, v74, v100
	v_mul_f32_e32 v66, 0x3fb8aa3b, v66
	v_mul_f32_e32 v71, 0x3fb8aa3b, v74
	v_exp_f32_e32 v70, v66
	v_pk_mul_f32 v[66:67], v[108:109], v[110:111]
	v_exp_f32_e32 v108, v71
	v_sub_f32_e32 v71, v75, v101
	v_mul_f32_e32 v71, 0x3fb8aa3b, v71
	v_mul_f32_e32 v62, 0x3fb8aa3b, v62
	v_mul_f32_e32 v63, 0x3fb8aa3b, v63
	v_exp_f32_e32 v100, v71
	v_sub_f32_e32 v71, v24, v74
	v_exp_f32_e32 v62, v62
	v_exp_f32_e32 v63, v63
	v_mul_f32_e32 v71, 0x3fb8aa3b, v71
	v_exp_f32_e32 v74, v71
	v_mul_f32_e32 v71, 0x3fb8aa3b, v75
	v_sub_f32_e32 v75, v25, v75
	v_mul_f32_e32 v75, 0x3fb8aa3b, v75
	v_exp_f32_e32 v118, v75
	v_mul_f32_e32 v75, 0x3fb8aa3b, v76
	v_pk_mul_f32 v[62:63], v[62:63], v[116:117]
	v_exp_f32_e32 v116, v71
	v_sub_f32_e32 v71, v76, v102
	v_exp_f32_e32 v109, v75
	v_sub_f32_e32 v75, v77, v103
	v_mul_f32_e32 v71, 0x3fb8aa3b, v71
	v_mul_f32_e32 v75, 0x3fb8aa3b, v75
	v_rcp_f32_e32 v68, v60
	v_rcp_f32_e32 v69, v61
	v_exp_f32_e32 v71, v71
	v_exp_f32_e32 v101, v75
	v_sub_f32_e32 v75, v26, v76
	v_mul_f32_e32 v76, 0x3fb8aa3b, v77
	v_exp_f32_e32 v117, v76
	v_sub_f32_e32 v76, v27, v77
	v_mul_f32_e32 v76, 0x3fb8aa3b, v76
	v_lshlrev_b32_e32 v61, 16, v13
	v_lshlrev_b32_e32 v60, 16, v12
	v_exp_f32_e32 v119, v76
	v_lshlrev_b32_e32 v77, 16, v7
	v_lshlrev_b32_e32 v76, 16, v6
	v_pk_mul_f32 v[68:69], v[68:69], v[60:61]
	v_pk_mul_f32 v[60:61], v[78:79], v[60:61]
	v_rcp_f32_e32 v78, v70
	v_rcp_f32_e32 v110, v100
	v_rcp_f32_e32 v79, v71
	v_rcp_f32_e32 v111, v101
	v_pk_mul_f32 v[70:71], v[70:71], v[76:77]
	v_pk_mul_f32 v[100:101], v[100:101], v[120:121]
	v_bfe_u32 v122, v115, 16, 1
	v_bfe_u32 v123, v114, 16, 1
	v_bfe_u32 v102, v101, 16, 1
	v_bfe_u32 v103, v100, 16, 1
	v_add3_u32 v114, v114, v123, s86
	v_add3_u32 v115, v115, v122, s86
	v_bfe_u32 v122, v70, 16, 1
	v_bfe_u32 v123, v71, 16, 1
	v_add3_u32 v100, v100, v103, s86
	v_add3_u32 v101, v101, v102, s86
	v_bfe_u32 v102, v112, 16, 1
	v_bfe_u32 v103, v113, 16, 1
	v_add3_u32 v71, v71, v123, s86
	v_add3_u32 v70, v70, v122, s86
	ds_read_b128 v[104:107], v21 offset:51216
	ds_read_b128 v[40:43], v21 offset:51232
	ds_read_b128 v[28:31], v90
	ds_read_b128 v[20:23], v91
	v_add3_u32 v103, v113, v103, s86
	v_add3_u32 v102, v112, v102, s86
	v_lshrrev_b32_e32 v70, 16, v70
	v_lshrrev_b32_e32 v71, 16, v71
	v_lshrrev_b32_e32 v112, 16, v102
	v_lshrrev_b32_e32 v113, 16, v103
	v_and_or_b32 v103, v101, s87, v71
	v_and_or_b32 v102, v100, s87, v70
	v_lshlrev_b32_e32 v71, 16, v15
	v_lshlrev_b32_e32 v70, 16, v14
	v_mul_f32_e32 v75, 0x3fb8aa3b, v75
	v_and_or_b32 v101, v115, s87, v113
	v_and_or_b32 v100, v114, s87, v112
	v_pk_mul_f32 v[114:115], v[78:79], v[70:71]
	s_waitcnt lgkmcnt(3)
	v_sub_f32_e32 v78, v44, v104
	v_sub_f32_e32 v105, v45, v105
	v_exp_f32_e32 v75, v75
	v_mul_f32_e32 v78, 0x3fb8aa3b, v78
	v_mul_f32_e32 v105, 0x3fb8aa3b, v105
	v_exp_f32_e32 v104, v78
	v_pk_mul_f32 v[78:79], v[116:117], v[120:121]
	v_exp_f32_e32 v116, v105
	v_mul_f32_e32 v105, 0x3fb8aa3b, v45
	s_waitcnt lgkmcnt(1)
	v_sub_f32_e32 v45, v29, v45
	v_mul_f32_e32 v45, 0x3fb8aa3b, v45
	v_and_b32_e32 v113, 0xffff0000, v15
	v_and_b32_e32 v112, 0xffff0000, v14
	v_exp_f32_e32 v120, v105
	v_sub_f32_e32 v105, v46, v106
	v_exp_f32_e32 v106, v45
	v_mul_f32_e32 v45, 0x3fb8aa3b, v46
	v_pk_mul_f32 v[110:111], v[110:111], v[112:113]
	v_pk_mul_f32 v[70:71], v[74:75], v[70:71]
	v_pk_mul_f32 v[74:75], v[118:119], v[112:113]
	v_exp_f32_e32 v113, v45
	v_sub_f32_e32 v45, v47, v107
	v_mul_f32_e32 v45, 0x3fb8aa3b, v45
	v_exp_f32_e32 v117, v45
	v_sub_f32_e32 v45, v30, v46
	v_mul_f32_e32 v46, 0x3fb8aa3b, v47
	v_exp_f32_e32 v121, v46
	v_sub_f32_e32 v46, v31, v47
	v_pk_mul_f32 v[76:77], v[108:109], v[76:77]
	v_mul_f32_e32 v109, 0x3fb8aa3b, v44
	v_mul_f32_e32 v105, 0x3fb8aa3b, v105
	v_mul_f32_e32 v46, 0x3fb8aa3b, v46
	v_exp_f32_e32 v112, v109
	v_exp_f32_e32 v105, v105
	v_exp_f32_e32 v107, v46
	v_rcp_f32_e32 v118, v116
	v_rcp_f32_e32 v119, v117
	v_sub_f32_e32 v44, v28, v44
	v_lshlrev_b32_e32 v47, 16, v9
	v_lshlrev_b32_e32 v46, 16, v8
	v_rcp_f32_e32 v108, v104
	v_mul_f32_e32 v44, 0x3fb8aa3b, v44
	v_rcp_f32_e32 v109, v105
	v_mul_f32_e32 v45, 0x3fb8aa3b, v45
	v_pk_mul_f32 v[104:105], v[104:105], v[46:47]
	v_pk_mul_f32 v[112:113], v[112:113], v[46:47]
	v_sub_f32_e32 v40, v36, v40
	v_pk_mul_f32 v[46:47], v[106:107], v[126:127]
	v_mul_f32_e32 v107, 0x3fb8aa3b, v36
	s_waitcnt lgkmcnt(0)
; #define LAS __attribute__((address_space(3)))
; __device__ __forceinline__ unsigned pk2(float lo, float hi) { return f2bf(lo) | (f2bf(hi) << 16); }
; __device__ __forceinline__ void phase_gla_pre(const Params& P, LAS unsigned char* lds, bool dry) {
;     ...
;                 oqi[e2] = pk2(vqi[0], vqi[1]); oki[e2] = pk2(vki[0], vki[1]); oqd[e2] = pk2(vqd[0], vqd[1]); oks[e2] = pk2(vks[0], vks[1]);
;             }
;             *(LAS u32x4*)(Lqi + te * QP + 32 * kc) = (u32x4){oqi[0], oqi[1], oqi[2], oqi[3]}; *(LAS u32x4*)(Lqi + te * QP + 32 * kc + 16) = (u32x4){oqi[4], oqi[5], oqi[6], oqi[7]};
;             *(LAS u32x4*)(Lki + te * QP + 32 * kc) = (u32x4){oki[0], oki[1], oki[2], oki[3]}; *(LAS u32x4*)(Lki + te * QP + 32 * kc + 16) = (u32x4){oki[4], oki[5], oki[6], oki[7]};
;             if (!dry) {
;                 bf16_t* p_ = PJ + ((size_t)bh * SEQ + c * 64 + te) * 128 + 16 * kc;
;                 *(u32x4*)(p_ + T_Q) = (u32x4){oqd[0], oqd[1], oqd[2], oqd[3]}; *(u32x4*)(p_ + T_Q + 8) = (u32x4){oqd[4], oqd[5], oqd[6], oqd[7]};
;                 *(u32x4*)(p_ + T_K) = (u32x4){oks[0], oks[1], oks[2], oks[3]}; *(u32x4*)(p_ + T_K + 8) = (u32x4){oks[4], oks[5], oks[6], oks[7]};
;                 if (te == 63) {
; #pragma unroll
;                     for (int i = 0; i < 4; ++i) *(f32x4*)(DEC + (size_t)item * 128 + 16 * kc + 4 * i) = (f32x4){__expf(bl[i][0]), __expf(bl[i][1]), __expf(bl[i][2]), __expf(bl[i][3])};
	v_sub_f32_e32 v36, v20, v36
	v_exp_f32_e32 v44, v44
	v_exp_f32_e32 v45, v45
	v_mul_f32_e32 v36, 0x3fb8aa3b, v36
	v_pk_mul_f32 v[118:119], v[118:119], v[126:127]
	v_exp_f32_e32 v126, v36
	v_mul_f32_e32 v36, 0x3fb8aa3b, v37
	v_sub_f32_e32 v41, v37, v41
	v_exp_f32_e32 v130, v36
	v_sub_f32_e32 v36, v38, v42
	v_mul_f32_e32 v41, 0x3fb8aa3b, v41
	v_mul_f32_e32 v36, 0x3fb8aa3b, v36
	v_pk_mul_f32 v[108:109], v[108:109], v[124:125]
	v_pk_mul_f32 v[44:45], v[44:45], v[124:125]
	v_exp_f32_e32 v124, v41
	v_exp_f32_e32 v41, v36
	v_sub_f32_e32 v36, v21, v37
	v_mul_f32_e32 v36, 0x3fb8aa3b, v36
	v_and_b32_e32 v123, 0xffff0000, v9
	v_and_b32_e32 v122, 0xffff0000, v8
	v_exp_f32_e32 v42, v36
	v_mul_f32_e32 v36, 0x3fb8aa3b, v38
	v_pk_mul_f32 v[116:117], v[116:117], v[122:123]
	v_pk_mul_f32 v[120:121], v[120:121], v[122:123]
	v_exp_f32_e32 v123, v36
	v_sub_f32_e32 v36, v39, v43
	v_mul_f32_e32 v36, 0x3fb8aa3b, v36
	v_mul_f32_e32 v40, 0x3fb8aa3b, v40
	v_exp_f32_e32 v125, v36
	v_sub_f32_e32 v36, v22, v38
	v_exp_f32_e32 v40, v40
	v_mul_f32_e32 v36, 0x3fb8aa3b, v36
	v_exp_f32_e32 v127, v36
	v_mul_f32_e32 v36, 0x3fb8aa3b, v39
	v_exp_f32_e32 v131, v36
	v_sub_f32_e32 v36, v23, v39
	v_mul_f32_e32 v36, 0x3fb8aa3b, v36
	v_rcp_f32_e32 v128, v124
	v_rcp_f32_e32 v129, v125
	v_exp_f32_e32 v43, v36
	v_pk_mul_f32 v[36:37], v[40:41], v[132:133]
	v_pk_mul_f32 v[38:39], v[124:125], v[134:135]
	v_bfe_u32 v124, v117, 16, 1
	v_bfe_u32 v125, v116, 16, 1
	v_rcp_f32_e32 v106, v40
	v_exp_f32_e32 v122, v107
	v_rcp_f32_e32 v107, v41
	v_bfe_u32 v40, v39, 16, 1
	v_bfe_u32 v41, v38, 16, 1
	v_add3_u32 v116, v116, v125, s86
	v_add3_u32 v117, v117, v124, s86
	v_bfe_u32 v124, v36, 16, 1
	v_bfe_u32 v125, v37, 16, 1
	v_add3_u32 v38, v38, v41, s86
	v_add3_u32 v39, v39, v40, s86
	v_bfe_u32 v40, v104, 16, 1
	v_bfe_u32 v41, v105, 16, 1
	v_add3_u32 v37, v37, v125, s86
	v_add3_u32 v36, v36, v124, s86
	v_add3_u32 v41, v105, v41, s86
	v_add3_u32 v40, v104, v40, s86
	v_lshrrev_b32_e32 v36, 16, v36
	v_lshrrev_b32_e32 v37, 16, v37
	v_lshrrev_b32_e32 v40, 16, v40
	v_lshrrev_b32_e32 v41, 16, v41
	v_and_or_b32 v39, v39, s87, v37
	v_and_or_b32 v38, v38, s87, v36
	v_and_or_b32 v37, v117, s87, v41
	v_and_or_b32 v36, v116, s87, v40
	ds_write_b128 v92, v[100:103]
	ds_write_b128 v92, v[36:39] offset:16
	v_bfe_u32 v38, v73, 16, 1
	v_bfe_u32 v39, v72, 16, 1
	v_add3_u32 v72, v72, v39, s86
	v_add3_u32 v73, v73, v38, s86
	v_bfe_u32 v38, v68, 16, 1
	v_bfe_u32 v39, v69, 16, 1
	v_add3_u32 v39, v69, v39, s86
	v_add3_u32 v38, v68, v38, s86
	v_lshrrev_b32_e32 v68, 16, v38
	v_lshrrev_b32_e32 v69, 16, v39
	v_lshlrev_b32_e32 v41, 16, v19
	v_lshlrev_b32_e32 v40, 16, v18
	v_cvt_pk_bf16_f32 v39, v115, v111
	v_cvt_pk_bf16_f32 v38, v114, v110
	v_and_or_b32 v37, v73, s87, v69
	v_and_or_b32 v36, v72, s87, v68
	v_and_b32_e32 v105, 0xffff0000, v19
	v_and_b32_e32 v104, 0xffff0000, v18
	v_pk_mul_f32 v[106:107], v[106:107], v[40:41]
	ds_write_b128 v92, v[36:39] offset:17408
	v_pk_mul_f32 v[116:117], v[128:129], v[104:105]
	v_cvt_pk_bf16_f32 v39, v107, v117
	v_cvt_pk_bf16_f32 v38, v106, v116
	v_cvt_pk_bf16_f32 v37, v109, v119
	v_cvt_pk_bf16_f32 v36, v108, v118
	ds_write_b128 v92, v[36:39] offset:17424
	v_lshl_add_u64 v[36:37], s[74:75], 0, v[48:49]
	v_lshlrev_b64 v[36:37], 8, v[36:37]
	v_lshl_add_u64 v[38:39], v[52:53], 0, s[36:37]
	v_lshl_add_u64 v[68:69], v[38:39], 0, v[36:37]
	v_bfe_u32 v38, v67, 16, 1
	v_bfe_u32 v39, v66, 16, 1
	v_add3_u32 v66, v66, v39, s86
	v_add3_u32 v67, v67, v38, s86
	v_bfe_u32 v38, v64, 16, 1
	v_bfe_u32 v39, v65, 16, 1
	v_add3_u32 v39, v65, v39, s86
	v_add3_u32 v38, v64, v38, s86
	v_lshrrev_b32_e32 v64, 16, v38
	v_lshrrev_b32_e32 v65, 16, v39
	s_brev_b32 s36, 16
	v_cvt_pk_bf16_f32 v39, v77, v79
	v_and_or_b32 v36, v66, s87, v64
	v_add_co_u32_e32 v64, vcc, s36, v68
	v_cvt_pk_bf16_f32 v38, v76, v78
	v_and_or_b32 v37, v67, s87, v65
	v_addc_co_u32_e32 v65, vcc, 0, v69, vcc
	v_pk_mul_f32 v[122:123], v[122:123], v[132:133]
	global_store_dwordx4 v[64:65], v[36:39], off
	v_pk_mul_f32 v[124:125], v[130:131], v[134:135]
	s_nop 0
	v_cvt_pk_bf16_f32 v39, v123, v125
	v_cvt_pk_bf16_f32 v38, v122, v124
	v_cvt_pk_bf16_f32 v37, v113, v121
	v_cvt_pk_bf16_f32 v36, v112, v120
	global_store_dwordx4 v[64:65], v[36:39], off offset:16
	s_nop 1
	v_bfe_u32 v38, v63, 16, 1
	s_nop 0
	v_bfe_u32 v39, v62, 16, 1
	v_add3_u32 v62, v62, v39, s86
	v_add3_u32 v63, v63, v38, s86
	v_bfe_u32 v38, v60, 16, 1
	v_bfe_u32 v39, v61, 16, 1
	v_add3_u32 v39, v61, v39, s86
	v_add3_u32 v38, v60, v38, s86
	v_lshrrev_b32_e32 v60, 16, v38
	v_lshrrev_b32_e32 v61, 16, v39
	v_cvt_pk_bf16_f32 v39, v71, v75
	v_and_or_b32 v36, v62, s87, v60
	v_add_co_u32_e32 v60, vcc, s95, v68
	v_pk_mul_f32 v[42:43], v[42:43], v[104:105]
	v_cvt_pk_bf16_f32 v38, v70, v74
	v_and_or_b32 v37, v63, s87, v61
	v_addc_co_u32_e32 v61, vcc, 0, v69, vcc
	v_pk_mul_f32 v[40:41], v[126:127], v[40:41]
	global_store_dwordx4 v[60:61], v[36:39], off
	s_nop 1
	v_bfe_u32 v36, v43, 16, 1
	v_bfe_u32 v37, v42, 16, 1
	v_bfe_u32 v38, v47, 16, 1
	v_bfe_u32 v39, v46, 16, 1
	v_add3_u32 v46, v46, v39, s86
	v_add3_u32 v47, v47, v38, s86
	v_add3_u32 v37, v42, v37, s86
	v_add3_u32 v36, v43, v36, s86
	v_bfe_u32 v38, v44, 16, 1
	v_bfe_u32 v39, v45, 16, 1
	v_bfe_u32 v42, v40, 16, 1
	v_bfe_u32 v43, v41, 16, 1
	v_add3_u32 v41, v41, v43, s86
	v_add3_u32 v40, v40, v42, s86
	v_add3_u32 v39, v45, v39, s86
	v_add3_u32 v38, v44, v38, s86
	v_lshrrev_b32_e32 v42, 16, v38
	v_lshrrev_b32_e32 v43, 16, v39
	v_lshrrev_b32_e32 v38, 16, v40
	v_lshrrev_b32_e32 v39, 16, v41
	v_and_or_b32 v39, v36, s87, v39
	v_and_or_b32 v38, v37, s87, v38
	v_and_or_b32 v37, v47, s87, v43
	v_and_or_b32 v36, v46, s87, v42
	global_store_dwordx4 v[60:61], v[36:39], off offset:16
	s_and_saveexec_b64 s[36:37], s[12:13]
	s_cbranch_execz .LBB0_494
	v_mul_f32_e32 v32, 0x3fb8aa3b, v32
	v_mul_f32_e32 v33, 0x3fb8aa3b, v33
	v_mul_f32_e32 v34, 0x3fb8aa3b, v34
	v_mul_f32_e32 v35, 0x3fb8aa3b, v35
	v_exp_f32_e32 v32, v32
	v_exp_f32_e32 v33, v33
	v_exp_f32_e32 v34, v34
	v_exp_f32_e32 v35, v35
	v_mul_f32_e32 v24, 0x3fb8aa3b, v24
	v_mul_f32_e32 v25, 0x3fb8aa3b, v25
	v_mul_f32_e32 v26, 0x3fb8aa3b, v26
	v_mul_f32_e32 v27, 0x3fb8aa3b, v27
	s_ashr_i32 s81, s80, 31
	v_exp_f32_e32 v24, v24
	v_exp_f32_e32 v25, v25
	v_exp_f32_e32 v26, v26
	v_exp_f32_e32 v27, v27
	v_mul_f32_e32 v28, 0x3fb8aa3b, v28
	v_mul_f32_e32 v29, 0x3fb8aa3b, v29
	v_mul_f32_e32 v30, 0x3fb8aa3b, v30
	v_mul_f32_e32 v31, 0x3fb8aa3b, v31
	s_lshl_b64 s[42:43], s[80:81], 9
	v_exp_f32_e32 v28, v28
	v_exp_f32_e32 v29, v29
	v_exp_f32_e32 v30, v30
	v_exp_f32_e32 v31, v31
	v_mul_f32_e32 v20, 0x3fb8aa3b, v20
	v_mul_f32_e32 v21, 0x3fb8aa3b, v21
	v_mul_f32_e32 v22, 0x3fb8aa3b, v22
	v_mul_f32_e32 v23, 0x3fb8aa3b, v23
	v_lshl_add_u64 v[36:37], v[54:55], 0, s[42:43]
	v_exp_f32_e32 v20, v20
	v_exp_f32_e32 v21, v21
	v_exp_f32_e32 v22, v22
	v_exp_f32_e32 v23, v23
	global_store_dwordx4 v[36:37], v[32:35], off
	global_store_dwordx4 v[36:37], v[24:27], off offset:16
	global_store_dwordx4 v[36:37], v[28:31], off offset:32
	global_store_dwordx4 v[36:37], v[20:23], off offset:48

; #define LAS __attribute__((address_space(3)))
; __device__ __forceinline__ float bflo(unsigned w) { return __uint_as_float(w << 16); }
; __device__ __forceinline__ float bfhi(unsigned w) { return __uint_as_float(w & 0xffff0000u); }
; __device__ __forceinline__ unsigned pk2(float lo, float hi) { return f2bf(lo) | (f2bf(hi) << 16); }
; __device__ __forceinline__ void phase_mixer_a(const Params& P, LAS unsigned char* lds, int ustart, int ustride, bool dry) {
;     ...
;             for (int i = 0; i < 4; ++i) {
;                 const int item = tid + 512 * i, c8 = item & 15, s = item >> 4;
;                 const u32x4 gv = pgv[i];
;                 const float mean = stats[2 * s], rstd = stats[2 * s + 1];
;                 const f32x4 g0 = *(const f32x4*)(P.ln_v_g + h * 128 + c8 * 8), g1 = *(const f32x4*)(P.ln_v_g + h * 128 + c8 * 8 + 4);
;                 const f32x4 b0 = *(const f32x4*)(P.ln_v_b + h * 128 + c8 * 8), b1 = *(const f32x4*)(P.ln_v_b + h * 128 + c8 * 8 + 4);
;                 u32x4 o;
;                 o.x = pk2((bflo(gv.x) - mean) * rstd * g0[0] + b0[0], (bfhi(gv.x) - mean) * rstd * g0[1] + b0[1]);
;                 o.y = pk2((bflo(gv.y) - mean) * rstd * g0[2] + b0[2], (bfhi(gv.y) - mean) * rstd * g0[3] + b0[3]);
;                 o.z = pk2((bflo(gv.z) - mean) * rstd * g1[0] + b1[0], (bfhi(gv.z) - mean) * rstd * g1[1] + b1[1]);
;                 o.w = pk2((bflo(gv.w) - mean) * rstd * g1[2] + b1[2], (bfhi(gv.w) - mean) * rstd * g1[3] + b1[3]);
;                 *(LAS u32x4*)(lds + s * VN_P + c8 * 16) = o;
;                 *(LAS u32x4*)(lds + W_OFF + s * W_P + c8 * 16) = *(const u32x4*)(WsT + h * 16384 + item * 8);
;             }
.LBB0_632:
	v_lshl_add_u64 v[16:17], v[62:63], 0, s[6:7]
	global_load_dwordx4 v[24:27], v[16:17], off offset:-16
	v_lshl_add_u64 v[20:21], v[66:67], 0, s[6:7]
	global_load_dwordx4 v[28:31], v[20:21], off offset:-16
	s_nop 0
	global_load_dwordx4 v[16:19], v[16:17], off
	s_nop 0
	global_load_dwordx4 v[20:23], v[20:21], off
	s_nop 0
	global_load_dwordx4 v[168:171], v[126:127], off
	global_load_dwordx4 v[172:175], v[124:125], off
	ds_read_b64 v[128:129], v151
	s_waitcnt vmcnt(9)
	v_lshlrev_b32_e32 v131, 16, v1
	v_lshlrev_b32_e32 v130, 16, v0
	v_and_b32_e32 v177, 0xffff0000, v1
	v_and_b32_e32 v176, 0xffff0000, v0
	v_lshlrev_b32_e32 v179, 16, v3
	v_lshlrev_b32_e32 v178, 16, v2
	v_and_b32_e32 v181, 0xffff0000, v3
	v_and_b32_e32 v180, 0xffff0000, v2
	s_waitcnt lgkmcnt(0)
	v_pk_add_f32 v[130:131], v[130:131], v[128:129] op_sel_hi:[1,0] neg_lo:[0,1] neg_hi:[0,1]
	v_pk_add_f32 v[176:177], v[176:177], v[128:129] op_sel_hi:[1,0] neg_lo:[0,1] neg_hi:[0,1]
	v_pk_add_f32 v[178:179], v[178:179], v[128:129] op_sel_hi:[1,0] neg_lo:[0,1] neg_hi:[0,1]
	v_pk_add_f32 v[180:181], v[180:181], v[128:129] op_sel_hi:[1,0] neg_lo:[0,1] neg_hi:[0,1]
	v_pk_mul_f32 v[188:189], v[128:129], v[130:131] op_sel:[1,0]
	v_pk_mul_f32 v[176:177], v[128:129], v[176:177] op_sel:[1,0]
	v_pk_mul_f32 v[178:179], v[128:129], v[178:179] op_sel:[1,0]
	v_pk_mul_f32 v[180:181], v[128:129], v[180:181] op_sel:[1,0]
	s_waitcnt vmcnt(8)
	v_lshlrev_b32_e32 v183, 16, v5
	v_lshlrev_b32_e32 v182, 16, v4
	v_and_b32_e32 v185, 0xffff0000, v5
	v_and_b32_e32 v184, 0xffff0000, v4
	v_lshlrev_b32_e32 v187, 16, v7
	v_lshlrev_b32_e32 v186, 16, v6
	s_cmpk_lg_i32 s16, 0x700
	s_waitcnt vmcnt(4)
	v_mov_b32_e32 v130, v28
	v_mov_b32_e32 v128, v24
	v_mov_b32_e32 v129, v26
	v_mov_b32_e32 v131, v30
	v_mov_b32_e32 v26, v25
	v_mov_b32_e32 v30, v29
	s_waitcnt vmcnt(3)
	v_mov_b32_e32 v24, v16
	v_mov_b32_e32 v25, v18
	s_waitcnt vmcnt(2)
	v_mov_b32_e32 v28, v20
	v_mov_b32_e32 v29, v22
	v_mov_b32_e32 v18, v17
	v_mov_b32_e32 v22, v21
	v_pk_fma_f32 v[16:17], v[188:189], v[128:129], v[130:131]
	v_pk_fma_f32 v[20:21], v[176:177], v[26:27], v[30:31]
	v_pk_fma_f32 v[176:177], v[178:179], v[24:25], v[28:29]
	v_pk_fma_f32 v[178:179], v[180:181], v[18:19], v[22:23]
	v_bfe_u32 v45, v21, 16, 1
	v_bfe_u32 v47, v20, 16, 1
	v_bfe_u32 v61, v16, 16, 1
	v_bfe_u32 v65, v17, 16, 1
	v_add3_u32 v20, v20, v47, s18
	v_add3_u32 v21, v21, v45, s18
	v_add3_u32 v17, v17, v65, s18
	v_add3_u32 v16, v16, v61, s18
	v_lshrrev_b32_e32 v16, 16, v16
	v_lshrrev_b32_e32 v17, 16, v17
	v_cvt_pk_bf16_f32 v179, v177, v179
	v_cvt_pk_bf16_f32 v178, v176, v178
	v_and_or_b32 v177, v21, s3, v17
	v_and_or_b32 v176, v20, s3, v16
	ds_write_b128 v152, v[176:179]
	s_waitcnt vmcnt(1)
	ds_write_b128 v153, v[168:171] offset:36864
	ds_read_b64 v[16:17], v154
	global_load_dwordx4 v[168:171], v[122:123], off
	v_and_b32_e32 v21, 0xffff0000, v7
	v_and_b32_e32 v20, 0xffff0000, v6
	s_waitcnt lgkmcnt(0)
	v_pk_add_f32 v[176:177], v[182:183], v[16:17] op_sel_hi:[1,0] neg_lo:[0,1] neg_hi:[0,1]
	v_pk_add_f32 v[178:179], v[184:185], v[16:17] op_sel_hi:[1,0] neg_lo:[0,1] neg_hi:[0,1]
	v_pk_add_f32 v[180:181], v[186:187], v[16:17] op_sel_hi:[1,0] neg_lo:[0,1] neg_hi:[0,1]
	v_pk_add_f32 v[20:21], v[20:21], v[16:17] op_sel_hi:[1,0] neg_lo:[0,1] neg_hi:[0,1]
	v_pk_mul_f32 v[176:177], v[16:17], v[176:177] op_sel:[1,0]
	v_pk_mul_f32 v[178:179], v[16:17], v[178:179] op_sel:[1,0]
	v_pk_mul_f32 v[180:181], v[16:17], v[180:181] op_sel:[1,0]
	v_pk_mul_f32 v[16:17], v[16:17], v[20:21] op_sel:[1,0]
	v_pk_fma_f32 v[20:21], v[128:129], v[176:177], v[130:131]
	v_pk_fma_f32 v[16:17], v[18:19], v[16:17], v[22:23]
	v_pk_fma_f32 v[176:177], v[26:27], v[178:179], v[30:31]
	v_pk_fma_f32 v[178:179], v[24:25], v[180:181], v[28:29]
	v_bfe_u32 v41, v17, 16, 1
	v_bfe_u32 v43, v16, 16, 1
	v_bfe_u32 v61, v20, 16, 1
	v_add3_u32 v16, v16, v43, s18
	v_add3_u32 v17, v17, v41, s18
	v_bfe_u32 v41, v21, 16, 1
	v_bfe_u32 v43, v178, 16, 1
	v_bfe_u32 v65, v179, 16, 1
	v_bfe_u32 v45, v177, 16, 1
	v_bfe_u32 v47, v176, 16, 1
	v_add3_u32 v65, v179, v65, s18
	v_add3_u32 v43, v178, v43, s18
	v_add3_u32 v21, v21, v41, s18
	v_add3_u32 v20, v20, v61, s18
	v_add3_u32 v47, v176, v47, s18
	v_add3_u32 v45, v177, v45, s18
	v_lshrrev_b32_e32 v20, 16, v20
	v_lshrrev_b32_e32 v21, 16, v21
	v_lshrrev_b32_e32 v41, 16, v43
	v_lshrrev_b32_e32 v43, 16, v65
	v_and_or_b32 v179, v17, s3, v43
	v_and_or_b32 v178, v16, s3, v41
	v_and_or_b32 v177, v45, s3, v21
	v_and_or_b32 v176, v47, s3, v20
	ds_write_b128 v155, v[176:179]
	s_waitcnt vmcnt(1)
; #define LAS __attribute__((address_space(3)))
; __device__ __forceinline__ float bflo(unsigned w) { return __uint_as_float(w << 16); }
; __device__ __forceinline__ float bfhi(unsigned w) { return __uint_as_float(w & 0xffff0000u); }
; __device__ __forceinline__ unsigned pk2(float lo, float hi) { return f2bf(lo) | (f2bf(hi) << 16); }
; __device__ __forceinline__ void phase_mixer_a(const Params& P, LAS unsigned char* lds, int ustart, int ustride, bool dry) {
;     ...
;             for (int i = 0; i < 4; ++i) {
;                 const int item = tid + 512 * i, c8 = item & 15, s = item >> 4;
;                 const u32x4 gv = pgv[i];
;                 const float mean = stats[2 * s], rstd = stats[2 * s + 1];
;                 const f32x4 g0 = *(const f32x4*)(P.ln_v_g + h * 128 + c8 * 8), g1 = *(const f32x4*)(P.ln_v_g + h * 128 + c8 * 8 + 4);
;                 const f32x4 b0 = *(const f32x4*)(P.ln_v_b + h * 128 + c8 * 8), b1 = *(const f32x4*)(P.ln_v_b + h * 128 + c8 * 8 + 4);
;                 u32x4 o;
;                 o.x = pk2((bflo(gv.x) - mean) * rstd * g0[0] + b0[0], (bfhi(gv.x) - mean) * rstd * g0[1] + b0[1]);
;                 o.y = pk2((bflo(gv.y) - mean) * rstd * g0[2] + b0[2], (bfhi(gv.y) - mean) * rstd * g0[3] + b0[3]);
;                 o.z = pk2((bflo(gv.z) - mean) * rstd * g1[0] + b1[0], (bfhi(gv.z) - mean) * rstd * g1[1] + b1[1]);
;                 o.w = pk2((bflo(gv.w) - mean) * rstd * g1[2] + b1[2], (bfhi(gv.w) - mean) * rstd * g1[3] + b1[3]);
;                 *(LAS u32x4*)(lds + s * VN_P + c8 * 16) = o;
;                 *(LAS u32x4*)(lds + W_OFF + s * W_P + c8 * 16) = *(const u32x4*)(WsT + h * 16384 + item * 8);
;             }
;             __syncthreads();
;             if (h + 1 < 8) {
; #pragma unroll
;                 for (int i = 0; i < 4; ++i) { const int item = tid + 512 * i, c8 = item & 15, s = item >> 4;
;                     pgv[i] = *(const u32x4*)(PJ + T_GV + (size_t)(r0 + s) * 1024 + (h + 1) * 128 + c8 * 8); }
;             }
	ds_write_b128 v156, v[172:175] offset:36864
	ds_read_b64 v[16:17], v157
	v_and_b32_e32 v173, 0xffff0000, v9
	v_and_b32_e32 v172, 0xffff0000, v8
	v_lshlrev_b32_e32 v21, 16, v9
	v_lshlrev_b32_e32 v20, 16, v8
	s_waitcnt lgkmcnt(0)
	v_pk_add_f32 v[172:173], v[172:173], v[16:17] op_sel_hi:[1,0] neg_lo:[0,1] neg_hi:[0,1]
	v_and_b32_e32 v181, 0xffff0000, v11
	v_pk_mul_f32 v[172:173], v[16:17], v[172:173] op_sel:[1,0]
	v_and_b32_e32 v180, 0xffff0000, v10
	v_pk_fma_f32 v[176:177], v[26:27], v[172:173], v[30:31]
	v_lshlrev_b32_e32 v173, 16, v11
	v_lshlrev_b32_e32 v172, 16, v10
	v_pk_add_f32 v[172:173], v[172:173], v[16:17] op_sel_hi:[1,0] neg_lo:[0,1] neg_hi:[0,1]
	v_pk_add_f32 v[20:21], v[20:21], v[16:17] op_sel_hi:[1,0] neg_lo:[0,1] neg_hi:[0,1]
	v_pk_mul_f32 v[172:173], v[16:17], v[172:173] op_sel:[1,0]
	v_pk_add_f32 v[180:181], v[180:181], v[16:17] op_sel_hi:[1,0] neg_lo:[0,1] neg_hi:[0,1]
	v_pk_fma_f32 v[178:179], v[24:25], v[172:173], v[28:29]
	global_load_dwordx4 v[172:175], v[120:121], off
	v_pk_mul_f32 v[20:21], v[16:17], v[20:21] op_sel:[1,0]
	v_pk_mul_f32 v[16:17], v[16:17], v[180:181] op_sel:[1,0]
	v_pk_fma_f32 v[20:21], v[128:129], v[20:21], v[130:131]
	v_pk_fma_f32 v[16:17], v[18:19], v[16:17], v[22:23]
	v_bfe_u32 v61, v178, 16, 1
	v_bfe_u32 v41, v17, 16, 1
	v_bfe_u32 v43, v16, 16, 1
	v_add3_u32 v16, v16, v43, s18
	v_add3_u32 v17, v17, v41, s18
	v_bfe_u32 v41, v20, 16, 1
	v_bfe_u32 v43, v21, 16, 1
	v_bfe_u32 v65, v179, 16, 1
	v_bfe_u32 v45, v177, 16, 1
	v_bfe_u32 v47, v176, 16, 1
	v_add3_u32 v65, v179, v65, s18
	v_add3_u32 v61, v178, v61, s18
	v_add3_u32 v21, v21, v43, s18
	v_add3_u32 v20, v20, v41, s18
	v_add3_u32 v47, v176, v47, s18
	v_add3_u32 v45, v177, v45, s18
	v_lshrrev_b32_e32 v20, 16, v20
	v_lshrrev_b32_e32 v21, 16, v21
	v_lshrrev_b32_e32 v41, 16, v61
	v_lshrrev_b32_e32 v43, 16, v65
	v_and_or_b32 v179, v17, s3, v43
	v_and_or_b32 v178, v16, s3, v41
	v_and_or_b32 v177, v45, s3, v21
	v_and_or_b32 v176, v47, s3, v20
	ds_write_b128 v158, v[176:179]
	s_waitcnt vmcnt(1)
	ds_write_b128 v159, v[168:171] offset:36864
	ds_read_b64 v[16:17], v160
	v_lshlrev_b32_e32 v21, 16, v13
	v_lshlrev_b32_e32 v20, 16, v12
	s_waitcnt lgkmcnt(0)
	v_pk_add_f32 v[20:21], v[20:21], v[16:17] op_sel_hi:[1,0] neg_lo:[0,1] neg_hi:[0,1]
	s_nop 0
	v_pk_mul_f32 v[20:21], v[16:17], v[20:21] op_sel:[1,0]
	s_nop 0
	v_pk_fma_f32 v[20:21], v[128:129], v[20:21], v[130:131]
	v_and_b32_e32 v129, 0xffff0000, v13
	v_and_b32_e32 v128, 0xffff0000, v12
	v_pk_add_f32 v[128:129], v[128:129], v[16:17] op_sel_hi:[1,0] neg_lo:[0,1] neg_hi:[0,1]
	s_nop 0
	v_pk_mul_f32 v[128:129], v[16:17], v[128:129] op_sel:[1,0]
	s_nop 0
	v_pk_fma_f32 v[26:27], v[26:27], v[128:129], v[30:31]
	v_lshlrev_b32_e32 v31, 16, v15
	v_lshlrev_b32_e32 v30, 16, v14
	v_pk_add_f32 v[30:31], v[30:31], v[16:17] op_sel_hi:[1,0] neg_lo:[0,1] neg_hi:[0,1]
	s_nop 0
	v_pk_mul_f32 v[30:31], v[16:17], v[30:31] op_sel:[1,0]
	s_nop 0
	v_pk_fma_f32 v[24:25], v[24:25], v[30:31], v[28:29]
	v_and_b32_e32 v29, 0xffff0000, v15
	v_and_b32_e32 v28, 0xffff0000, v14
	v_pk_add_f32 v[28:29], v[28:29], v[16:17] op_sel_hi:[1,0] neg_lo:[0,1] neg_hi:[0,1]
	s_nop 0
	v_pk_mul_f32 v[16:17], v[16:17], v[28:29] op_sel:[1,0]
	s_nop 0
	v_pk_fma_f32 v[16:17], v[18:19], v[16:17], v[22:23]
	v_bfe_u32 v22, v27, 16, 1
	v_bfe_u32 v18, v17, 16, 1
	v_bfe_u32 v19, v16, 16, 1
	v_bfe_u32 v23, v26, 16, 1
	v_add3_u32 v23, v26, v23, s18
	v_add3_u32 v22, v27, v22, s18
	v_add3_u32 v16, v16, v19, s18
	v_add3_u32 v17, v17, v18, s18
	v_bfe_u32 v18, v20, 16, 1
	v_bfe_u32 v19, v21, 16, 1
	v_bfe_u32 v26, v24, 16, 1
	v_bfe_u32 v27, v25, 16, 1
	v_add3_u32 v25, v25, v27, s18
	v_add3_u32 v24, v24, v26, s18
	v_add3_u32 v19, v21, v19, s18
	v_add3_u32 v18, v20, v18, s18
	v_lshrrev_b32_e32 v20, 16, v18
	v_lshrrev_b32_e32 v21, 16, v19
	v_lshrrev_b32_e32 v18, 16, v24
	v_lshrrev_b32_e32 v19, 16, v25
	v_and_or_b32 v19, v17, s3, v19
	v_and_or_b32 v18, v16, s3, v18
	v_and_or_b32 v17, v22, s3, v21
	v_and_or_b32 v16, v23, s3, v20
	ds_write_b128 v161, v[16:19]
	s_waitcnt vmcnt(0)
	ds_write_b128 v162, v[172:175] offset:36864
	s_waitcnt lgkmcnt(0)
	s_barrier
	s_cbranch_scc0 .LBB0_631
	v_lshl_add_u64 v[12:13], v[86:87], 0, s[16:17]
	v_lshl_add_u64 v[8:9], v[84:85], 0, s[16:17]
	v_lshl_add_u64 v[4:5], v[82:83], 0, s[16:17]
	v_lshl_add_u64 v[0:1], v[80:81], 0, s[16:17]
	global_load_dwordx4 v[0:3], v[0:1], off
	s_nop 0
	global_load_dwordx4 v[4:7], v[4:5], off
	s_nop 0
	global_load_dwordx4 v[8:11], v[8:9], off
	s_nop 0
	global_load_dwordx4 v[12:15], v[12:13], off
	s_branch .LBB0_631

; #define LAS __attribute__((address_space(3)))
; __device__ __forceinline__ void tr_item(const float* W, int ldw, int src_col0, int k0, bf16_t* dst, int ldd, int dst_row0, int dst_col0, LAS float* scr, int lane) {
; #pragma unroll 8
;     for (int i = 0; i < 32; ++i) { const int kk = 2 * i + (lane >> 5); scr[kk * 33 + (lane & 31)] = W[(size_t)(k0 + kk) * ldw + src_col0 + (lane & 31)]; }
;     asm volatile("s_waitcnt lgkmcnt(0)" ::: "memory");
.LBB0_640:
	s_lshl_b32 s19, s16, 1
	s_lshl_b32 s20, s17, 1
	v_or_b32_e32 v4, s19, v1
	v_or_b32_e32 v19, s20, v0
	s_add_i32 s21, s19, 4
	s_add_i32 s22, s20, 4
	s_add_i32 s23, s19, 8
	s_add_i32 s24, s20, 8
	s_add_i32 s25, s19, 12
	s_add_i32 s26, s20, 12
	s_add_i32 s27, s19, 16
	s_add_i32 s28, s20, 16
	s_add_i32 s29, s19, 20
	s_add_i32 s30, s20, 20
	s_add_i32 s31, s19, 24
	s_add_i32 s34, s20, 24
	s_add_i32 s19, s19, 28
	s_add_i32 s20, s20, 28
	v_add_u32_e32 v32, v19, v18
	v_or_b32_e32 v29, s21, v1
	v_or_b32_e32 v62, s22, v0
	v_or_b32_e32 v63, s23, v1
	v_or_b32_e32 v64, s24, v0
	v_or_b32_e32 v65, s25, v1
	v_or_b32_e32 v66, s26, v0
	v_or_b32_e32 v67, s27, v1
	v_or_b32_e32 v68, s28, v0
	v_or_b32_e32 v69, s29, v1
	v_or_b32_e32 v70, s30, v0
	v_or_b32_e32 v71, s31, v1
	v_or_b32_e32 v72, s34, v0
	v_or_b32_e32 v73, s19, v1
	v_or_b32_e32 v74, s20, v0
	v_add_u32_e32 v30, v4, v3
	v_ashrrev_i32_e32 v33, 31, v32
	v_add_u32_e32 v34, v29, v3
	v_add_u32_e32 v36, v62, v18
	v_add_u32_e32 v38, v63, v3
	v_add_u32_e32 v40, v64, v18
	v_add_u32_e32 v42, v65, v3
	v_add_u32_e32 v44, v66, v18
	v_add_u32_e32 v46, v67, v3
	v_add_u32_e32 v48, v68, v18
	v_add_u32_e32 v50, v69, v3
	v_add_u32_e32 v52, v70, v18
	v_add_u32_e32 v54, v71, v3
	v_add_u32_e32 v56, v72, v18
	v_add_u32_e32 v58, v73, v3
	v_add_u32_e32 v60, v74, v18
	v_ashrrev_i32_e32 v31, 31, v30
	v_lshlrev_b64 v[32:33], 12, v[32:33]
	v_ashrrev_i32_e32 v37, 31, v36
	v_ashrrev_i32_e32 v35, 31, v34
	v_ashrrev_i32_e32 v41, 31, v40
	v_ashrrev_i32_e32 v39, 31, v38
	v_ashrrev_i32_e32 v45, 31, v44
	v_ashrrev_i32_e32 v43, 31, v42
	v_ashrrev_i32_e32 v49, 31, v48
	v_ashrrev_i32_e32 v47, 31, v46
	v_ashrrev_i32_e32 v53, 31, v52
	v_ashrrev_i32_e32 v51, 31, v50
	v_ashrrev_i32_e32 v57, 31, v56
	v_ashrrev_i32_e32 v55, 31, v54
	v_ashrrev_i32_e32 v61, 31, v60
	v_ashrrev_i32_e32 v59, 31, v58
	v_lshlrev_b64 v[30:31], 12, v[30:31]
	v_lshl_add_u64 v[32:33], v[20:21], 0, v[32:33]
	v_lshlrev_b64 v[34:35], 12, v[34:35]
	v_lshlrev_b64 v[36:37], 12, v[36:37]
	v_lshlrev_b64 v[38:39], 12, v[38:39]
	v_lshlrev_b64 v[40:41], 12, v[40:41]
	v_lshlrev_b64 v[42:43], 12, v[42:43]
	v_lshlrev_b64 v[44:45], 12, v[44:45]
	v_lshlrev_b64 v[46:47], 12, v[46:47]
	v_lshlrev_b64 v[48:49], 12, v[48:49]
	v_lshlrev_b64 v[50:51], 12, v[50:51]
	v_lshlrev_b64 v[52:53], 12, v[52:53]
	v_lshlrev_b64 v[54:55], 12, v[54:55]
	v_lshlrev_b64 v[56:57], 12, v[56:57]
	v_lshlrev_b64 v[58:59], 12, v[58:59]
	v_lshlrev_b64 v[60:61], 12, v[60:61]
	v_lshl_add_u64 v[30:31], v[20:21], 0, v[30:31]
	v_lshl_add_u64 v[36:37], v[20:21], 0, v[36:37]
	v_lshl_add_u64 v[34:35], v[20:21], 0, v[34:35]
	v_lshl_add_u64 v[40:41], v[20:21], 0, v[40:41]
	v_lshl_add_u64 v[38:39], v[20:21], 0, v[38:39]
	v_lshl_add_u64 v[44:45], v[20:21], 0, v[44:45]
	v_lshl_add_u64 v[42:43], v[20:21], 0, v[42:43]
	v_lshl_add_u64 v[48:49], v[20:21], 0, v[48:49]
	v_lshl_add_u64 v[46:47], v[20:21], 0, v[46:47]
	v_lshl_add_u64 v[52:53], v[20:21], 0, v[52:53]
	v_lshl_add_u64 v[50:51], v[20:21], 0, v[50:51]
	v_lshl_add_u64 v[56:57], v[20:21], 0, v[56:57]
	v_lshl_add_u64 v[54:55], v[20:21], 0, v[54:55]
	v_lshl_add_u64 v[60:61], v[20:21], 0, v[60:61]
	v_lshl_add_u64 v[58:59], v[20:21], 0, v[58:59]
	global_load_dword v75, v[32:33], off
	global_load_dword v76, v[30:31], off
	global_load_dword v77, v[36:37], off
	global_load_dword v78, v[34:35], off
	global_load_dword v79, v[40:41], off
	global_load_dword v80, v[38:39], off
	global_load_dword v81, v[44:45], off
	global_load_dword v82, v[42:43], off
	global_load_dword v83, v[48:49], off
	global_load_dword v84, v[46:47], off
	global_load_dword v85, v[52:53], off
	global_load_dword v86, v[50:51], off
	global_load_dword v87, v[56:57], off
	global_load_dword v88, v[54:55], off
	global_load_dword v89, v[60:61], off
	global_load_dword v90, v[58:59], off
	s_add_i32 s17, s17, 16
	s_add_i32 s16, s16, 16
	s_add_i32 s18, s18, -16
	v_mad_u64_u32 v[30:31], s[20:21], v19, s1, v[2:3]
	s_cmp_lg_u32 s18, 0
	v_mad_u64_u32 v[32:33], s[20:21], v4, s1, v[2:3]
	v_mad_u64_u32 v[34:35], s[20:21], v62, s1, v[2:3]
	v_mad_u64_u32 v[36:37], s[20:21], v29, s1, v[2:3]
	v_mad_u64_u32 v[38:39], s[20:21], v64, s1, v[2:3]
	v_mad_u64_u32 v[40:41], s[20:21], v63, s1, v[2:3]
	v_mad_u64_u32 v[42:43], s[20:21], v66, s1, v[2:3]
	v_mad_u64_u32 v[44:45], s[20:21], v65, s1, v[2:3]
	v_mad_u64_u32 v[46:47], s[20:21], v68, s1, v[2:3]
	v_mad_u64_u32 v[48:49], s[20:21], v67, s1, v[2:3]
	v_mad_u64_u32 v[50:51], s[20:21], v70, s1, v[2:3]
	v_mad_u64_u32 v[52:53], s[20:21], v69, s1, v[2:3]
	v_mad_u64_u32 v[54:55], s[20:21], v72, s1, v[2:3]
	v_mad_u64_u32 v[56:57], s[20:21], v71, s1, v[2:3]
	v_mad_u64_u32 v[58:59], s[20:21], v74, s1, v[2:3]
	v_mad_u64_u32 v[60:61], s[20:21], v73, s1, v[2:3]
	s_waitcnt vmcnt(15)
	ds_write_b32 v30, v75
	s_waitcnt vmcnt(14)
	ds_write_b32 v32, v76
	s_waitcnt vmcnt(13)
	ds_write_b32 v34, v77
	s_waitcnt vmcnt(12)
	ds_write_b32 v36, v78
	s_waitcnt vmcnt(11)
	ds_write_b32 v38, v79
	s_waitcnt vmcnt(10)
	ds_write_b32 v40, v80
	s_waitcnt vmcnt(9)
	ds_write_b32 v42, v81
	s_waitcnt vmcnt(8)
	ds_write_b32 v44, v82
	s_waitcnt vmcnt(7)
	ds_write_b32 v46, v83
	s_waitcnt vmcnt(6)
	ds_write_b32 v48, v84
	s_waitcnt vmcnt(5)
	ds_write_b32 v50, v85
	s_waitcnt vmcnt(4)
	ds_write_b32 v52, v86
	s_waitcnt vmcnt(3)
	ds_write_b32 v54, v87
	s_waitcnt vmcnt(2)
	ds_write_b32 v56, v88
	s_waitcnt vmcnt(1)
	ds_write_b32 v58, v89
	s_waitcnt vmcnt(0)
	ds_write_b32 v60, v90
	s_cbranch_scc1 .LBB0_640
; #define LAS __attribute__((address_space(3)))
; __device__ __forceinline__ unsigned pk2(float lo, float hi) { return f2bf(lo) | (f2bf(hi) << 16); }
; __device__ __forceinline__ void tr_item(const float* W, int ldw, int src_col0, int k0, bf16_t* dst, int ldd, int dst_row0, int dst_col0, LAS float* scr, int lane) {
;     ...
;     const int c = lane & 7;
; #pragma unroll
;     for (int j = 0; j < 4; ++j) { const int n = (lane >> 3) + 8 * j; const LAS float* s = scr + (8 * c) * 33 + n;
;         u32x4 o; o.x = pk2(s[0 * 33], s[1 * 33]); o.y = pk2(s[2 * 33], s[3 * 33]); o.z = pk2(s[4 * 33], s[5 * 33]); o.w = pk2(s[6 * 33], s[7 * 33]);
;         *(u32x4*)(dst + (size_t)(dst_row0 + n) * ldd + dst_col0 + k0 + 8 * c) = o; }
;     asm volatile("s_waitcnt lgkmcnt(0)" ::: "memory");
	s_waitcnt lgkmcnt(0)
	ds_read2_b32 v[30:31], v24 offset1:8
	ds_read2_b32 v[34:35], v24 offset0:33 offset1:41
	ds_read2_b32 v[36:37], v24 offset0:66 offset1:74
	ds_read2_b32 v[38:39], v24 offset0:99 offset1:107
	ds_read2_b32 v[40:41], v24 offset0:132 offset1:140
	v_mov_b32_e32 v19, v5
	s_waitcnt lgkmcnt(4)
	s_waitcnt lgkmcnt(3)
	ds_read2_b32 v[42:43], v24 offset0:165 offset1:173
	v_lshl_add_u64 v[32:33], v[18:19], 1, v[6:7]
	v_cvt_pk_bf16_f32 v18, v30, v34
	s_waitcnt lgkmcnt(3)
	s_waitcnt lgkmcnt(2)
	ds_read2_b32 v[44:45], v24 offset0:198 offset1:206
	ds_read2_b32 v[46:47], v24 offset0:231 offset1:239
	v_cvt_pk_bf16_f32 v19, v36, v38
	s_waitcnt lgkmcnt(3)
	s_waitcnt lgkmcnt(2)
	v_cvt_pk_bf16_f32 v20, v40, v42
	s_waitcnt lgkmcnt(1)
	s_waitcnt lgkmcnt(0)
	v_cvt_pk_bf16_f32 v21, v44, v46
	v_or_b32_e32 v3, v28, v23
	v_lshlrev_b32_e32 v4, 11, v3
	v_bfe_u32 v3, v31, 16, 1
	v_lshl_add_u64 v[48:49], v[32:33], 0, v[4:5]
	v_add3_u32 v3, v31, v3, s13
	v_bfe_u32 v4, v35, 16, 1
	v_lshrrev_b32_e32 v3, 16, v3
	v_add3_u32 v4, v35, v4, s13
	global_store_dwordx4 v[48:49], v[18:21], off
	ds_read2_b32 v[30:31], v24 offset0:16 offset1:24
	s_nop 0
	v_and_or_b32 v18, v4, s14, v3
	v_cvt_pk_bf16_f32 v19, v37, v39
	v_cvt_pk_bf16_f32 v20, v41, v43
	v_cvt_pk_bf16_f32 v21, v45, v47
	v_or_b32_e32 v3, v28, v25
	v_lshlrev_b32_e32 v4, 11, v3
	v_lshl_add_u64 v[34:35], v[32:33], 0, v[4:5]
	global_store_dwordx4 v[34:35], v[18:21], off
	ds_read2_b32 v[34:35], v24 offset0:49 offset1:57
	ds_read2_b32 v[36:37], v24 offset0:82 offset1:90
	ds_read2_b32 v[38:39], v24 offset0:115 offset1:123
	s_waitcnt lgkmcnt(3)
	s_waitcnt lgkmcnt(2)
	ds_read2_b32 v[40:41], v24 offset0:148 offset1:156
	ds_read2_b32 v[42:43], v24 offset0:181 offset1:189
	v_cvt_pk_bf16_f32 v18, v30, v34
	s_waitcnt lgkmcnt(3)
	s_waitcnt lgkmcnt(2)
	ds_read2_b32 v[44:45], v24 offset0:214 offset1:222
	ds_read2_b32 v[46:47], v24 offset0:247 offset1:255
	v_cvt_pk_bf16_f32 v19, v36, v38
	s_waitcnt lgkmcnt(3)
	s_waitcnt lgkmcnt(2)
	v_cvt_pk_bf16_f32 v20, v40, v42
	s_waitcnt lgkmcnt(1)
	s_waitcnt lgkmcnt(0)
	v_cvt_pk_bf16_f32 v21, v44, v46
	v_or_b32_e32 v3, v28, v26
	v_lshlrev_b32_e32 v4, 11, v3
	v_lshl_add_u64 v[48:49], v[32:33], 0, v[4:5]
	global_store_dwordx4 v[48:49], v[18:21], off
	s_nop 1
	v_cvt_pk_bf16_f32 v18, v31, v35
	v_cvt_pk_bf16_f32 v19, v37, v39
	v_cvt_pk_bf16_f32 v20, v41, v43
	v_cvt_pk_bf16_f32 v21, v45, v47
	v_or_b32_e32 v3, v28, v27
	v_lshlrev_b32_e32 v4, 11, v3
	v_lshl_add_u64 v[28:29], v[32:33], 0, v[4:5]
	global_store_dwordx4 v[28:29], v[18:21], off
	s_waitcnt lgkmcnt(0)

; #define LAS __attribute__((address_space(3)))
; __device__ __forceinline__ void tr_item(const float* W, int ldw, int src_col0, int k0, bf16_t* dst, int ldd, int dst_row0, int dst_col0, LAS float* scr, int lane) {
; #pragma unroll 8
;     for (int i = 0; i < 32; ++i) { const int kk = 2 * i + (lane >> 5); scr[kk * 33 + (lane & 31)] = W[(size_t)(k0 + kk) * ldw + src_col0 + (lane & 31)]; }
;     asm volatile("s_waitcnt lgkmcnt(0)" ::: "memory");
.LBB0_644:
	s_lshl_b32 s19, s16, 1
	s_lshl_b32 s20, s17, 1
	v_or_b32_e32 v4, s19, v1
	v_or_b32_e32 v19, s20, v0
	s_add_i32 s21, s19, 4
	s_add_i32 s22, s20, 4
	s_add_i32 s23, s19, 8
	s_add_i32 s24, s20, 8
	s_add_i32 s25, s19, 12
	s_add_i32 s26, s20, 12
	s_add_i32 s27, s19, 16
	s_add_i32 s28, s20, 16
	s_add_i32 s29, s19, 20
	s_add_i32 s30, s20, 20
	s_add_i32 s31, s19, 24
	s_add_i32 s34, s20, 24
	s_add_i32 s19, s19, 28
	s_add_i32 s20, s20, 28
	v_add_u32_e32 v32, v19, v18
	v_or_b32_e32 v29, s21, v1
	v_or_b32_e32 v62, s22, v0
	v_or_b32_e32 v63, s23, v1
	v_or_b32_e32 v64, s24, v0
	v_or_b32_e32 v65, s25, v1
	v_or_b32_e32 v66, s26, v0
	v_or_b32_e32 v67, s27, v1
	v_or_b32_e32 v68, s28, v0
	v_or_b32_e32 v69, s29, v1
	v_or_b32_e32 v70, s30, v0
	v_or_b32_e32 v71, s31, v1
	v_or_b32_e32 v72, s34, v0
	v_or_b32_e32 v73, s19, v1
	v_or_b32_e32 v74, s20, v0
	v_add_u32_e32 v30, v4, v3
	v_ashrrev_i32_e32 v33, 31, v32
	v_add_u32_e32 v34, v29, v3
	v_add_u32_e32 v36, v62, v18
	v_add_u32_e32 v38, v63, v3
	v_add_u32_e32 v40, v64, v18
	v_add_u32_e32 v42, v65, v3
	v_add_u32_e32 v44, v66, v18
	v_add_u32_e32 v46, v67, v3
	v_add_u32_e32 v48, v68, v18
	v_add_u32_e32 v50, v69, v3
	v_add_u32_e32 v52, v70, v18
	v_add_u32_e32 v54, v71, v3
	v_add_u32_e32 v56, v72, v18
	v_add_u32_e32 v58, v73, v3
	v_add_u32_e32 v60, v74, v18
	v_ashrrev_i32_e32 v31, 31, v30
	v_lshlrev_b64 v[32:33], 12, v[32:33]
	v_ashrrev_i32_e32 v37, 31, v36
	v_ashrrev_i32_e32 v35, 31, v34
	v_ashrrev_i32_e32 v41, 31, v40
	v_ashrrev_i32_e32 v39, 31, v38
	v_ashrrev_i32_e32 v45, 31, v44
	v_ashrrev_i32_e32 v43, 31, v42
	v_ashrrev_i32_e32 v49, 31, v48
	v_ashrrev_i32_e32 v47, 31, v46
	v_ashrrev_i32_e32 v53, 31, v52
	v_ashrrev_i32_e32 v51, 31, v50
	v_ashrrev_i32_e32 v57, 31, v56
	v_ashrrev_i32_e32 v55, 31, v54
	v_ashrrev_i32_e32 v61, 31, v60
	v_ashrrev_i32_e32 v59, 31, v58
	v_lshlrev_b64 v[30:31], 12, v[30:31]
	v_lshl_add_u64 v[32:33], v[20:21], 0, v[32:33]
	v_lshlrev_b64 v[34:35], 12, v[34:35]
	v_lshlrev_b64 v[36:37], 12, v[36:37]
	v_lshlrev_b64 v[38:39], 12, v[38:39]
	v_lshlrev_b64 v[40:41], 12, v[40:41]
	v_lshlrev_b64 v[42:43], 12, v[42:43]
	v_lshlrev_b64 v[44:45], 12, v[44:45]
	v_lshlrev_b64 v[46:47], 12, v[46:47]
	v_lshlrev_b64 v[48:49], 12, v[48:49]
	v_lshlrev_b64 v[50:51], 12, v[50:51]
	v_lshlrev_b64 v[52:53], 12, v[52:53]
	v_lshlrev_b64 v[54:55], 12, v[54:55]
	v_lshlrev_b64 v[56:57], 12, v[56:57]
	v_lshlrev_b64 v[58:59], 12, v[58:59]
	v_lshlrev_b64 v[60:61], 12, v[60:61]
	v_lshl_add_u64 v[30:31], v[20:21], 0, v[30:31]
	v_lshl_add_u64 v[36:37], v[20:21], 0, v[36:37]
	v_lshl_add_u64 v[34:35], v[20:21], 0, v[34:35]
	v_lshl_add_u64 v[40:41], v[20:21], 0, v[40:41]
	v_lshl_add_u64 v[38:39], v[20:21], 0, v[38:39]
	v_lshl_add_u64 v[44:45], v[20:21], 0, v[44:45]
	v_lshl_add_u64 v[42:43], v[20:21], 0, v[42:43]
	v_lshl_add_u64 v[48:49], v[20:21], 0, v[48:49]
	v_lshl_add_u64 v[46:47], v[20:21], 0, v[46:47]
	v_lshl_add_u64 v[52:53], v[20:21], 0, v[52:53]
	v_lshl_add_u64 v[50:51], v[20:21], 0, v[50:51]
	v_lshl_add_u64 v[56:57], v[20:21], 0, v[56:57]
	v_lshl_add_u64 v[54:55], v[20:21], 0, v[54:55]
	v_lshl_add_u64 v[60:61], v[20:21], 0, v[60:61]
	v_lshl_add_u64 v[58:59], v[20:21], 0, v[58:59]
	global_load_dword v75, v[32:33], off
	global_load_dword v76, v[30:31], off
	global_load_dword v77, v[36:37], off
	global_load_dword v78, v[34:35], off
	global_load_dword v79, v[40:41], off
	global_load_dword v80, v[38:39], off
	global_load_dword v81, v[44:45], off
	global_load_dword v82, v[42:43], off
	global_load_dword v83, v[48:49], off
	global_load_dword v84, v[46:47], off
	global_load_dword v85, v[52:53], off
	global_load_dword v86, v[50:51], off
	global_load_dword v87, v[56:57], off
	global_load_dword v88, v[54:55], off
	global_load_dword v89, v[60:61], off
	global_load_dword v90, v[58:59], off
	s_add_i32 s17, s17, 16
	s_add_i32 s16, s16, 16
	s_add_i32 s18, s18, -16
	v_mad_u64_u32 v[30:31], s[20:21], v19, s1, v[2:3]
	s_cmp_lg_u32 s18, 0
	v_mad_u64_u32 v[32:33], s[20:21], v4, s1, v[2:3]
	v_mad_u64_u32 v[34:35], s[20:21], v62, s1, v[2:3]
	v_mad_u64_u32 v[36:37], s[20:21], v29, s1, v[2:3]
	v_mad_u64_u32 v[38:39], s[20:21], v64, s1, v[2:3]
	v_mad_u64_u32 v[40:41], s[20:21], v63, s1, v[2:3]
	v_mad_u64_u32 v[42:43], s[20:21], v66, s1, v[2:3]
	v_mad_u64_u32 v[44:45], s[20:21], v65, s1, v[2:3]
	v_mad_u64_u32 v[46:47], s[20:21], v68, s1, v[2:3]
	v_mad_u64_u32 v[48:49], s[20:21], v67, s1, v[2:3]
	v_mad_u64_u32 v[50:51], s[20:21], v70, s1, v[2:3]
	v_mad_u64_u32 v[52:53], s[20:21], v69, s1, v[2:3]
	v_mad_u64_u32 v[54:55], s[20:21], v72, s1, v[2:3]
	v_mad_u64_u32 v[56:57], s[20:21], v71, s1, v[2:3]
	v_mad_u64_u32 v[58:59], s[20:21], v74, s1, v[2:3]
	v_mad_u64_u32 v[60:61], s[20:21], v73, s1, v[2:3]
	s_waitcnt vmcnt(15)
	ds_write_b32 v30, v75
	s_waitcnt vmcnt(14)
	ds_write_b32 v32, v76
	s_waitcnt vmcnt(13)
	ds_write_b32 v34, v77
	s_waitcnt vmcnt(12)
	ds_write_b32 v36, v78
	s_waitcnt vmcnt(11)
	ds_write_b32 v38, v79
	s_waitcnt vmcnt(10)
	ds_write_b32 v40, v80
	s_waitcnt vmcnt(9)
	ds_write_b32 v42, v81
	s_waitcnt vmcnt(8)
	ds_write_b32 v44, v82
	s_waitcnt vmcnt(7)
	ds_write_b32 v46, v83
	s_waitcnt vmcnt(6)
	ds_write_b32 v48, v84
	s_waitcnt vmcnt(5)
	ds_write_b32 v50, v85
	s_waitcnt vmcnt(4)
	ds_write_b32 v52, v86
	s_waitcnt vmcnt(3)
	ds_write_b32 v54, v87
	s_waitcnt vmcnt(2)
	ds_write_b32 v56, v88
	s_waitcnt vmcnt(1)
	ds_write_b32 v58, v89
	s_waitcnt vmcnt(0)
	ds_write_b32 v60, v90
	s_cbranch_scc1 .LBB0_644
; #define LAS __attribute__((address_space(3)))
; __device__ __forceinline__ unsigned pk2(float lo, float hi) { return f2bf(lo) | (f2bf(hi) << 16); }
; __device__ __forceinline__ void tr_item(const float* W, int ldw, int src_col0, int k0, bf16_t* dst, int ldd, int dst_row0, int dst_col0, LAS float* scr, int lane) {
;     ...
;     const int c = lane & 7;
; #pragma unroll
;     for (int j = 0; j < 4; ++j) { const int n = (lane >> 3) + 8 * j; const LAS float* s = scr + (8 * c) * 33 + n;
;         u32x4 o; o.x = pk2(s[0 * 33], s[1 * 33]); o.y = pk2(s[2 * 33], s[3 * 33]); o.z = pk2(s[4 * 33], s[5 * 33]); o.w = pk2(s[6 * 33], s[7 * 33]);
;         *(u32x4*)(dst + (size_t)(dst_row0 + n) * ldd + dst_col0 + k0 + 8 * c) = o; }
;     asm volatile("s_waitcnt lgkmcnt(0)" ::: "memory");
	s_waitcnt lgkmcnt(0)
	ds_read2_b32 v[30:31], v24 offset1:8
	ds_read2_b32 v[34:35], v24 offset0:33 offset1:41
	ds_read2_b32 v[36:37], v24 offset0:66 offset1:74
	ds_read2_b32 v[38:39], v24 offset0:99 offset1:107
	ds_read2_b32 v[40:41], v24 offset0:132 offset1:140
	v_mov_b32_e32 v19, v5
	s_waitcnt lgkmcnt(4)
	s_waitcnt lgkmcnt(3)
	ds_read2_b32 v[42:43], v24 offset0:165 offset1:173
	v_lshl_add_u64 v[32:33], v[18:19], 1, v[8:9]
	v_cvt_pk_bf16_f32 v18, v30, v34
	s_waitcnt lgkmcnt(3)
	s_waitcnt lgkmcnt(2)
	ds_read2_b32 v[44:45], v24 offset0:198 offset1:206
	ds_read2_b32 v[46:47], v24 offset0:231 offset1:239
	v_cvt_pk_bf16_f32 v19, v36, v38
	s_waitcnt lgkmcnt(3)
	s_waitcnt lgkmcnt(2)
	v_cvt_pk_bf16_f32 v20, v40, v42
	s_waitcnt lgkmcnt(1)
	s_waitcnt lgkmcnt(0)
	v_cvt_pk_bf16_f32 v21, v44, v46
	v_or_b32_e32 v3, v28, v23
	v_lshlrev_b32_e32 v4, 12, v3
	v_bfe_u32 v3, v31, 16, 1
	v_lshl_add_u64 v[48:49], v[32:33], 0, v[4:5]
	v_add3_u32 v3, v31, v3, s13
	v_bfe_u32 v4, v35, 16, 1
	v_lshrrev_b32_e32 v3, 16, v3
	v_add3_u32 v4, v35, v4, s13
	global_store_dwordx4 v[48:49], v[18:21], off
	ds_read2_b32 v[30:31], v24 offset0:16 offset1:24
	s_nop 0
	v_and_or_b32 v18, v4, s14, v3
	v_cvt_pk_bf16_f32 v19, v37, v39
	v_cvt_pk_bf16_f32 v20, v41, v43
	v_cvt_pk_bf16_f32 v21, v45, v47
	v_or_b32_e32 v3, v28, v25
	v_lshlrev_b32_e32 v4, 12, v3
	v_lshl_add_u64 v[34:35], v[32:33], 0, v[4:5]
	global_store_dwordx4 v[34:35], v[18:21], off
	ds_read2_b32 v[34:35], v24 offset0:49 offset1:57
	ds_read2_b32 v[36:37], v24 offset0:82 offset1:90
	ds_read2_b32 v[38:39], v24 offset0:115 offset1:123
	s_waitcnt lgkmcnt(3)
	s_waitcnt lgkmcnt(2)
	ds_read2_b32 v[40:41], v24 offset0:148 offset1:156
	ds_read2_b32 v[42:43], v24 offset0:181 offset1:189
	v_cvt_pk_bf16_f32 v18, v30, v34
	s_waitcnt lgkmcnt(3)
	s_waitcnt lgkmcnt(2)
	ds_read2_b32 v[44:45], v24 offset0:214 offset1:222
	ds_read2_b32 v[46:47], v24 offset0:247 offset1:255
	v_cvt_pk_bf16_f32 v19, v36, v38
	s_waitcnt lgkmcnt(3)
	s_waitcnt lgkmcnt(2)
	v_cvt_pk_bf16_f32 v20, v40, v42
	s_waitcnt lgkmcnt(1)
	s_waitcnt lgkmcnt(0)
	v_cvt_pk_bf16_f32 v21, v44, v46
	v_or_b32_e32 v3, v28, v26
	v_lshlrev_b32_e32 v4, 12, v3
	v_lshl_add_u64 v[48:49], v[32:33], 0, v[4:5]
	global_store_dwordx4 v[48:49], v[18:21], off
	s_nop 1
	v_cvt_pk_bf16_f32 v18, v31, v35
	v_cvt_pk_bf16_f32 v19, v37, v39
	v_cvt_pk_bf16_f32 v20, v41, v43
	v_cvt_pk_bf16_f32 v21, v45, v47
	v_or_b32_e32 v3, v28, v27
	v_lshlrev_b32_e32 v4, 12, v3
	v_lshl_add_u64 v[28:29], v[32:33], 0, v[4:5]
	global_store_dwordx4 v[28:29], v[18:21], off
	s_waitcnt lgkmcnt(0)

; #define LAS __attribute__((address_space(3)))
; __device__ __forceinline__ void tr_item(const float* W, int ldw, int src_col0, int k0, bf16_t* dst, int ldd, int dst_row0, int dst_col0, LAS float* scr, int lane) {
; #pragma unroll 8
;     for (int i = 0; i < 32; ++i) { const int kk = 2 * i + (lane >> 5); scr[kk * 33 + (lane & 31)] = W[(size_t)(k0 + kk) * ldw + src_col0 + (lane & 31)]; }
;     asm volatile("s_waitcnt lgkmcnt(0)" ::: "memory");
.LBB0_649:
	s_lshl_b32 s17, s10, 1
	s_lshl_b32 s18, s11, 1
	v_or_b32_e32 v4, s17, v1
	v_or_b32_e32 v19, s18, v0
	s_add_i32 s19, s17, 4
	s_add_i32 s20, s18, 4
	s_add_i32 s21, s17, 8
	s_add_i32 s22, s18, 8
	s_add_i32 s23, s17, 12
	s_add_i32 s24, s18, 12
	s_add_i32 s25, s17, 16
	s_add_i32 s26, s18, 16
	s_add_i32 s27, s17, 20
	s_add_i32 s28, s18, 20
	s_add_i32 s29, s17, 24
	s_add_i32 s30, s18, 24
	s_add_i32 s17, s17, 28
	s_add_i32 s18, s18, 28
	v_add_u32_e32 v32, v19, v18
	v_or_b32_e32 v29, s19, v1
	v_or_b32_e32 v62, s20, v0
	v_or_b32_e32 v63, s21, v1
	v_or_b32_e32 v64, s22, v0
	v_or_b32_e32 v65, s23, v1
	v_or_b32_e32 v66, s24, v0
	v_or_b32_e32 v67, s25, v1
	v_or_b32_e32 v68, s26, v0
	v_or_b32_e32 v69, s27, v1
	v_or_b32_e32 v70, s28, v0
	v_or_b32_e32 v71, s29, v1
	v_or_b32_e32 v72, s30, v0
	v_or_b32_e32 v73, s17, v1
	v_or_b32_e32 v74, s18, v0
	v_add_u32_e32 v30, v4, v3
	v_ashrrev_i32_e32 v33, 31, v32
	v_add_u32_e32 v34, v29, v3
	v_add_u32_e32 v36, v62, v18
	v_add_u32_e32 v38, v63, v3
	v_add_u32_e32 v40, v64, v18
	v_add_u32_e32 v42, v65, v3
	v_add_u32_e32 v44, v66, v18
	v_add_u32_e32 v46, v67, v3
	v_add_u32_e32 v48, v68, v18
	v_add_u32_e32 v50, v69, v3
	v_add_u32_e32 v52, v70, v18
	v_add_u32_e32 v54, v71, v3
	v_add_u32_e32 v56, v72, v18
	v_add_u32_e32 v58, v73, v3
	v_add_u32_e32 v60, v74, v18
	v_ashrrev_i32_e32 v31, 31, v30
	v_lshlrev_b64 v[32:33], 12, v[32:33]
	v_ashrrev_i32_e32 v37, 31, v36
	v_ashrrev_i32_e32 v35, 31, v34
	v_ashrrev_i32_e32 v41, 31, v40
	v_ashrrev_i32_e32 v39, 31, v38
	v_ashrrev_i32_e32 v45, 31, v44
	v_ashrrev_i32_e32 v43, 31, v42
	v_ashrrev_i32_e32 v49, 31, v48
	v_ashrrev_i32_e32 v47, 31, v46
	v_ashrrev_i32_e32 v53, 31, v52
	v_ashrrev_i32_e32 v51, 31, v50
	v_ashrrev_i32_e32 v57, 31, v56
	v_ashrrev_i32_e32 v55, 31, v54
	v_ashrrev_i32_e32 v61, 31, v60
	v_ashrrev_i32_e32 v59, 31, v58
	v_lshlrev_b64 v[30:31], 12, v[30:31]
	v_lshl_add_u64 v[32:33], v[20:21], 0, v[32:33]
	v_lshlrev_b64 v[34:35], 12, v[34:35]
	v_lshlrev_b64 v[36:37], 12, v[36:37]
	v_lshlrev_b64 v[38:39], 12, v[38:39]
	v_lshlrev_b64 v[40:41], 12, v[40:41]
	v_lshlrev_b64 v[42:43], 12, v[42:43]
	v_lshlrev_b64 v[44:45], 12, v[44:45]
	v_lshlrev_b64 v[46:47], 12, v[46:47]
	v_lshlrev_b64 v[48:49], 12, v[48:49]
	v_lshlrev_b64 v[50:51], 12, v[50:51]
	v_lshlrev_b64 v[52:53], 12, v[52:53]
	v_lshlrev_b64 v[54:55], 12, v[54:55]
	v_lshlrev_b64 v[56:57], 12, v[56:57]
	v_lshlrev_b64 v[58:59], 12, v[58:59]
	v_lshlrev_b64 v[60:61], 12, v[60:61]
	v_lshl_add_u64 v[30:31], v[20:21], 0, v[30:31]
	v_lshl_add_u64 v[36:37], v[20:21], 0, v[36:37]
	v_lshl_add_u64 v[34:35], v[20:21], 0, v[34:35]
	v_lshl_add_u64 v[40:41], v[20:21], 0, v[40:41]
	v_lshl_add_u64 v[38:39], v[20:21], 0, v[38:39]
	v_lshl_add_u64 v[44:45], v[20:21], 0, v[44:45]
	v_lshl_add_u64 v[42:43], v[20:21], 0, v[42:43]
	v_lshl_add_u64 v[48:49], v[20:21], 0, v[48:49]
	v_lshl_add_u64 v[46:47], v[20:21], 0, v[46:47]
	v_lshl_add_u64 v[52:53], v[20:21], 0, v[52:53]
	v_lshl_add_u64 v[50:51], v[20:21], 0, v[50:51]
	v_lshl_add_u64 v[56:57], v[20:21], 0, v[56:57]
	v_lshl_add_u64 v[54:55], v[20:21], 0, v[54:55]
	v_lshl_add_u64 v[60:61], v[20:21], 0, v[60:61]
	v_lshl_add_u64 v[58:59], v[20:21], 0, v[58:59]
	global_load_dword v75, v[32:33], off
	global_load_dword v76, v[30:31], off
	global_load_dword v77, v[36:37], off
	global_load_dword v78, v[34:35], off
	global_load_dword v79, v[40:41], off
	global_load_dword v80, v[38:39], off
	global_load_dword v81, v[44:45], off
	global_load_dword v82, v[42:43], off
	global_load_dword v83, v[48:49], off
	global_load_dword v84, v[46:47], off
	global_load_dword v85, v[52:53], off
	global_load_dword v86, v[50:51], off
	global_load_dword v87, v[56:57], off
	global_load_dword v88, v[54:55], off
	global_load_dword v89, v[60:61], off
	global_load_dword v90, v[58:59], off
	s_add_i32 s11, s11, 16
	s_add_i32 s10, s10, 16
	s_add_i32 s16, s16, -16
	v_mad_u64_u32 v[30:31], s[18:19], v19, s1, v[2:3]
	s_cmp_lg_u32 s16, 0
	v_mad_u64_u32 v[32:33], s[18:19], v4, s1, v[2:3]
	v_mad_u64_u32 v[34:35], s[18:19], v62, s1, v[2:3]
	v_mad_u64_u32 v[36:37], s[18:19], v29, s1, v[2:3]
	v_mad_u64_u32 v[38:39], s[18:19], v64, s1, v[2:3]
	v_mad_u64_u32 v[40:41], s[18:19], v63, s1, v[2:3]
	v_mad_u64_u32 v[42:43], s[18:19], v66, s1, v[2:3]
	v_mad_u64_u32 v[44:45], s[18:19], v65, s1, v[2:3]
	v_mad_u64_u32 v[46:47], s[18:19], v68, s1, v[2:3]
	v_mad_u64_u32 v[48:49], s[18:19], v67, s1, v[2:3]
	v_mad_u64_u32 v[50:51], s[18:19], v70, s1, v[2:3]
	v_mad_u64_u32 v[52:53], s[18:19], v69, s1, v[2:3]
	v_mad_u64_u32 v[54:55], s[18:19], v72, s1, v[2:3]
	v_mad_u64_u32 v[56:57], s[18:19], v71, s1, v[2:3]
	v_mad_u64_u32 v[58:59], s[18:19], v74, s1, v[2:3]
	v_mad_u64_u32 v[60:61], s[18:19], v73, s1, v[2:3]
	s_waitcnt vmcnt(15)
	ds_write_b32 v30, v75
	s_waitcnt vmcnt(14)
	ds_write_b32 v32, v76
	s_waitcnt vmcnt(13)
	ds_write_b32 v34, v77
	s_waitcnt vmcnt(12)
	ds_write_b32 v36, v78
	s_waitcnt vmcnt(11)
	ds_write_b32 v38, v79
	s_waitcnt vmcnt(10)
	ds_write_b32 v40, v80
	s_waitcnt vmcnt(9)
	ds_write_b32 v42, v81
	s_waitcnt vmcnt(8)
	ds_write_b32 v44, v82
	s_waitcnt vmcnt(7)
	ds_write_b32 v46, v83
	s_waitcnt vmcnt(6)
	ds_write_b32 v48, v84
	s_waitcnt vmcnt(5)
	ds_write_b32 v50, v85
	s_waitcnt vmcnt(4)
	ds_write_b32 v52, v86
	s_waitcnt vmcnt(3)
	ds_write_b32 v54, v87
	s_waitcnt vmcnt(2)
	ds_write_b32 v56, v88
	s_waitcnt vmcnt(1)
	ds_write_b32 v58, v89
	s_waitcnt vmcnt(0)
	ds_write_b32 v60, v90
	s_cbranch_scc1 .LBB0_649
; #define LAS __attribute__((address_space(3)))
; __device__ __forceinline__ unsigned pk2(float lo, float hi) { return f2bf(lo) | (f2bf(hi) << 16); }
; __device__ __forceinline__ void tr_item(const float* W, int ldw, int src_col0, int k0, bf16_t* dst, int ldd, int dst_row0, int dst_col0, LAS float* scr, int lane) {
;     ...
;     const int c = lane & 7;
; #pragma unroll
;     for (int j = 0; j < 4; ++j) { const int n = (lane >> 3) + 8 * j; const LAS float* s = scr + (8 * c) * 33 + n;
;         u32x4 o; o.x = pk2(s[0 * 33], s[1 * 33]); o.y = pk2(s[2 * 33], s[3 * 33]); o.z = pk2(s[4 * 33], s[5 * 33]); o.w = pk2(s[6 * 33], s[7 * 33]);
;         *(u32x4*)(dst + (size_t)(dst_row0 + n) * ldd + dst_col0 + k0 + 8 * c) = o; }
;     asm volatile("s_waitcnt lgkmcnt(0)" ::: "memory");
	s_waitcnt lgkmcnt(0)
	ds_read2_b32 v[30:31], v24 offset1:8
	ds_read2_b32 v[34:35], v24 offset0:33 offset1:41
	ds_read2_b32 v[36:37], v24 offset0:66 offset1:74
	ds_read2_b32 v[38:39], v24 offset0:99 offset1:107
	ds_read2_b32 v[40:41], v24 offset0:132 offset1:140
	v_ashrrev_i32_e32 v19, 31, v18
	s_waitcnt lgkmcnt(4)
	s_waitcnt lgkmcnt(3)
	ds_read2_b32 v[42:43], v24 offset0:165 offset1:173
	v_lshl_add_u64 v[32:33], v[18:19], 1, v[10:11]
	v_cvt_pk_bf16_f32 v18, v30, v34
	s_waitcnt lgkmcnt(3)
	s_waitcnt lgkmcnt(2)
	ds_read2_b32 v[44:45], v24 offset0:198 offset1:206
	ds_read2_b32 v[46:47], v24 offset0:231 offset1:239
	v_cvt_pk_bf16_f32 v19, v36, v38
	s_waitcnt lgkmcnt(3)
	s_waitcnt lgkmcnt(2)
	v_cvt_pk_bf16_f32 v20, v40, v42
	s_waitcnt lgkmcnt(1)
	s_waitcnt lgkmcnt(0)
	v_cvt_pk_bf16_f32 v21, v44, v46
	v_or_b32_e32 v3, v28, v23
	v_lshlrev_b32_e32 v4, 12, v3
	v_bfe_u32 v3, v31, 16, 1
	v_lshl_add_u64 v[48:49], v[32:33], 0, v[4:5]
	v_add3_u32 v3, v31, v3, s13
	v_bfe_u32 v4, v35, 16, 1
	v_lshrrev_b32_e32 v3, 16, v3
	v_add3_u32 v4, v35, v4, s13
	global_store_dwordx4 v[48:49], v[18:21], off
	ds_read2_b32 v[30:31], v24 offset0:16 offset1:24
	s_nop 0
	v_and_or_b32 v18, v4, s14, v3
	v_cvt_pk_bf16_f32 v19, v37, v39
	v_cvt_pk_bf16_f32 v20, v41, v43
	v_cvt_pk_bf16_f32 v21, v45, v47
	v_or_b32_e32 v3, v28, v25
	v_lshlrev_b32_e32 v4, 12, v3
	v_lshl_add_u64 v[34:35], v[32:33], 0, v[4:5]
	global_store_dwordx4 v[34:35], v[18:21], off
	ds_read2_b32 v[34:35], v24 offset0:49 offset1:57
	ds_read2_b32 v[36:37], v24 offset0:82 offset1:90
	ds_read2_b32 v[38:39], v24 offset0:115 offset1:123
	s_waitcnt lgkmcnt(3)
	s_waitcnt lgkmcnt(2)
	ds_read2_b32 v[40:41], v24 offset0:148 offset1:156
	ds_read2_b32 v[42:43], v24 offset0:181 offset1:189
	v_cvt_pk_bf16_f32 v18, v30, v34
	s_waitcnt lgkmcnt(3)
	s_waitcnt lgkmcnt(2)
	ds_read2_b32 v[44:45], v24 offset0:214 offset1:222
	ds_read2_b32 v[46:47], v24 offset0:247 offset1:255
	v_cvt_pk_bf16_f32 v19, v36, v38
	s_waitcnt lgkmcnt(3)
	s_waitcnt lgkmcnt(2)
	v_cvt_pk_bf16_f32 v20, v40, v42
	s_waitcnt lgkmcnt(1)
	s_waitcnt lgkmcnt(0)
	v_cvt_pk_bf16_f32 v21, v44, v46
	v_or_b32_e32 v3, v28, v26
	v_lshlrev_b32_e32 v4, 12, v3
	v_lshl_add_u64 v[48:49], v[32:33], 0, v[4:5]
	global_store_dwordx4 v[48:49], v[18:21], off
	s_nop 1
	v_cvt_pk_bf16_f32 v18, v31, v35
	v_cvt_pk_bf16_f32 v19, v37, v39
	v_cvt_pk_bf16_f32 v20, v41, v43
	v_cvt_pk_bf16_f32 v21, v45, v47
	v_or_b32_e32 v3, v28, v27
	v_lshlrev_b32_e32 v4, 12, v3
	v_lshl_add_u64 v[28:29], v[32:33], 0, v[4:5]
	global_store_dwordx4 v[28:29], v[18:21], off
	s_waitcnt lgkmcnt(0)
	s_branch .LBB0_636

; __device__ __forceinline__ void gla_scan(const Params& P, LAS unsigned char* lds, int bh, int seg, int nseg, bool dry) {
;     ...
;         __syncthreads();
;         for (int i = 0; i < seg; ++i) {
;             const char* src = (const char*)(SL + (size_t)(bh * 3 + i) * 32768); const char* dsrc = (const char*)(DL + (size_t)(bh * 4 + i) * 128);
; #pragma unroll
;             for (int kt = 0; kt < 8; ++kt) {
;                 const f32x4 dv = i ? *(const f32x4*)(dsrc + (size_t)((unsigned)g * 16u + (unsigned)(64 * kt))) : (f32x4){0.f, 0.f, 0.f, 0.f};
; #pragma unroll
;                 for (int vt = 0; vt < 2; ++vt) S[kt][vt] = S[kt][vt] * dv + *(const f32x4*)(src + (size_t)((unsigned)tid * 16u + (unsigned)((kt * 2 + vt) * 8192)));
;                 asm volatile("" : "+v"(S[kt][0]), "+v"(S[kt][1]) :: "memory");
;             }
.LBB0_689:
	s_or_b64 exec, exec, s[4:5]
	s_mul_i32 s9, s1, 0x60000
	v_lshlrev_b32_e32 v66, 4, v114
	s_add_u32 s4, s18, s9
	s_addc_u32 s5, s19, 0
	v_add_u32_e32 v68, 0x2000, v66
	s_barrier
	v_add_u32_e32 v70, 0x4000, v66
	v_add_u32_e32 v72, 0x6000, v66
	v_add_u32_e32 v74, 0x8000, v66
	v_add_u32_e32 v76, 0xa000, v66
	v_add_u32_e32 v78, 0xc000, v66
	v_add_u32_e32 v80, 0xe000, v66
	v_add_u32_e32 v82, 0x10000, v66
	v_add_u32_e32 v84, 0x12000, v66
	v_add_u32_e32 v86, 0x14000, v66
	v_add_u32_e32 v88, 0x16000, v66
	v_add_u32_e32 v90, 0x18000, v66
	v_add_u32_e32 v92, 0x1a000, v66
	v_add_u32_e32 v94, 0x1c000, v66
	v_add_u32_e32 v96, 0x1e000, v66
	global_load_dwordx4 v[32:35], v66, s[4:5]
	global_load_dwordx4 v[0:3], v68, s[4:5]
	global_load_dwordx4 v[4:7], v70, s[4:5]
	global_load_dwordx4 v[8:11], v72, s[4:5]
	global_load_dwordx4 v[12:15], v74, s[4:5]
	global_load_dwordx4 v[16:19], v76, s[4:5]
	global_load_dwordx4 v[20:23], v78, s[4:5]
	global_load_dwordx4 v[24:27], v80, s[4:5]
	global_load_dwordx4 v[36:39], v82, s[4:5]
	global_load_dwordx4 v[28:31], v84, s[4:5]
	global_load_dwordx4 v[40:43], v86, s[4:5]
	global_load_dwordx4 v[44:47], v88, s[4:5]
	global_load_dwordx4 v[48:51], v90, s[4:5]
	global_load_dwordx4 v[52:55], v92, s[4:5]
	global_load_dwordx4 v[56:59], v94, s[4:5]
	global_load_dwordx4 v[60:63], v96, s[4:5]
	s_cmp_eq_u32 s3, 1
	s_mov_b32 s5, 0
	s_waitcnt vmcnt(0)
	v_pk_add_f32 v[34:35], v[34:35], 0 op_sel_hi:[1,0]
	v_pk_add_f32 v[32:33], v[32:33], 0 op_sel_hi:[1,0]
	v_pk_add_f32 v[2:3], v[2:3], 0 op_sel_hi:[1,0]
	v_pk_add_f32 v[0:1], v[0:1], 0 op_sel_hi:[1,0]
	v_pk_add_f32 v[6:7], v[6:7], 0 op_sel_hi:[1,0]
	v_pk_add_f32 v[4:5], v[4:5], 0 op_sel_hi:[1,0]
	v_pk_add_f32 v[10:11], v[10:11], 0 op_sel_hi:[1,0]
	v_pk_add_f32 v[8:9], v[8:9], 0 op_sel_hi:[1,0]
	v_pk_add_f32 v[14:15], v[14:15], 0 op_sel_hi:[1,0]
	v_pk_add_f32 v[12:13], v[12:13], 0 op_sel_hi:[1,0]
	v_pk_add_f32 v[18:19], v[18:19], 0 op_sel_hi:[1,0]
	v_pk_add_f32 v[16:17], v[16:17], 0 op_sel_hi:[1,0]
	v_pk_add_f32 v[22:23], v[22:23], 0 op_sel_hi:[1,0]
	v_pk_add_f32 v[20:21], v[20:21], 0 op_sel_hi:[1,0]
	v_pk_add_f32 v[26:27], v[26:27], 0 op_sel_hi:[1,0]
	v_pk_add_f32 v[24:25], v[24:25], 0 op_sel_hi:[1,0]
	v_pk_add_f32 v[38:39], v[38:39], 0 op_sel_hi:[1,0]
	v_pk_add_f32 v[36:37], v[36:37], 0 op_sel_hi:[1,0]
	v_pk_add_f32 v[30:31], v[30:31], 0 op_sel_hi:[1,0]
	v_pk_add_f32 v[28:29], v[28:29], 0 op_sel_hi:[1,0]
	v_pk_add_f32 v[42:43], v[42:43], 0 op_sel_hi:[1,0]
	v_pk_add_f32 v[40:41], v[40:41], 0 op_sel_hi:[1,0]
	v_pk_add_f32 v[46:47], v[46:47], 0 op_sel_hi:[1,0]
	v_pk_add_f32 v[44:45], v[44:45], 0 op_sel_hi:[1,0]
	v_pk_add_f32 v[50:51], v[50:51], 0 op_sel_hi:[1,0]
	v_pk_add_f32 v[48:49], v[48:49], 0 op_sel_hi:[1,0]
	v_pk_add_f32 v[54:55], v[54:55], 0 op_sel_hi:[1,0]
	v_pk_add_f32 v[52:53], v[52:53], 0 op_sel_hi:[1,0]
	v_pk_add_f32 v[58:59], v[58:59], 0 op_sel_hi:[1,0]
	v_pk_add_f32 v[56:57], v[56:57], 0 op_sel_hi:[1,0]
	v_pk_add_f32 v[62:63], v[62:63], 0 op_sel_hi:[1,0]
	v_pk_add_f32 v[60:61], v[60:61], 0 op_sel_hi:[1,0]
	s_cbranch_scc1 .LBB0_692
	v_mov_b32_e32 v67, 0
	s_lshl_b32 s4, s1, 2
	v_lshlrev_b32_e32 v64, 4, v100
	v_mov_b32_e32 v65, v67
	s_add_i32 s8, s3, -1
	s_or_b32 s4, s4, 1
	v_mov_b32_e32 v69, v67
	v_mov_b32_e32 v71, v67
	v_mov_b32_e32 v73, v67
	v_mov_b32_e32 v75, v67
	v_mov_b32_e32 v77, v67
	v_mov_b32_e32 v79, v67
	v_mov_b32_e32 v81, v67
	v_mov_b32_e32 v83, v67
	v_mov_b32_e32 v85, v67
	v_mov_b32_e32 v87, v67
	v_mov_b32_e32 v89, v67
	v_mov_b32_e32 v91, v67
	v_mov_b32_e32 v93, v67
	v_mov_b32_e32 v95, v67
	v_mov_b32_e32 v97, v67
	v_lshl_add_u64 v[64:65], s[6:7], 0, v[64:65]
	s_mov_b64 s[10:11], 0x1f020000
	s_add_u32 s6, s70, s9
	v_lshl_add_u64 v[66:67], v[66:67], 0, s[10:11]
	s_addc_u32 s7, s71, 0
	v_lshl_add_u64 v[68:69], v[68:69], 0, s[10:11]
	v_lshl_add_u64 v[70:71], v[70:71], 0, s[10:11]
	v_lshl_add_u64 v[72:73], v[72:73], 0, s[10:11]
	v_lshl_add_u64 v[74:75], v[74:75], 0, s[10:11]
	v_lshl_add_u64 v[76:77], v[76:77], 0, s[10:11]
	v_lshl_add_u64 v[78:79], v[78:79], 0, s[10:11]
	v_lshl_add_u64 v[80:81], v[80:81], 0, s[10:11]
	v_lshl_add_u64 v[82:83], v[82:83], 0, s[10:11]
	v_lshl_add_u64 v[84:85], v[84:85], 0, s[10:11]
	v_lshl_add_u64 v[86:87], v[86:87], 0, s[10:11]
	v_lshl_add_u64 v[88:89], v[88:89], 0, s[10:11]
	v_lshl_add_u64 v[90:91], v[90:91], 0, s[10:11]
	v_lshl_add_u64 v[92:93], v[92:93], 0, s[10:11]
	v_lshl_add_u64 v[94:95], v[94:95], 0, s[10:11]
	v_lshl_add_u64 v[96:97], v[96:97], 0, s[10:11]
; __device__ __forceinline__ void gla_scan(const Params& P, LAS unsigned char* lds, int bh, int seg, int nseg, bool dry) {
;     ...
;         for (int i = 0; i < seg; ++i) {
;             const char* src = (const char*)(SL + (size_t)(bh * 3 + i) * 32768); const char* dsrc = (const char*)(DL + (size_t)(bh * 4 + i) * 128);
; #pragma unroll
;             for (int kt = 0; kt < 8; ++kt) {
;                 const f32x4 dv = i ? *(const f32x4*)(dsrc + (size_t)((unsigned)g * 16u + (unsigned)(64 * kt))) : (f32x4){0.f, 0.f, 0.f, 0.f};
; #pragma unroll
;                 for (int vt = 0; vt < 2; ++vt) S[kt][vt] = S[kt][vt] * dv + *(const f32x4*)(src + (size_t)((unsigned)tid * 16u + (unsigned)((kt * 2 + vt) * 8192)));
;                 asm volatile("" : "+v"(S[kt][0]), "+v"(S[kt][1]) :: "memory");
;             }
.LBB0_691:
	s_lshl_b64 s[10:11], s[4:5], 9
	v_lshl_add_u64 v[98:99], v[64:65], 0, s[10:11]
	global_load_dwordx4 v[120:123], v[98:99], off
	global_load_dwordx4 v[124:127], v[98:99], off offset:64
	global_load_dwordx4 v[128:131], v[98:99], off offset:128
	global_load_dwordx4 v[132:135], v[98:99], off offset:192
	global_load_dwordx4 v[136:139], v[98:99], off offset:256
	global_load_dwordx4 v[140:143], v[98:99], off offset:320
	global_load_dwordx4 v[144:147], v[98:99], off offset:384
	global_load_dwordx4 v[148:151], v[98:99], off offset:448
	v_lshl_add_u64 v[116:117], s[6:7], 0, v[66:67]
	global_load_dwordx4 v[152:155], v[116:117], off
	v_lshl_add_u64 v[118:119], s[6:7], 0, v[68:69]
	global_load_dwordx4 v[156:159], v[118:119], off
	v_lshl_add_u64 v[116:117], s[6:7], 0, v[70:71]
	global_load_dwordx4 v[160:163], v[116:117], off
	v_lshl_add_u64 v[118:119], s[6:7], 0, v[72:73]
	global_load_dwordx4 v[164:167], v[118:119], off
	v_lshl_add_u64 v[116:117], s[6:7], 0, v[74:75]
	global_load_dwordx4 v[168:171], v[116:117], off
	v_lshl_add_u64 v[118:119], s[6:7], 0, v[76:77]
	global_load_dwordx4 v[172:175], v[118:119], off
	v_lshl_add_u64 v[116:117], s[6:7], 0, v[78:79]
	global_load_dwordx4 v[176:179], v[116:117], off
	v_lshl_add_u64 v[118:119], s[6:7], 0, v[80:81]
	global_load_dwordx4 v[180:183], v[118:119], off
	v_lshl_add_u64 v[116:117], s[6:7], 0, v[82:83]
	global_load_dwordx4 v[184:187], v[116:117], off
	v_lshl_add_u64 v[118:119], s[6:7], 0, v[84:85]
	global_load_dwordx4 v[188:191], v[118:119], off
	v_lshl_add_u64 v[116:117], s[6:7], 0, v[86:87]
	global_load_dwordx4 v[196:199], v[116:117], off
	v_lshl_add_u64 v[118:119], s[6:7], 0, v[88:89]
	global_load_dwordx4 v[200:203], v[118:119], off
	v_lshl_add_u64 v[116:117], s[6:7], 0, v[90:91]
	global_load_dwordx4 v[204:207], v[116:117], off
	v_lshl_add_u64 v[118:119], s[6:7], 0, v[92:93]
	global_load_dwordx4 v[208:211], v[118:119], off
	v_lshl_add_u64 v[116:117], s[6:7], 0, v[94:95]
	global_load_dwordx4 v[212:215], v[116:117], off
	v_lshl_add_u64 v[118:119], s[6:7], 0, v[96:97]
	global_load_dwordx4 v[216:219], v[118:119], off
	s_add_i32 s8, s8, -1
	s_add_i32 s4, s4, 1
	s_add_u32 s6, s6, 0x20000
	s_addc_u32 s7, s7, 0
	s_cmp_lg_u32 s8, 0
	s_waitcnt vmcnt(0)
	v_pk_fma_f32 v[34:35], v[34:35], v[122:123], v[154:155]
	v_pk_fma_f32 v[32:33], v[32:33], v[120:121], v[152:153]
	v_pk_fma_f32 v[2:3], v[2:3], v[122:123], v[158:159]
	v_pk_fma_f32 v[0:1], v[0:1], v[120:121], v[156:157]
	v_pk_fma_f32 v[6:7], v[6:7], v[126:127], v[162:163]
	v_pk_fma_f32 v[4:5], v[4:5], v[124:125], v[160:161]
	v_pk_fma_f32 v[10:11], v[10:11], v[126:127], v[166:167]
	v_pk_fma_f32 v[8:9], v[8:9], v[124:125], v[164:165]
	v_pk_fma_f32 v[14:15], v[14:15], v[130:131], v[170:171]
	v_pk_fma_f32 v[12:13], v[12:13], v[128:129], v[168:169]
	v_pk_fma_f32 v[18:19], v[18:19], v[130:131], v[174:175]
	v_pk_fma_f32 v[16:17], v[16:17], v[128:129], v[172:173]
	v_pk_fma_f32 v[22:23], v[22:23], v[134:135], v[178:179]
	v_pk_fma_f32 v[20:21], v[20:21], v[132:133], v[176:177]
	v_pk_fma_f32 v[26:27], v[26:27], v[134:135], v[182:183]
	v_pk_fma_f32 v[24:25], v[24:25], v[132:133], v[180:181]
	v_pk_fma_f32 v[38:39], v[38:39], v[138:139], v[186:187]
	v_pk_fma_f32 v[36:37], v[36:37], v[136:137], v[184:185]
	v_pk_fma_f32 v[30:31], v[30:31], v[138:139], v[190:191]
	v_pk_fma_f32 v[28:29], v[28:29], v[136:137], v[188:189]
	v_pk_fma_f32 v[42:43], v[42:43], v[142:143], v[198:199]
	v_pk_fma_f32 v[40:41], v[40:41], v[140:141], v[196:197]
	v_pk_fma_f32 v[46:47], v[46:47], v[142:143], v[202:203]
	v_pk_fma_f32 v[44:45], v[44:45], v[140:141], v[200:201]
	v_pk_fma_f32 v[50:51], v[50:51], v[146:147], v[206:207]
	v_pk_fma_f32 v[48:49], v[48:49], v[144:145], v[204:205]
	v_pk_fma_f32 v[54:55], v[54:55], v[146:147], v[210:211]
	v_pk_fma_f32 v[52:53], v[52:53], v[144:145], v[208:209]
	v_pk_fma_f32 v[58:59], v[58:59], v[150:151], v[214:215]
	v_pk_fma_f32 v[56:57], v[56:57], v[148:149], v[212:213]
	v_pk_fma_f32 v[62:63], v[62:63], v[150:151], v[218:219]
	v_pk_fma_f32 v[60:61], v[60:61], v[148:149], v[216:217]
	s_cbranch_scc1 .LBB0_691
; #define LAS __attribute__((address_space(3)))
; __device__ __forceinline__ unsigned pk2(float lo, float hi) { return f2bf(lo) | (f2bf(hi) << 16); }
; __device__ __forceinline__ void gla_write_st(LAS unsigned char* Lst, const f32x4 (&S)[8][2], int w, int fr, int g) {
; #pragma unroll
;     for (int kt = 0; kt < 8; ++kt)
; #pragma unroll
;         for (int vt = 0; vt < 2; ++vt) { u32x2 sv; sv.x = pk2(S[kt][vt][0], S[kt][vt][1]); sv.y = pk2(S[kt][vt][2], S[kt][vt][3]);
;             *(LAS u32x2*)(Lst + (32 * w + 16 * vt + fr) * gla::ST_P + (16 * kt + 4 * g) * 2) = sv; }
; }
; template <bool FULL>
; __device__ __forceinline__ void gla_pass(const Params& P, LAS unsigned char* lds, f32x4 (&S)[8][2], int bh, int c0, int L, bool dry) {
;     ...
;     GLA_LOAD(c0); GLA_STORE();
.LBB0_692:
	v_and_b32_e32 v64, 15, v114
	v_lshrrev_b32_e32 v65, 1, v114
	s_mov_b32 s4, 0xfffffe0
	v_and_or_b32 v66, v65, s4, v64
	s_movk_i32 s4, 0x7fff
	s_movk_i32 s6, 0x110
	v_lshlrev_b32_e32 v67, 3, v100
	s_add_i32 s12, 0, 0x13800
	v_mul_lo_u32 v66, v66, s6
	s_mov_b32 s5, 0xffff0000
	v_add3_u32 v70, s12, v67, v66
	v_cvt_pk_bf16_f32 v64, v32, v33
	v_cvt_pk_bf16_f32 v66, v0, v1
	v_cvt_pk_bf16_f32 v65, v34, v35
	v_cvt_pk_bf16_f32 v67, v2, v3
	v_cvt_pk_bf16_f32 v68, v4, v5
	v_cvt_pk_bf16_f32 v69, v6, v7
	ds_write2_b64 v70, v[64:65], v[68:69] offset1:4
	v_cvt_pk_bf16_f32 v64, v8, v9
	v_cvt_pk_bf16_f32 v65, v10, v11
	v_add_u32_e32 v71, 0x1000, v70
	ds_write2_b64 v71, v[66:67], v[64:65] offset0:32 offset1:36
	v_cvt_pk_bf16_f32 v64, v12, v13
	v_cvt_pk_bf16_f32 v65, v14, v15
	v_cvt_pk_bf16_f32 v66, v16, v17
	v_cvt_pk_bf16_f32 v67, v18, v19
	v_cvt_pk_bf16_f32 v68, v20, v21
	v_cvt_pk_bf16_f32 v69, v22, v23
	ds_write2_b64 v70, v[64:65], v[68:69] offset0:8 offset1:12
	v_cvt_pk_bf16_f32 v64, v24, v25
	v_cvt_pk_bf16_f32 v65, v26, v27
	ds_write2_b64 v71, v[66:67], v[64:65] offset0:40 offset1:44
	v_cvt_pk_bf16_f32 v64, v36, v37
	v_cvt_pk_bf16_f32 v65, v38, v39
	v_cvt_pk_bf16_f32 v66, v28, v29
	v_cvt_pk_bf16_f32 v67, v30, v31
	v_cvt_pk_bf16_f32 v68, v40, v41
	v_cvt_pk_bf16_f32 v69, v42, v43
	ds_write2_b64 v70, v[64:65], v[68:69] offset0:16 offset1:20
	v_cvt_pk_bf16_f32 v64, v44, v45
	v_cvt_pk_bf16_f32 v65, v46, v47
	ds_write2_b64 v71, v[66:67], v[64:65] offset0:48 offset1:52
	v_cvt_pk_bf16_f32 v64, v48, v49
	v_cvt_pk_bf16_f32 v65, v50, v51
	v_cvt_pk_bf16_f32 v66, v52, v53
	v_cvt_pk_bf16_f32 v67, v54, v55
	v_cvt_pk_bf16_f32 v68, v56, v57
	v_cvt_pk_bf16_f32 v69, v58, v59
	ds_write2_b64 v70, v[64:65], v[68:69] offset0:24 offset1:28
	v_cvt_pk_bf16_f32 v64, v60, v61
	s_add_u32 s20, s70, 0xc000000
	s_addc_u32 s21, s71, 0
	s_lshl_b32 s4, s1, 12
	s_lshl_b32 s16, s3, 10
	s_mov_b32 s11, 0
	s_add_i32 s10, s4, s16
	v_cvt_pk_bf16_f32 v65, v62, v63
	s_lshl_b64 s[4:5], s[10:11], 8
	s_add_u32 s6, s20, s4
	s_addc_u32 s7, s21, s5
	s_add_u32 s3, s70, 0xa000000
	s_addc_u32 s22, s71, 0
	s_add_u32 s4, s3, s4
	s_addc_u32 s5, s22, s5
	s_lshl_b64 s[8:9], s[10:11], 9
	s_add_u32 s23, s70, 0xe000000
	s_addc_u32 s24, s71, 0
	v_mov_b32_e32 v108, v194
	s_add_u32 s18, s23, s8
	ds_write2_b64 v71, v[66:67], v[64:65] offset0:56 offset1:60
	s_addc_u32 s19, s24, s9
	v_lshlrev_b32_e32 v152, 4, v108
	global_load_dwordx4 v[64:67], v152, s[6:7]
	global_load_dwordx4 v[68:71], v152, s[4:5]
	v_add_u32_e32 v154, 0x2000, v152
	global_load_dwordx4 v[80:83], v152, s[18:19]
	global_load_dwordx4 v[72:75], v154, s[4:5]
	global_load_dwordx4 v[84:87], v154, s[18:19]
	s_lshl_b32 s4, s1, 6
	s_add_i32 s14, s0, s4
	s_mov_b32 s15, s11
	s_lshl_b64 s[8:9], s[14:15], 13
	s_add_u32 s4, s72, s8
	v_lshlrev_b32_e32 v104, 3, v108
	v_add_u32_e32 v158, 0x6000, v152
	s_addc_u32 s5, s73, s9
	v_ashrrev_i32_e32 v105, 31, v104
	v_add_u32_e32 v156, 0x4000, v152
	global_load_dwordx4 v[76:79], v154, s[6:7]
	global_load_dwordx4 v[92:95], v156, s[18:19]
	v_lshl_add_u64 v[88:89], v[104:105], 1, s[4:5]
	global_load_dwordx4 v[96:99], v158, s[18:19]
	global_load_dwordx4 v[100:103], v[88:89], off
	v_mov_b32_e32 v153, 0
	v_cmp_gt_i32_e64 s[4:5], 32, v108
	v_mov_b32_e32 v88, v153
	v_mov_b32_e32 v89, v153
	v_mov_b32_e32 v90, v153
	v_mov_b32_e32 v91, v153
	v_lshlrev_b32_e32 v106, 2, v108
	s_and_saveexec_b64 s[6:7], s[4:5]
	s_cbranch_execz .LBB0_694
	s_lshl_b64 s[18:19], s[14:15], 9
	s_add_u32 s18, s50, s18
	s_addc_u32 s19, s51, s19
	v_ashrrev_i32_e32 v107, 31, v106
	v_lshl_add_u64 v[88:89], v[106:107], 2, s[18:19]
	global_load_dwordx4 v[88:91], v[88:89], off

; #define LAS __attribute__((address_space(3)))
; __device__ __forceinline__ unsigned pk2(float lo, float hi) { return f2bf(lo) | (f2bf(hi) << 16); }
; __device__ __forceinline__ void gla_write_st(LAS unsigned char* Lst, const f32x4 (&S)[8][2], int w, int fr, int g) {
; #pragma unroll
;     for (int kt = 0; kt < 8; ++kt)
; #pragma unroll
;         for (int vt = 0; vt < 2; ++vt) { u32x2 sv; sv.x = pk2(S[kt][vt][0], S[kt][vt][1]); sv.y = pk2(S[kt][vt][2], S[kt][vt][3]);
;             *(LAS u32x2*)(Lst + (32 * w + 16 * vt + fr) * gla::ST_P + (16 * kt + 4 * g) * 2) = sv; }
; }
; template <bool FULL>
; __device__ __forceinline__ void gla_pass(const Params& P, LAS unsigned char* lds, f32x4 (&S)[8][2], int bh, int c0, int L, bool dry) {
;     ...
;         __syncthreads();
;         if (FULL) gla_write_st(Lst, S, w, fr, g);
;         if (n + 1 < c0 + L) GLA_STORE();
.LBB0_711:
	s_or_b64 exec, exec, s[18:19]
	s_waitcnt lgkmcnt(0)
	v_cvt_pk_bf16_f32 v136, v32, v33
	v_cvt_pk_bf16_f32 v137, v34, v35
	v_cvt_pk_bf16_f32 v138, v0, v1
	v_cvt_pk_bf16_f32 v139, v2, v3
	v_cvt_pk_bf16_f32 v140, v4, v5
	v_cvt_pk_bf16_f32 v141, v6, v7
	s_barrier
	ds_write2_b64 v201, v[136:137], v[140:141] offset1:4
	v_cvt_pk_bf16_f32 v136, v8, v9
	v_cvt_pk_bf16_f32 v137, v10, v11
	v_add_u32_e32 v142, 0x1000, v201
	ds_write2_b64 v142, v[138:139], v[136:137] offset0:32 offset1:36
	v_cvt_pk_bf16_f32 v136, v12, v13
	v_cvt_pk_bf16_f32 v137, v14, v15
	v_cvt_pk_bf16_f32 v138, v16, v17
	v_cvt_pk_bf16_f32 v139, v18, v19
	v_cvt_pk_bf16_f32 v140, v20, v21
	v_cvt_pk_bf16_f32 v141, v22, v23
	ds_write2_b64 v201, v[136:137], v[140:141] offset0:8 offset1:12
	v_cvt_pk_bf16_f32 v136, v24, v25
	v_cvt_pk_bf16_f32 v137, v26, v27
	ds_write2_b64 v142, v[138:139], v[136:137] offset0:40 offset1:44
	v_cvt_pk_bf16_f32 v136, v36, v37
	v_cvt_pk_bf16_f32 v137, v38, v39
	v_cvt_pk_bf16_f32 v138, v28, v29
	v_cvt_pk_bf16_f32 v139, v30, v31
	v_cvt_pk_bf16_f32 v140, v40, v41
	v_cvt_pk_bf16_f32 v141, v42, v43
	ds_write2_b64 v201, v[136:137], v[140:141] offset0:16 offset1:20
	v_cvt_pk_bf16_f32 v136, v44, v45
	v_cvt_pk_bf16_f32 v137, v46, v47
	ds_write2_b64 v142, v[138:139], v[136:137] offset0:48 offset1:52
	v_cvt_pk_bf16_f32 v136, v48, v49
	v_cvt_pk_bf16_f32 v137, v50, v51
	v_cvt_pk_bf16_f32 v138, v52, v53
	v_cvt_pk_bf16_f32 v139, v54, v55
	v_cvt_pk_bf16_f32 v140, v56, v57
	v_cvt_pk_bf16_f32 v141, v58, v59
	ds_write2_b64 v201, v[136:137], v[140:141] offset0:24 offset1:28
	v_cvt_pk_bf16_f32 v136, v60, v61
	v_cvt_pk_bf16_f32 v137, v62, v63
	s_and_b64 vcc, exec, s[8:9]
	ds_write2_b64 v142, v[138:139], v[136:137] offset0:56 offset1:60
	s_cbranch_vccz .LBB0_698
	s_waitcnt vmcnt(16)
	ds_write_b128 v182, v[64:67]
	s_waitcnt vmcnt(15)
	ds_write_b128 v183, v[68:71] offset:18432
	s_waitcnt vmcnt(14)
	ds_write_b128 v182, v[76:79] offset:9216
	s_waitcnt vmcnt(13)
	ds_write_b128 v183, v[72:75] offset:27136
	s_waitcnt vmcnt(12)
	ds_write_b128 v184, v[80:83] offset:35840
	s_waitcnt vmcnt(11)
	ds_write_b128 v184, v[84:87] offset:44544
	s_waitcnt vmcnt(10)
	ds_write_b128 v184, v[92:95] offset:53248
	s_waitcnt vmcnt(9)
	ds_write_b128 v184, v[96:99] offset:61952
	s_waitcnt vmcnt(8)
	ds_write_b128 v185, v[100:103]
	s_and_saveexec_b64 s[8:9], s[4:5]
	s_cbranch_execz .LBB0_697
	v_add_u32_e32 v136, 0x25000, v186
	ds_write_b128 v136, v[88:91]
	s_branch .LBB0_697

; #define LAS __attribute__((address_space(3)))
; __global__ void __launch_bounds__(512, 2) k_mega(Params P) {
;     extern __shared__ __attribute__((aligned(16))) unsigned char shm[];
;     LAS unsigned char* lds = (LAS unsigned char*)shm;
	.amdhsa_kernel _Z6k_mega6Params
		.amdhsa_group_segment_fixed_size 0
		.amdhsa_private_segment_fixed_size 0
		.amdhsa_kernarg_size 392
		.amdhsa_user_sgpr_count 2
		.amdhsa_user_sgpr_dispatch_ptr 0
		.amdhsa_user_sgpr_queue_ptr 0
		.amdhsa_user_sgpr_kernarg_segment_ptr 1
		.amdhsa_user_sgpr_dispatch_id 0
		.amdhsa_user_sgpr_kernarg_preload_length 0
		.amdhsa_user_sgpr_kernarg_preload_offset 0
		.amdhsa_user_sgpr_private_segment_size 0
		.amdhsa_uses_dynamic_stack 0
		.amdhsa_enable_private_segment 0
		.amdhsa_system_sgpr_workgroup_id_x 1
		.amdhsa_system_sgpr_workgroup_id_y 0
		.amdhsa_system_sgpr_workgroup_id_z 0
		.amdhsa_system_sgpr_workgroup_info 0
		.amdhsa_system_vgpr_workitem_id 2
		.amdhsa_next_free_vgpr 237
		.amdhsa_next_free_sgpr 99
		.amdhsa_accum_offset 240
		.amdhsa_reserve_vcc 1
		.amdhsa_float_round_mode_32 0
		.amdhsa_float_round_mode_16_64 0
		.amdhsa_float_denorm_mode_32 3
		.amdhsa_float_denorm_mode_16_64 3
		.amdhsa_dx10_clamp 1
		.amdhsa_ieee_mode 1
		.amdhsa_fp16_overflow 0
		.amdhsa_tg_split 0
		.amdhsa_exception_fp_ieee_invalid_op 0
		.amdhsa_exception_fp_denorm_src 0
		.amdhsa_exception_fp_ieee_div_zero 0
		.amdhsa_exception_fp_ieee_overflow 0
		.amdhsa_exception_fp_ieee_underflow 0
		.amdhsa_exception_fp_ieee_inexact 0
		.amdhsa_exception_int_div_zero 0
	.end_amdhsa_kernel

; #define LAS __attribute__((address_space(3)))
; __global__ void __launch_bounds__(512, 2) k_mega(Params P) {
;     extern __shared__ __attribute__((aligned(16))) unsigned char shm[];
;     LAS unsigned char* lds = (LAS unsigned char*)shm;
amdhsa.kernels:
  - .agpr_count:     0
    .args:
      - .offset:         0
        .size:           136
        .value_kind:     by_value
      - .offset:         136
        .size:           4
        .value_kind:     hidden_block_count_x
      - .offset:         140
        .size:           4
        .value_kind:     hidden_block_count_y
      - .offset:         144
        .size:           4
        .value_kind:     hidden_block_count_z
      - .offset:         148
        .size:           2
        .value_kind:     hidden_group_size_x
      - .offset:         150
        .size:           2
        .value_kind:     hidden_group_size_y
      - .offset:         152
        .size:           2
        .value_kind:     hidden_group_size_z
      - .offset:         154
        .size:           2
        .value_kind:     hidden_remainder_x
      - .offset:         156
        .size:           2
        .value_kind:     hidden_remainder_y
      - .offset:         158
        .size:           2
        .value_kind:     hidden_remainder_z
      - .offset:         176
        .size:           8
        .value_kind:     hidden_global_offset_x
      - .offset:         184
        .size:           8
        .value_kind:     hidden_global_offset_y
      - .offset:         192
        .size:           8
        .value_kind:     hidden_global_offset_z
      - .offset:         200
        .size:           2
        .value_kind:     hidden_grid_dims
      - .offset:         224
        .size:           8
        .value_kind:     hidden_multigrid_sync_arg
      - .offset:         256
        .size:           4
        .value_kind:     hidden_dynamic_lds_size
    .group_segment_fixed_size: 0
    .kernarg_segment_align: 8
    .kernarg_segment_size: 392
    .language:       OpenCL C
    .language_version:
      - 2
      - 0
    .max_flat_workgroup_size: 512
    .name:           _Z6k_mega6Params
    .private_segment_fixed_size: 0
    .sgpr_count:     105
    .sgpr_spill_count: 10
    .symbol:         _Z6k_mega6Params.kd
    .uniform_work_group_size: 1
    .uses_dynamic_stack: false
    .vgpr_count:     237
    .vgpr_spill_count: 0
    .wavefront_size: 64
